# v082 + removed the 36 no-op s_setprio 0/1 pairs in the middle of GEMM MFMA blocks
# baseline (speedup 1.0000x reference)
; #define PG8_STAGE(bufoff, gbase, voff) do { _Pragma("unroll") for (int _i = 0; _i < 2; ++_i) \
;         __builtin_amdgcn_global_load_lds((const unsigned*)((const char*)(gbase) + (voff)[_i]), (LAS unsigned*)(lds + (bufoff) + ldsw + _i * 8192), 16, 0, 0); } while (0)
; #define PG8_WAIT_V(n) asm volatile("s_waitcnt vmcnt(" #n ")" ::: "memory")
; #define PG8_WAIT_L(n) asm volatile("s_waitcnt lgkmcnt(" #n ")" ::: "memory")
; #define PG8_BAR __builtin_amdgcn_s_barrier()
; #define PG8_SCHED __builtin_amdgcn_sched_barrier(0)
; template <bool F8 = false, class Epi, class Sched>
; __device__ __forceinline__ void gemm_phase(LAS unsigned char* lds, const int lda, const int ldb, const int K, const Sched& S, const Epi& E) {
;     ...
;         for (int t = 0; t < nt; t += 2) {
;             const bool last = (t == nt - 2);
;             const char* a1 = cA + (size_t)(t + 1) * kstep;
;             const char* a2 = last ? nA : cA + (size_t)(t + 2) * kstep; const char* b2 = last ? nB : cB + (size_t)(t + 2) * kstep;
;             const char* a3 = a2 + kstep; const char* b3 = b2 + kstep;
;             PG8_LDB(B0, 0, 0); PG8_LDB(B1, 0, 1); PG8_SCHED; PG8_LDA(At, 0, 0); PG8_STAGE(PG8_SA(1, 1), a1 + hstepA, voffA);
;             PG8_WAIT_V(8); PG8_WAIT_L(0); PG8_BAR; PG8_MMA(0, 0, At, B0); PG8_MMA(0, 1, At, B1); PG8_BAR; PG8_SCHED;
;             PG8_LDA(At, 0, 1); PG8_STAGE(PG8_SB(0, 0), b2, voffB); PG8_STAGE(PG8_SB(0, 1), b2 + hstepB, voffB); PG8_STAGE(PG8_SA(0, 0), a2, voffA);
;             PG8_WAIT_V(8); PG8_WAIT_L(0); PG8_BAR; PG8_MMA(1, 0, At, B0); PG8_MMA(1, 1, At, B1); PG8_BAR; PG8_SCHED;
.LBB0_242:
	s_add_u32 s29, s72, 0xfff80080
	s_addc_u32 s30, s73, -1
	s_add_i32 s31, 0, 0x10000
	s_cmp_eq_u32 s28, 28
	s_cselect_b32 s75, s5, s30
	s_cselect_b32 s74, s13, s29
	s_cselect_b32 s53, s11, vcc_hi
	s_cselect_b32 s52, s15, vcc_lo
	s_add_i32 s29, 0, 0x14000
	v_add_u32_e32 v158, s31, v147
	v_add_u32_e32 v174, s29, v147
	ds_read_b128 v[142:145], v158
	ds_read_b128 v[150:153], v158 offset:1024
	ds_read_b128 v[154:157], v158 offset:2048
	ds_read_b128 v[158:161], v158 offset:3072
	ds_read_b128 v[162:165], v174
	ds_read_b128 v[166:169], v174 offset:1024
	ds_read_b128 v[170:173], v174 offset:2048
	ds_read_b128 v[174:177], v174 offset:3072
	v_lshl_add_u64 v[194:195], s[72:73], 0, v[136:137]
	s_add_i32 m0, s26, 0xc000
	ds_read_b128 v[178:181], v149
	ds_read_b128 v[182:185], v149 offset:1024
	ds_read_b128 v[186:189], v149 offset:2048
	ds_read_b128 v[190:193], v149 offset:3072
	ds_read_b128 v[202:205], v149 offset:4096
	ds_read_b128 v[206:209], v149 offset:5120
	ds_read_b128 v[210:213], v149 offset:6144
	ds_read_b128 v[214:217], v149 offset:7168
	global_load_lds_dwordx4 v[194:195], off
	v_lshl_add_u64 v[194:195], s[72:73], 0, v[138:139]
	s_add_i32 m0, s26, 0xe000
	s_nop 0
	global_load_lds_dwordx4 v[194:195], off
	s_waitcnt vmcnt(8)
	s_waitcnt lgkmcnt(0)
	s_barrier
	s_setprio 1
	v_mfma_f32_16x16x32_bf16 v[126:129], v[142:145], v[178:181], v[126:129]
	v_mfma_f32_16x16x32_bf16 v[122:125], v[154:157], v[178:181], v[122:125]
	v_mfma_f32_16x16x32_bf16 v[114:117], v[142:145], v[186:189], v[114:117]
	v_mfma_f32_16x16x32_bf16 v[106:109], v[154:157], v[186:189], v[106:109]
	v_mfma_f32_16x16x32_bf16 v[98:101], v[142:145], v[202:205], v[98:101]
	v_mfma_f32_16x16x32_bf16 v[90:93], v[154:157], v[202:205], v[90:93]
	v_mfma_f32_16x16x32_bf16 v[82:85], v[142:145], v[210:213], v[82:85]
	v_mfma_f32_16x16x32_bf16 v[74:77], v[154:157], v[210:213], v[74:77]
	v_mfma_f32_16x16x32_bf16 v[126:129], v[150:153], v[182:185], v[126:129]
	v_mfma_f32_16x16x32_bf16 v[122:125], v[158:161], v[182:185], v[122:125]
	v_mfma_f32_16x16x32_bf16 v[114:117], v[150:153], v[190:193], v[114:117]
	v_mfma_f32_16x16x32_bf16 v[106:109], v[158:161], v[190:193], v[106:109]
	v_mfma_f32_16x16x32_bf16 v[98:101], v[150:153], v[206:209], v[98:101]
	v_mfma_f32_16x16x32_bf16 v[90:93], v[158:161], v[206:209], v[90:93]
	v_mfma_f32_16x16x32_bf16 v[82:85], v[150:153], v[214:217], v[82:85]
	v_mfma_f32_16x16x32_bf16 v[74:77], v[158:161], v[214:217], v[74:77]
	v_mfma_f32_16x16x32_bf16 v[118:121], v[162:165], v[178:181], v[118:121]
	v_mfma_f32_16x16x32_bf16 v[110:113], v[170:173], v[178:181], v[110:113]
	v_mfma_f32_16x16x32_bf16 v[102:105], v[162:165], v[186:189], v[102:105]
	v_mfma_f32_16x16x32_bf16 v[94:97], v[170:173], v[186:189], v[94:97]
	v_mfma_f32_16x16x32_bf16 v[86:89], v[162:165], v[202:205], v[86:89]
	v_mfma_f32_16x16x32_bf16 v[78:81], v[170:173], v[202:205], v[78:81]
	v_mfma_f32_16x16x32_bf16 v[70:73], v[162:165], v[210:213], v[70:73]
	v_mfma_f32_16x16x32_bf16 v[66:69], v[170:173], v[210:213], v[66:69]
	v_mfma_f32_16x16x32_bf16 v[118:121], v[166:169], v[182:185], v[118:121]
	v_mfma_f32_16x16x32_bf16 v[110:113], v[174:177], v[182:185], v[110:113]
	v_mfma_f32_16x16x32_bf16 v[102:105], v[166:169], v[190:193], v[102:105]
	v_mfma_f32_16x16x32_bf16 v[94:97], v[174:177], v[190:193], v[94:97]
	v_mfma_f32_16x16x32_bf16 v[86:89], v[166:169], v[206:209], v[86:89]
	v_mfma_f32_16x16x32_bf16 v[78:81], v[174:177], v[206:209], v[78:81]
	v_mfma_f32_16x16x32_bf16 v[70:73], v[166:169], v[214:217], v[70:73]
	v_mfma_f32_16x16x32_bf16 v[66:69], v[174:177], v[214:217], v[66:69]
	s_setprio 0
	s_barrier
	s_add_i32 s30, s31, s25
	v_lshl_add_u64 v[194:195], s[52:53], 0, v[0:1]
	s_mov_b32 m0, s30
	ds_read_b128 v[178:181], v149 offset:16384
	ds_read_b128 v[182:185], v149 offset:17408
	ds_read_b128 v[186:189], v149 offset:18432
	ds_read_b128 v[190:193], v149 offset:19456
	ds_read_b128 v[202:205], v149 offset:20480
	ds_read_b128 v[206:209], v149 offset:21504
	ds_read_b128 v[210:213], v149 offset:22528
	ds_read_b128 v[214:217], v149 offset:23552
	global_load_lds_dwordx4 v[194:195], off
	s_add_i32 m0, s30, 0x2000
	s_add_u32 s30, s52, 0x80000
	v_lshl_add_u64 v[218:219], s[52:53], 0, v[134:135]
	s_addc_u32 s31, s53, 0
	s_add_i32 s29, s29, s25
	global_load_lds_dwordx4 v[218:219], off
	v_lshl_add_u64 v[220:221], s[30:31], 0, v[0:1]
	s_mov_b32 m0, s29
	v_lshl_add_u64 v[222:223], s[74:75], 0, v[132:133]
	global_load_lds_dwordx4 v[220:221], off
	v_lshl_add_u64 v[220:221], s[30:31], 0, v[134:135]
	s_add_i32 m0, s29, 0x2000
	s_nop 0
	global_load_lds_dwordx4 v[220:221], off
	v_lshl_add_u64 v[220:221], s[74:75], 0, v[130:131]
	s_mov_b32 m0, s26
	s_nop 0
	global_load_lds_dwordx4 v[220:221], off
	s_mov_b32 m0, s27
	s_nop 0
	global_load_lds_dwordx4 v[222:223], off
	s_waitcnt vmcnt(8)
	s_waitcnt lgkmcnt(0)
	s_barrier
; #define PG8_STAGE(bufoff, gbase, voff) do { _Pragma("unroll") for (int _i = 0; _i < 2; ++_i) \
;         __builtin_amdgcn_global_load_lds((const unsigned*)((const char*)(gbase) + (voff)[_i]), (LAS unsigned*)(lds + (bufoff) + ldsw + _i * 8192), 16, 0, 0); } while (0)
; #define PG8_WAIT_V(n) asm volatile("s_waitcnt vmcnt(" #n ")" ::: "memory")
; #define PG8_WAIT_L(n) asm volatile("s_waitcnt lgkmcnt(" #n ")" ::: "memory")
; #define PG8_BAR __builtin_amdgcn_s_barrier()
; #define PG8_SCHED __builtin_amdgcn_sched_barrier(0)
; template <bool F8 = false, class Epi, class Sched>
; __device__ __forceinline__ void gemm_phase(LAS unsigned char* lds, const int lda, const int ldb, const int K, const Sched& S, const Epi& E) {
;     ...
;             PG8_WAIT_V(8); PG8_WAIT_L(0); PG8_BAR; PG8_MMA(1, 0, At, B0); PG8_MMA(1, 1, At, B1); PG8_BAR; PG8_SCHED;
;             PG8_LDB(B0, 1, 0); PG8_LDB(B1, 1, 1); PG8_SCHED; PG8_LDA(At, 1, 0); PG8_STAGE(PG8_SA(0, 1), a2 + hstepA, voffA);
;             PG8_WAIT_V(8); PG8_WAIT_L(0); PG8_BAR; PG8_MMA(0, 0, At, B0); PG8_MMA(0, 1, At, B1); PG8_BAR; PG8_SCHED;
;             PG8_LDA(At, 1, 1); PG8_STAGE(PG8_SB(1, 0), b3, voffB); PG8_STAGE(PG8_SB(1, 1), b3 + hstepB, voffB); PG8_STAGE(PG8_SA(1, 0), a3, voffA);
	s_setprio 1
	v_mfma_f32_16x16x32_bf16 v[62:65], v[142:145], v[178:181], v[62:65]
	v_mfma_f32_16x16x32_bf16 v[58:61], v[154:157], v[178:181], v[58:61]
	v_mfma_f32_16x16x32_bf16 v[50:53], v[142:145], v[186:189], v[50:53]
	v_mfma_f32_16x16x32_bf16 v[42:45], v[154:157], v[186:189], v[42:45]
	v_mfma_f32_16x16x32_bf16 v[34:37], v[142:145], v[202:205], v[34:37]
	v_mfma_f32_16x16x32_bf16 v[26:29], v[154:157], v[202:205], v[26:29]
	v_mfma_f32_16x16x32_bf16 v[18:21], v[142:145], v[210:213], v[18:21]
	v_mfma_f32_16x16x32_bf16 v[10:13], v[154:157], v[210:213], v[10:13]
	v_mfma_f32_16x16x32_bf16 v[62:65], v[150:153], v[182:185], v[62:65]
	v_mfma_f32_16x16x32_bf16 v[58:61], v[158:161], v[182:185], v[58:61]
	v_mfma_f32_16x16x32_bf16 v[50:53], v[150:153], v[190:193], v[50:53]
	v_mfma_f32_16x16x32_bf16 v[42:45], v[158:161], v[190:193], v[42:45]
	v_mfma_f32_16x16x32_bf16 v[34:37], v[150:153], v[206:209], v[34:37]
	v_mfma_f32_16x16x32_bf16 v[26:29], v[158:161], v[206:209], v[26:29]
	v_mfma_f32_16x16x32_bf16 v[18:21], v[150:153], v[214:217], v[18:21]
	v_mfma_f32_16x16x32_bf16 v[10:13], v[158:161], v[214:217], v[10:13]
	v_mfma_f32_16x16x32_bf16 v[54:57], v[162:165], v[178:181], v[54:57]
	v_mfma_f32_16x16x32_bf16 v[46:49], v[170:173], v[178:181], v[46:49]
	v_mfma_f32_16x16x32_bf16 v[38:41], v[162:165], v[186:189], v[38:41]
	v_mfma_f32_16x16x32_bf16 v[30:33], v[170:173], v[186:189], v[30:33]
	v_mfma_f32_16x16x32_bf16 v[22:25], v[162:165], v[202:205], v[22:25]
	v_mfma_f32_16x16x32_bf16 v[14:17], v[170:173], v[202:205], v[14:17]
	v_mfma_f32_16x16x32_bf16 v[6:9], v[162:165], v[210:213], v[6:9]
	v_mfma_f32_16x16x32_bf16 v[2:5], v[170:173], v[210:213], v[2:5]
	v_mfma_f32_16x16x32_bf16 v[54:57], v[166:169], v[182:185], v[54:57]
	v_mfma_f32_16x16x32_bf16 v[46:49], v[174:177], v[182:185], v[46:49]
	v_mfma_f32_16x16x32_bf16 v[38:41], v[166:169], v[190:193], v[38:41]
	v_mfma_f32_16x16x32_bf16 v[30:33], v[174:177], v[190:193], v[30:33]
	v_mfma_f32_16x16x32_bf16 v[22:25], v[166:169], v[206:209], v[22:25]
	v_mfma_f32_16x16x32_bf16 v[14:17], v[174:177], v[206:209], v[14:17]
	v_mfma_f32_16x16x32_bf16 v[6:9], v[166:169], v[214:217], v[6:9]
	v_mfma_f32_16x16x32_bf16 v[2:5], v[174:177], v[214:217], v[2:5]
	s_setprio 0
	s_barrier
	s_add_i32 s29, 0, 0x18000
	s_add_i32 s33, 0, 0x1c000
	v_add_u32_e32 v158, s29, v147
	v_add_u32_e32 v174, s33, v147
	ds_read_b128 v[142:145], v158
	ds_read_b128 v[150:153], v158 offset:1024
	ds_read_b128 v[154:157], v158 offset:2048
	ds_read_b128 v[158:161], v158 offset:3072
	ds_read_b128 v[162:165], v174
	ds_read_b128 v[166:169], v174 offset:1024
	ds_read_b128 v[170:173], v174 offset:2048
	ds_read_b128 v[174:177], v174 offset:3072
	s_add_u32 s30, s74, 0x80000
	s_addc_u32 s31, s75, 0
	s_mov_b32 m0, s56
	v_lshl_add_u64 v[224:225], s[30:31], 0, v[130:131]
	ds_read_b128 v[178:181], v149 offset:32768
	ds_read_b128 v[182:185], v149 offset:33792
	ds_read_b128 v[186:189], v149 offset:34816
	ds_read_b128 v[190:193], v149 offset:35840
	ds_read_b128 v[202:205], v149 offset:36864
	ds_read_b128 v[206:209], v149 offset:37888
	ds_read_b128 v[210:213], v149 offset:38912
	ds_read_b128 v[214:217], v149 offset:39936
	global_load_lds_dwordx4 v[224:225], off
	v_lshl_add_u64 v[224:225], s[30:31], 0, v[132:133]
	s_mov_b32 m0, s57
	s_nop 0
	global_load_lds_dwordx4 v[224:225], off
	s_waitcnt vmcnt(8)
	s_waitcnt lgkmcnt(0)
	s_barrier
	s_setprio 1
	v_mfma_f32_16x16x32_bf16 v[126:129], v[142:145], v[178:181], v[126:129]
	v_mfma_f32_16x16x32_bf16 v[122:125], v[154:157], v[178:181], v[122:125]
	v_mfma_f32_16x16x32_bf16 v[114:117], v[142:145], v[186:189], v[114:117]
	v_mfma_f32_16x16x32_bf16 v[106:109], v[154:157], v[186:189], v[106:109]
	v_mfma_f32_16x16x32_bf16 v[98:101], v[142:145], v[202:205], v[98:101]
	v_mfma_f32_16x16x32_bf16 v[90:93], v[154:157], v[202:205], v[90:93]
	v_mfma_f32_16x16x32_bf16 v[82:85], v[142:145], v[210:213], v[82:85]
	v_mfma_f32_16x16x32_bf16 v[74:77], v[154:157], v[210:213], v[74:77]
	v_mfma_f32_16x16x32_bf16 v[126:129], v[150:153], v[182:185], v[126:129]
	v_mfma_f32_16x16x32_bf16 v[122:125], v[158:161], v[182:185], v[122:125]
	v_mfma_f32_16x16x32_bf16 v[114:117], v[150:153], v[190:193], v[114:117]
	v_mfma_f32_16x16x32_bf16 v[106:109], v[158:161], v[190:193], v[106:109]
	v_mfma_f32_16x16x32_bf16 v[98:101], v[150:153], v[206:209], v[98:101]
	v_mfma_f32_16x16x32_bf16 v[90:93], v[158:161], v[206:209], v[90:93]
	v_mfma_f32_16x16x32_bf16 v[82:85], v[150:153], v[214:217], v[82:85]
	v_mfma_f32_16x16x32_bf16 v[74:77], v[158:161], v[214:217], v[74:77]
	v_mfma_f32_16x16x32_bf16 v[118:121], v[162:165], v[178:181], v[118:121]
	v_mfma_f32_16x16x32_bf16 v[110:113], v[170:173], v[178:181], v[110:113]
	v_mfma_f32_16x16x32_bf16 v[102:105], v[162:165], v[186:189], v[102:105]
	v_mfma_f32_16x16x32_bf16 v[94:97], v[170:173], v[186:189], v[94:97]
	v_mfma_f32_16x16x32_bf16 v[86:89], v[162:165], v[202:205], v[86:89]
	v_mfma_f32_16x16x32_bf16 v[78:81], v[170:173], v[202:205], v[78:81]
	v_mfma_f32_16x16x32_bf16 v[70:73], v[162:165], v[210:213], v[70:73]
	v_mfma_f32_16x16x32_bf16 v[66:69], v[170:173], v[210:213], v[66:69]
	v_mfma_f32_16x16x32_bf16 v[118:121], v[166:169], v[182:185], v[118:121]
	v_mfma_f32_16x16x32_bf16 v[110:113], v[174:177], v[182:185], v[110:113]
	v_mfma_f32_16x16x32_bf16 v[102:105], v[166:169], v[190:193], v[102:105]
	v_mfma_f32_16x16x32_bf16 v[94:97], v[174:177], v[190:193], v[94:97]
	v_mfma_f32_16x16x32_bf16 v[86:89], v[166:169], v[206:209], v[86:89]
	v_mfma_f32_16x16x32_bf16 v[78:81], v[174:177], v[206:209], v[78:81]
	v_mfma_f32_16x16x32_bf16 v[70:73], v[166:169], v[214:217], v[70:73]
	v_mfma_f32_16x16x32_bf16 v[66:69], v[174:177], v[214:217], v[66:69]
	s_setprio 0
	s_barrier
; #define PG8_STAGE(bufoff, gbase, voff) do { _Pragma("unroll") for (int _i = 0; _i < 2; ++_i) \
;         __builtin_amdgcn_global_load_lds((const unsigned*)((const char*)(gbase) + (voff)[_i]), (LAS unsigned*)(lds + (bufoff) + ldsw + _i * 8192), 16, 0, 0); } while (0)
; #define PG8_WAIT_V(n) asm volatile("s_waitcnt vmcnt(" #n ")" ::: "memory")
; #define PG8_WAIT_L(n) asm volatile("s_waitcnt lgkmcnt(" #n ")" ::: "memory")
; #define PG8_BAR __builtin_amdgcn_s_barrier()
; #define PG8_SCHED __builtin_amdgcn_sched_barrier(0)
; template <bool F8 = false, class Epi, class Sched>
; __device__ __forceinline__ void gemm_phase(LAS unsigned char* lds, const int lda, const int ldb, const int K, const Sched& S, const Epi& E) {
;     ...
;             PG8_LDA(At, 1, 1); PG8_STAGE(PG8_SB(1, 0), b3, voffB); PG8_STAGE(PG8_SB(1, 1), b3 + hstepB, voffB); PG8_STAGE(PG8_SA(1, 0), a3, voffA);
;             PG8_WAIT_V(8); PG8_WAIT_L(0); PG8_BAR; PG8_MMA(1, 0, At, B0); PG8_MMA(1, 1, At, B1); PG8_BAR; PG8_SCHED;
;         }
;         if (wr == 0) PG8_BAR;
	s_add_i32 s29, s29, s25
	v_lshl_add_u64 v[194:195], v[194:195], 0, s[40:41]
	s_mov_b32 m0, s29
	ds_read_b128 v[178:181], v149 offset:49152
	ds_read_b128 v[182:185], v149 offset:50176
	ds_read_b128 v[186:189], v149 offset:51200
	ds_read_b128 v[190:193], v149 offset:52224
	ds_read_b128 v[202:205], v149 offset:53248
	ds_read_b128 v[206:209], v149 offset:54272
	ds_read_b128 v[210:213], v149 offset:55296
	ds_read_b128 v[214:217], v149 offset:56320
	global_load_lds_dwordx4 v[194:195], off
	s_add_i32 m0, s29, 0x2000
	s_add_u32 s30, s52, 0x80080
	v_lshl_add_u64 v[194:195], v[218:219], 0, s[40:41]
	s_addc_u32 s31, s53, 0
	s_add_i32 s29, s33, s25
	global_load_lds_dwordx4 v[194:195], off
	v_lshl_add_u64 v[194:195], s[30:31], 0, v[0:1]
	s_mov_b32 m0, s29
	s_nop 0
	global_load_lds_dwordx4 v[194:195], off
	v_lshl_add_u64 v[194:195], s[30:31], 0, v[134:135]
	s_add_i32 m0, s29, 0x2000
	s_nop 0
	global_load_lds_dwordx4 v[194:195], off
	v_lshl_add_u64 v[194:195], v[220:221], 0, s[40:41]
	s_mov_b32 m0, s94
	s_nop 0
	global_load_lds_dwordx4 v[194:195], off
	v_lshl_add_u64 v[194:195], v[222:223], 0, s[40:41]
	s_mov_b32 m0, s95
	s_nop 0
	global_load_lds_dwordx4 v[194:195], off
	s_waitcnt vmcnt(8)
	s_waitcnt lgkmcnt(0)
	s_barrier
	s_setprio 1
	v_mfma_f32_16x16x32_bf16 v[62:65], v[142:145], v[178:181], v[62:65]
	v_mfma_f32_16x16x32_bf16 v[58:61], v[154:157], v[178:181], v[58:61]
	v_mfma_f32_16x16x32_bf16 v[50:53], v[142:145], v[186:189], v[50:53]
	v_mfma_f32_16x16x32_bf16 v[42:45], v[154:157], v[186:189], v[42:45]
	v_mfma_f32_16x16x32_bf16 v[34:37], v[142:145], v[202:205], v[34:37]
	v_mfma_f32_16x16x32_bf16 v[26:29], v[154:157], v[202:205], v[26:29]
	v_mfma_f32_16x16x32_bf16 v[18:21], v[142:145], v[210:213], v[18:21]
	v_mfma_f32_16x16x32_bf16 v[10:13], v[154:157], v[210:213], v[10:13]
	v_mfma_f32_16x16x32_bf16 v[62:65], v[150:153], v[182:185], v[62:65]
	v_mfma_f32_16x16x32_bf16 v[58:61], v[158:161], v[182:185], v[58:61]
	v_mfma_f32_16x16x32_bf16 v[50:53], v[150:153], v[190:193], v[50:53]
	v_mfma_f32_16x16x32_bf16 v[42:45], v[158:161], v[190:193], v[42:45]
	v_mfma_f32_16x16x32_bf16 v[34:37], v[150:153], v[206:209], v[34:37]
	v_mfma_f32_16x16x32_bf16 v[26:29], v[158:161], v[206:209], v[26:29]
	v_mfma_f32_16x16x32_bf16 v[18:21], v[150:153], v[214:217], v[18:21]
	v_mfma_f32_16x16x32_bf16 v[10:13], v[158:161], v[214:217], v[10:13]
	v_mfma_f32_16x16x32_bf16 v[54:57], v[162:165], v[178:181], v[54:57]
	v_mfma_f32_16x16x32_bf16 v[46:49], v[170:173], v[178:181], v[46:49]
	v_mfma_f32_16x16x32_bf16 v[38:41], v[162:165], v[186:189], v[38:41]
	v_mfma_f32_16x16x32_bf16 v[30:33], v[170:173], v[186:189], v[30:33]
	v_mfma_f32_16x16x32_bf16 v[22:25], v[162:165], v[202:205], v[22:25]
	v_mfma_f32_16x16x32_bf16 v[14:17], v[170:173], v[202:205], v[14:17]
	v_mfma_f32_16x16x32_bf16 v[6:9], v[162:165], v[210:213], v[6:9]
	v_mfma_f32_16x16x32_bf16 v[2:5], v[170:173], v[210:213], v[2:5]
	v_mfma_f32_16x16x32_bf16 v[54:57], v[166:169], v[182:185], v[54:57]
	v_mfma_f32_16x16x32_bf16 v[46:49], v[174:177], v[182:185], v[46:49]
	v_mfma_f32_16x16x32_bf16 v[38:41], v[166:169], v[190:193], v[38:41]
	v_mfma_f32_16x16x32_bf16 v[30:33], v[174:177], v[190:193], v[30:33]
	v_mfma_f32_16x16x32_bf16 v[22:25], v[166:169], v[206:209], v[22:25]
	v_mfma_f32_16x16x32_bf16 v[14:17], v[174:177], v[206:209], v[14:17]
	v_mfma_f32_16x16x32_bf16 v[6:9], v[166:169], v[214:217], v[6:9]
	v_mfma_f32_16x16x32_bf16 v[2:5], v[174:177], v[214:217], v[2:5]
	s_setprio 0
	s_barrier
	s_add_i32 s28, s28, 2
	s_add_u32 s72, s72, 0x100
	s_addc_u32 s73, s73, 0
	s_add_u32 vcc_lo, vcc_lo, 0x100
	s_addc_u32 vcc_hi, vcc_hi, 0
	s_cmp_gt_u32 s28, 29
	s_cbranch_scc0 .LBB0_242
	s_and_b64 vcc, exec, s[8:9]
	s_cbranch_vccz .LBB0_245
	s_barrier

; #define PG8_STAGE(bufoff, gbase, voff) do { _Pragma("unroll") for (int _i = 0; _i < 2; ++_i) \
;         __builtin_amdgcn_global_load_lds((const unsigned*)((const char*)(gbase) + (voff)[_i]), (LAS unsigned*)(lds + (bufoff) + ldsw + _i * 8192), 16, 0, 0); } while (0)
; #define PG8_WAIT_V(n) asm volatile("s_waitcnt vmcnt(" #n ")" ::: "memory")
; #define PG8_WAIT_L(n) asm volatile("s_waitcnt lgkmcnt(" #n ")" ::: "memory")
; #define PG8_BAR __builtin_amdgcn_s_barrier()
; #define PG8_SCHED __builtin_amdgcn_sched_barrier(0)
; template <bool F8 = false, class Epi, class Sched>
; __device__ __forceinline__ void gemm_phase(LAS unsigned char* lds, const int lda, const int ldb, const int K, const Sched& S, const Epi& E) {
;     ...
;         for (int t = 0; t < nt; t += 2) {
;             const bool last = (t == nt - 2);
;             const char* a1 = cA + (size_t)(t + 1) * kstep;
;             const char* a2 = last ? nA : cA + (size_t)(t + 2) * kstep; const char* b2 = last ? nB : cB + (size_t)(t + 2) * kstep;
;             const char* a3 = a2 + kstep; const char* b3 = b2 + kstep;
;             PG8_LDB(B0, 0, 0); PG8_LDB(B1, 0, 1); PG8_SCHED; PG8_LDA(At, 0, 0); PG8_STAGE(PG8_SA(1, 1), a1 + hstepA, voffA);
;             PG8_WAIT_V(8); PG8_WAIT_L(0); PG8_BAR; PG8_MMA(0, 0, At, B0); PG8_MMA(0, 1, At, B1); PG8_BAR; PG8_SCHED;
;             PG8_LDA(At, 0, 1); PG8_STAGE(PG8_SB(0, 0), b2, voffB); PG8_STAGE(PG8_SB(0, 1), b2 + hstepB, voffB); PG8_STAGE(PG8_SA(0, 0), a2, voffA);
;             PG8_WAIT_V(8); PG8_WAIT_L(0); PG8_BAR; PG8_MMA(1, 0, At, B0); PG8_MMA(1, 1, At, B1); PG8_BAR; PG8_SCHED;
;             PG8_LDB(B0, 1, 0); PG8_LDB(B1, 1, 1); PG8_SCHED; PG8_LDA(At, 1, 0); PG8_STAGE(PG8_SA(0, 1), a2 + hstepA, voffA);
.LBB0_292:
	s_add_u32 s29, s72, 0xfffc0080
	s_addc_u32 s30, s73, -1
	s_add_i32 s28, 0, 0x10000
	s_cmp_eq_u32 s97, 12
	s_cselect_b32 s53, s11, s30
	s_cselect_b32 s52, s13, s29
	s_cselect_b32 vcc_hi, s9, s19
	s_cselect_b32 vcc_lo, s96, s18
	s_add_i32 s29, 0, 0x14000
	v_add_u32_e32 v2, s28, v177
	v_add_u32_e32 v14, s29, v177
	ds_read_b128 v[18:21], v2
	ds_read_b128 v[22:25], v2 offset:1024
	ds_read_b128 v[26:29], v2 offset:2048
	ds_read_b128 v[30:33], v2 offset:3072
	ds_read_b128 v[2:5], v14
	ds_read_b128 v[6:9], v14 offset:1024
	ds_read_b128 v[10:13], v14 offset:2048
	ds_read_b128 v[14:17], v14 offset:3072
	v_lshl_add_u64 v[210:211], s[72:73], 0, v[164:165]
	s_add_i32 m0, s15, 0xc000
	ds_read_b128 v[168:171], v179
	ds_read_b128 v[172:175], v179 offset:1024
	ds_read_b128 v[180:183], v179 offset:2048
	ds_read_b128 v[184:187], v179 offset:3072
	ds_read_b128 v[188:191], v179 offset:4096
	ds_read_b128 v[192:195], v179 offset:5120
	ds_read_b128 v[202:205], v179 offset:6144
	ds_read_b128 v[206:209], v179 offset:7168
	global_load_lds_dwordx4 v[210:211], off
	v_lshl_add_u64 v[210:211], s[72:73], 0, v[166:167]
	s_add_i32 m0, s15, 0xe000
	s_nop 0
	global_load_lds_dwordx4 v[210:211], off
	s_waitcnt vmcnt(8)
	s_waitcnt lgkmcnt(0)
	s_barrier
	s_setprio 1
	v_mfma_scale_f32_16x16x128_f8f6f4 v[158:161], v[18:25], v[168:175], v[158:161], v236, v236 op_sel_hi:[0,0,0]
	v_mfma_scale_f32_16x16x128_f8f6f4 v[154:157], v[26:33], v[168:175], v[154:157], v236, v236 op_sel_hi:[0,0,0]
	v_mfma_scale_f32_16x16x128_f8f6f4 v[150:153], v[18:25], v[180:187], v[150:153], v236, v236 op_sel_hi:[0,0,0]
	v_mfma_scale_f32_16x16x128_f8f6f4 v[142:145], v[26:33], v[180:187], v[142:145], v236, v236 op_sel_hi:[0,0,0]
	v_mfma_scale_f32_16x16x128_f8f6f4 v[134:137], v[18:25], v[188:195], v[134:137], v236, v236 op_sel_hi:[0,0,0]
	v_mfma_scale_f32_16x16x128_f8f6f4 v[126:129], v[26:33], v[188:195], v[126:129], v236, v236 op_sel_hi:[0,0,0]
	v_mfma_scale_f32_16x16x128_f8f6f4 v[118:121], v[18:25], v[202:209], v[118:121], v236, v236 op_sel_hi:[0,0,0]
	v_mfma_scale_f32_16x16x128_f8f6f4 v[110:113], v[26:33], v[202:209], v[110:113], v236, v236 op_sel_hi:[0,0,0]
	v_mfma_scale_f32_16x16x128_f8f6f4 v[146:149], v[2:9], v[168:175], v[146:149], v236, v236 op_sel_hi:[0,0,0]
	v_mfma_scale_f32_16x16x128_f8f6f4 v[138:141], v[10:17], v[168:175], v[138:141], v236, v236 op_sel_hi:[0,0,0]
	v_mfma_scale_f32_16x16x128_f8f6f4 v[130:133], v[2:9], v[180:187], v[130:133], v236, v236 op_sel_hi:[0,0,0]
	v_mfma_scale_f32_16x16x128_f8f6f4 v[122:125], v[10:17], v[180:187], v[122:125], v236, v236 op_sel_hi:[0,0,0]
	v_mfma_scale_f32_16x16x128_f8f6f4 v[114:117], v[2:9], v[188:195], v[114:117], v236, v236 op_sel_hi:[0,0,0]
	v_mfma_scale_f32_16x16x128_f8f6f4 v[106:109], v[10:17], v[188:195], v[106:109], v236, v236 op_sel_hi:[0,0,0]
	v_mfma_scale_f32_16x16x128_f8f6f4 v[102:105], v[2:9], v[202:209], v[102:105], v236, v236 op_sel_hi:[0,0,0]
	v_mfma_scale_f32_16x16x128_f8f6f4 v[98:101], v[10:17], v[202:209], v[98:101], v236, v236 op_sel_hi:[0,0,0]
	s_setprio 0
	s_barrier
	s_add_i32 s28, s28, s24
	v_lshl_add_u64 v[168:169], vcc, 0, v[0:1]
	s_mov_b32 m0, s28
	ds_read_b128 v[180:183], v179 offset:16384
	ds_read_b128 v[184:187], v179 offset:17408
	ds_read_b128 v[188:191], v179 offset:18432
	ds_read_b128 v[192:195], v179 offset:19456
	ds_read_b128 v[202:205], v179 offset:20480
	ds_read_b128 v[206:209], v179 offset:21504
	ds_read_b128 v[210:213], v179 offset:22528
	ds_read_b128 v[214:217], v179 offset:23552
	global_load_lds_dwordx4 v[168:169], off
	s_add_i32 m0, s28, 0x2000
	s_add_u32 s30, vcc_lo, 0x40000
	v_lshl_add_u64 v[170:171], vcc, 0, v[162:163]
	s_addc_u32 s31, vcc_hi, 0
	s_add_i32 s28, s29, s24
	global_load_lds_dwordx4 v[170:171], off
	v_lshl_add_u64 v[172:173], s[30:31], 0, v[0:1]
	s_mov_b32 m0, s28
	v_lshl_add_u64 v[174:175], s[52:53], 0, v[162:163]
	global_load_lds_dwordx4 v[172:173], off
	v_lshl_add_u64 v[172:173], s[30:31], 0, v[162:163]
	s_add_i32 m0, s28, 0x2000
	s_nop 0
	global_load_lds_dwordx4 v[172:173], off
	v_lshl_add_u64 v[172:173], s[52:53], 0, v[0:1]
	s_mov_b32 m0, s15
	s_nop 0
	global_load_lds_dwordx4 v[172:173], off
	s_mov_b32 m0, s26
	s_nop 0
	global_load_lds_dwordx4 v[174:175], off
	s_waitcnt vmcnt(8)
	s_waitcnt lgkmcnt(0)
	s_barrier
	s_setprio 1
	v_mfma_scale_f32_16x16x128_f8f6f4 v[94:97], v[18:25], v[180:187], v[94:97], v236, v236 op_sel_hi:[0,0,0]
	v_mfma_scale_f32_16x16x128_f8f6f4 v[90:93], v[26:33], v[180:187], v[90:93], v236, v236 op_sel_hi:[0,0,0]
	v_mfma_scale_f32_16x16x128_f8f6f4 v[86:89], v[18:25], v[188:195], v[86:89], v236, v236 op_sel_hi:[0,0,0]
	v_mfma_scale_f32_16x16x128_f8f6f4 v[78:81], v[26:33], v[188:195], v[78:81], v236, v236 op_sel_hi:[0,0,0]
	v_mfma_scale_f32_16x16x128_f8f6f4 v[70:73], v[18:25], v[202:209], v[70:73], v236, v236 op_sel_hi:[0,0,0]
	v_mfma_scale_f32_16x16x128_f8f6f4 v[62:65], v[26:33], v[202:209], v[62:65], v236, v236 op_sel_hi:[0,0,0]
	v_mfma_scale_f32_16x16x128_f8f6f4 v[54:57], v[18:25], v[210:217], v[54:57], v236, v236 op_sel_hi:[0,0,0]
	v_mfma_scale_f32_16x16x128_f8f6f4 v[46:49], v[26:33], v[210:217], v[46:49], v236, v236 op_sel_hi:[0,0,0]
	v_mfma_scale_f32_16x16x128_f8f6f4 v[82:85], v[2:9], v[180:187], v[82:85], v236, v236 op_sel_hi:[0,0,0]
	v_mfma_scale_f32_16x16x128_f8f6f4 v[74:77], v[10:17], v[180:187], v[74:77], v236, v236 op_sel_hi:[0,0,0]
	v_mfma_scale_f32_16x16x128_f8f6f4 v[66:69], v[2:9], v[188:195], v[66:69], v236, v236 op_sel_hi:[0,0,0]
	v_mfma_scale_f32_16x16x128_f8f6f4 v[58:61], v[10:17], v[188:195], v[58:61], v236, v236 op_sel_hi:[0,0,0]
	v_mfma_scale_f32_16x16x128_f8f6f4 v[50:53], v[2:9], v[202:209], v[50:53], v236, v236 op_sel_hi:[0,0,0]
	v_mfma_scale_f32_16x16x128_f8f6f4 v[42:45], v[10:17], v[202:209], v[42:45], v236, v236 op_sel_hi:[0,0,0]
	v_mfma_scale_f32_16x16x128_f8f6f4 v[38:41], v[2:9], v[210:217], v[38:41], v236, v236 op_sel_hi:[0,0,0]
	v_mfma_scale_f32_16x16x128_f8f6f4 v[34:37], v[10:17], v[210:217], v[34:37], v236, v236 op_sel_hi:[0,0,0]
	s_setprio 0
	s_barrier
; #define PG8_STAGE(bufoff, gbase, voff) do { _Pragma("unroll") for (int _i = 0; _i < 2; ++_i) \
;         __builtin_amdgcn_global_load_lds((const unsigned*)((const char*)(gbase) + (voff)[_i]), (LAS unsigned*)(lds + (bufoff) + ldsw + _i * 8192), 16, 0, 0); } while (0)
; #define PG8_WAIT_V(n) asm volatile("s_waitcnt vmcnt(" #n ")" ::: "memory")
; #define PG8_WAIT_L(n) asm volatile("s_waitcnt lgkmcnt(" #n ")" ::: "memory")
; #define PG8_BAR __builtin_amdgcn_s_barrier()
; #define PG8_SCHED __builtin_amdgcn_sched_barrier(0)
; template <bool F8 = false, class Epi, class Sched>
; __device__ __forceinline__ void gemm_phase(LAS unsigned char* lds, const int lda, const int ldb, const int K, const Sched& S, const Epi& E) {
;     ...
;             PG8_LDB(B0, 1, 0); PG8_LDB(B1, 1, 1); PG8_SCHED; PG8_LDA(At, 1, 0); PG8_STAGE(PG8_SA(0, 1), a2 + hstepA, voffA);
;             PG8_WAIT_V(8); PG8_WAIT_L(0); PG8_BAR; PG8_MMA(0, 0, At, B0); PG8_MMA(0, 1, At, B1); PG8_BAR; PG8_SCHED;
;             PG8_LDA(At, 1, 1); PG8_STAGE(PG8_SB(1, 0), b3, voffB); PG8_STAGE(PG8_SB(1, 1), b3 + hstepB, voffB); PG8_STAGE(PG8_SA(1, 0), a3, voffA);
;             PG8_WAIT_V(8); PG8_WAIT_L(0); PG8_BAR; PG8_MMA(1, 0, At, B0); PG8_MMA(1, 1, At, B1); PG8_BAR; PG8_SCHED;
;         }
;         if (wr == 0) PG8_BAR;
	s_add_i32 s30, 0, 0x18000
	s_add_i32 s31, 0, 0x1c000
	v_add_u32_e32 v14, s30, v177
	v_add_u32_e32 v30, s31, v177
	ds_read_b128 v[2:5], v14
	ds_read_b128 v[6:9], v14 offset:1024
	ds_read_b128 v[10:13], v14 offset:2048
	ds_read_b128 v[14:17], v14 offset:3072
	ds_read_b128 v[18:21], v30
	ds_read_b128 v[22:25], v30 offset:1024
	ds_read_b128 v[26:29], v30 offset:2048
	ds_read_b128 v[30:33], v30 offset:3072
	s_add_u32 s28, s52, 0x40000
	s_addc_u32 s29, s53, 0
	s_mov_b32 m0, s27
	v_lshl_add_u64 v[218:219], s[28:29], 0, v[0:1]
	ds_read_b128 v[180:183], v179 offset:32768
	ds_read_b128 v[184:187], v179 offset:33792
	ds_read_b128 v[188:191], v179 offset:34816
	ds_read_b128 v[192:195], v179 offset:35840
	ds_read_b128 v[202:205], v179 offset:36864
	ds_read_b128 v[206:209], v179 offset:37888
	ds_read_b128 v[210:213], v179 offset:38912
	ds_read_b128 v[214:217], v179 offset:39936
	global_load_lds_dwordx4 v[218:219], off
	v_lshl_add_u64 v[218:219], s[28:29], 0, v[162:163]
	s_mov_b32 m0, s56
	s_nop 0
	global_load_lds_dwordx4 v[218:219], off
	s_waitcnt vmcnt(8)
	s_waitcnt lgkmcnt(0)
	s_barrier
	s_setprio 1
	v_mfma_scale_f32_16x16x128_f8f6f4 v[158:161], v[2:9], v[180:187], v[158:161], v236, v236 op_sel_hi:[0,0,0]
	v_mfma_scale_f32_16x16x128_f8f6f4 v[154:157], v[10:17], v[180:187], v[154:157], v236, v236 op_sel_hi:[0,0,0]
	v_mfma_scale_f32_16x16x128_f8f6f4 v[150:153], v[2:9], v[188:195], v[150:153], v236, v236 op_sel_hi:[0,0,0]
	v_mfma_scale_f32_16x16x128_f8f6f4 v[142:145], v[10:17], v[188:195], v[142:145], v236, v236 op_sel_hi:[0,0,0]
	v_mfma_scale_f32_16x16x128_f8f6f4 v[134:137], v[2:9], v[202:209], v[134:137], v236, v236 op_sel_hi:[0,0,0]
	v_mfma_scale_f32_16x16x128_f8f6f4 v[126:129], v[10:17], v[202:209], v[126:129], v236, v236 op_sel_hi:[0,0,0]
	v_mfma_scale_f32_16x16x128_f8f6f4 v[118:121], v[2:9], v[210:217], v[118:121], v236, v236 op_sel_hi:[0,0,0]
	v_mfma_scale_f32_16x16x128_f8f6f4 v[110:113], v[10:17], v[210:217], v[110:113], v236, v236 op_sel_hi:[0,0,0]
	v_mfma_scale_f32_16x16x128_f8f6f4 v[146:149], v[18:25], v[180:187], v[146:149], v236, v236 op_sel_hi:[0,0,0]
	v_mfma_scale_f32_16x16x128_f8f6f4 v[138:141], v[26:33], v[180:187], v[138:141], v236, v236 op_sel_hi:[0,0,0]
	v_mfma_scale_f32_16x16x128_f8f6f4 v[130:133], v[18:25], v[188:195], v[130:133], v236, v236 op_sel_hi:[0,0,0]
	v_mfma_scale_f32_16x16x128_f8f6f4 v[122:125], v[26:33], v[188:195], v[122:125], v236, v236 op_sel_hi:[0,0,0]
	v_mfma_scale_f32_16x16x128_f8f6f4 v[114:117], v[18:25], v[202:209], v[114:117], v236, v236 op_sel_hi:[0,0,0]
	v_mfma_scale_f32_16x16x128_f8f6f4 v[106:109], v[26:33], v[202:209], v[106:109], v236, v236 op_sel_hi:[0,0,0]
	v_mfma_scale_f32_16x16x128_f8f6f4 v[102:105], v[18:25], v[210:217], v[102:105], v236, v236 op_sel_hi:[0,0,0]
	v_mfma_scale_f32_16x16x128_f8f6f4 v[98:101], v[26:33], v[210:217], v[98:101], v236, v236 op_sel_hi:[0,0,0]
	s_setprio 0
	s_barrier
	s_add_i32 s28, s30, s24
	v_lshl_add_u64 v[168:169], v[168:169], 0, s[40:41]
	s_mov_b32 m0, s28
	ds_read_b128 v[180:183], v179 offset:49152
	ds_read_b128 v[184:187], v179 offset:50176
	ds_read_b128 v[188:191], v179 offset:51200
	ds_read_b128 v[192:195], v179 offset:52224
	ds_read_b128 v[202:205], v179 offset:53248
	ds_read_b128 v[206:209], v179 offset:54272
	ds_read_b128 v[210:213], v179 offset:55296
	ds_read_b128 v[214:217], v179 offset:56320
	global_load_lds_dwordx4 v[168:169], off
	s_add_i32 m0, s28, 0x2000
	s_add_u32 s28, vcc_lo, 0x40080
	v_lshl_add_u64 v[168:169], v[170:171], 0, s[40:41]
	s_addc_u32 s29, vcc_hi, 0
	s_add_i32 s30, s31, s24
	global_load_lds_dwordx4 v[168:169], off
	v_lshl_add_u64 v[168:169], s[28:29], 0, v[0:1]
	s_mov_b32 m0, s30
	s_nop 0
	global_load_lds_dwordx4 v[168:169], off
	v_lshl_add_u64 v[168:169], s[28:29], 0, v[162:163]
	s_add_i32 m0, s30, 0x2000
	s_nop 0
	global_load_lds_dwordx4 v[168:169], off
	v_lshl_add_u64 v[168:169], v[172:173], 0, s[40:41]
	s_mov_b32 m0, s57
	s_nop 0
	global_load_lds_dwordx4 v[168:169], off
	v_lshl_add_u64 v[168:169], v[174:175], 0, s[40:41]
	s_mov_b32 m0, s94
	s_nop 0
	global_load_lds_dwordx4 v[168:169], off
	s_waitcnt vmcnt(8)
	s_waitcnt lgkmcnt(0)
	s_barrier
	s_setprio 1
	v_mfma_scale_f32_16x16x128_f8f6f4 v[94:97], v[2:9], v[180:187], v[94:97], v236, v236 op_sel_hi:[0,0,0]
	v_mfma_scale_f32_16x16x128_f8f6f4 v[90:93], v[10:17], v[180:187], v[90:93], v236, v236 op_sel_hi:[0,0,0]
	v_mfma_scale_f32_16x16x128_f8f6f4 v[86:89], v[2:9], v[188:195], v[86:89], v236, v236 op_sel_hi:[0,0,0]
	v_mfma_scale_f32_16x16x128_f8f6f4 v[78:81], v[10:17], v[188:195], v[78:81], v236, v236 op_sel_hi:[0,0,0]
	v_mfma_scale_f32_16x16x128_f8f6f4 v[70:73], v[2:9], v[202:209], v[70:73], v236, v236 op_sel_hi:[0,0,0]
	v_mfma_scale_f32_16x16x128_f8f6f4 v[62:65], v[10:17], v[202:209], v[62:65], v236, v236 op_sel_hi:[0,0,0]
	v_mfma_scale_f32_16x16x128_f8f6f4 v[54:57], v[2:9], v[210:217], v[54:57], v236, v236 op_sel_hi:[0,0,0]
	v_mfma_scale_f32_16x16x128_f8f6f4 v[46:49], v[10:17], v[210:217], v[46:49], v236, v236 op_sel_hi:[0,0,0]
	v_mfma_scale_f32_16x16x128_f8f6f4 v[82:85], v[18:25], v[180:187], v[82:85], v236, v236 op_sel_hi:[0,0,0]
	v_mfma_scale_f32_16x16x128_f8f6f4 v[74:77], v[26:33], v[180:187], v[74:77], v236, v236 op_sel_hi:[0,0,0]
	v_mfma_scale_f32_16x16x128_f8f6f4 v[66:69], v[18:25], v[188:195], v[66:69], v236, v236 op_sel_hi:[0,0,0]
	v_mfma_scale_f32_16x16x128_f8f6f4 v[58:61], v[26:33], v[188:195], v[58:61], v236, v236 op_sel_hi:[0,0,0]
	v_mfma_scale_f32_16x16x128_f8f6f4 v[50:53], v[18:25], v[202:209], v[50:53], v236, v236 op_sel_hi:[0,0,0]
	v_mfma_scale_f32_16x16x128_f8f6f4 v[42:45], v[26:33], v[202:209], v[42:45], v236, v236 op_sel_hi:[0,0,0]
	v_mfma_scale_f32_16x16x128_f8f6f4 v[38:41], v[18:25], v[210:217], v[38:41], v236, v236 op_sel_hi:[0,0,0]
	v_mfma_scale_f32_16x16x128_f8f6f4 v[34:37], v[26:33], v[210:217], v[34:37], v236, v236 op_sel_hi:[0,0,0]
	s_setprio 0
	s_barrier
	s_add_i32 s97, s97, 2
	s_add_u32 s72, s72, 0x100
	s_addc_u32 s73, s73, 0
	s_add_u32 s18, s18, 0x100
	s_addc_u32 s19, s19, 0
	s_cmp_gt_u32 s97, 13
	s_cbranch_scc0 .LBB0_292
	s_and_b64 vcc, exec, s[6:7]
	v_readlane_b32 s97, v249, 23
	s_cbranch_vccz .LBB0_295
	s_barrier

;     __device__ __forceinline__ bool next(int i, Unit& u) const { const int L = i * G + c; if (L >= 256) return false; u.sub = L & 3; const int t = L >> 2; u.pm = 64 + (t >> 3); u.pn = t & 7; return true; }
; #define PG8_STAGE(bufoff, gbase, voff) do { _Pragma("unroll") for (int _i = 0; _i < 2; ++_i) \
;         __builtin_amdgcn_global_load_lds((const unsigned*)((const char*)(gbase) + (voff)[_i]), (LAS unsigned*)(lds + (bufoff) + ldsw + _i * 8192), 16, 0, 0); } while (0)
; #define PG8_WAIT_V(n) asm volatile("s_waitcnt vmcnt(" #n ")" ::: "memory")
; #define PG8_WAIT_L(n) asm volatile("s_waitcnt lgkmcnt(" #n ")" ::: "memory")
; #define PG8_BAR __builtin_amdgcn_s_barrier()
; #define PG8_SCHED __builtin_amdgcn_sched_barrier(0)
;     __device__ __forceinline__ bool next(int i, Unit& u) const {
;         int L = i * G + c;
;         if (L < n0) { u.sub = 0; u.pm = L / nN0; u.pn = L - u.pm * nN0; return true; }
;         L -= n0; if (L >= n1) return false;
;         u.sub = 1; u.pm = L / nN1; u.pn = L - u.pm * nN1; return true;
;     }
;     __device__ __forceinline__ const char* ptrA(const Unit& u) const { return (u.sub ? A1 : A0) + (size_t)u.pm * aT; }
;     __device__ __forceinline__ const char* ptrB(const Unit& u) const { return (u.sub ? B1 : B0) + (size_t)u.pn * bT; }
; template <bool F8 = false, class Epi, class Sched>
; __device__ __forceinline__ void gemm_phase(LAS unsigned char* lds, const int lda, const int ldb, const int K, const Sched& S, const Epi& E) {
;     ...
;         for (int t = 0; t < nt; t += 2) {
;             const bool last = (t == nt - 2);
;             const char* a1 = cA + (size_t)(t + 1) * kstep;
;             const char* a2 = last ? nA : cA + (size_t)(t + 2) * kstep; const char* b2 = last ? nB : cB + (size_t)(t + 2) * kstep;
;             const char* a3 = a2 + kstep; const char* b3 = b2 + kstep;
;             PG8_LDB(B0, 0, 0); PG8_LDB(B1, 0, 1); PG8_SCHED; PG8_LDA(At, 0, 0); PG8_STAGE(PG8_SA(1, 1), a1 + hstepA, voffA);
;             PG8_WAIT_V(8); PG8_WAIT_L(0); PG8_BAR; PG8_MMA(0, 0, At, B0); PG8_MMA(0, 1, At, B1); PG8_BAR; PG8_SCHED;
;             PG8_LDA(At, 0, 1); PG8_STAGE(PG8_SB(0, 0), b2, voffB); PG8_STAGE(PG8_SB(0, 1), b2 + hstepB, voffB); PG8_STAGE(PG8_SA(0, 0), a2, voffA);
;             PG8_WAIT_V(8); PG8_WAIT_L(0); PG8_BAR; PG8_MMA(1, 0, At, B0); PG8_MMA(1, 1, At, B1); PG8_BAR; PG8_SCHED;
.LBB0_436:
	s_add_u32 s20, s18, 0x100
	s_addc_u32 s21, s19, 0
	s_add_i32 s30, 0, 0x10000
	s_cmp_eq_u32 s29, 4
	s_cselect_b32 s73, s15, s21
	s_cselect_b32 s72, s14, s20
	v_add_u32_e32 v140, s30, v143
	s_cselect_b32 s53, s17, s28
	s_cselect_b32 s52, s16, s11
	s_add_i32 s31, 0, 0x14000
	ds_read_b128 v[146:149], v140
	ds_read_b128 v[150:153], v140 offset:1024
	ds_read_b128 v[154:157], v140 offset:2048
	ds_read_b128 v[158:161], v140 offset:3072
	v_add_u32_e32 v140, s31, v143
	ds_read_b128 v[162:165], v140
	ds_read_b128 v[166:169], v140 offset:1024
	ds_read_b128 v[170:173], v140 offset:2048
	ds_read_b128 v[174:177], v140 offset:3072
	v_lshl_add_u64 v[140:141], s[18:19], 0, v[136:137]
	s_add_i32 m0, s13, 0xc000
	ds_read_b128 v[178:181], v145
	ds_read_b128 v[182:185], v145 offset:1024
	ds_read_b128 v[186:189], v145 offset:2048
	ds_read_b128 v[190:193], v145 offset:3072
	ds_read_b128 v[202:205], v145 offset:4096
	ds_read_b128 v[206:209], v145 offset:5120
	ds_read_b128 v[210:213], v145 offset:6144
	ds_read_b128 v[214:217], v145 offset:7168
	global_load_lds_dwordx4 v[140:141], off
	v_lshl_add_u64 v[140:141], s[18:19], 0, v[138:139]
	s_add_i32 m0, s13, 0xe000
	s_nop 0
	global_load_lds_dwordx4 v[140:141], off
	s_waitcnt vmcnt(8)
	s_waitcnt lgkmcnt(0)
	s_barrier
	s_setprio 1
	v_mfma_f32_16x16x32_bf16 v[126:129], v[146:149], v[178:181], v[126:129]
	v_mfma_f32_16x16x32_bf16 v[122:125], v[154:157], v[178:181], v[122:125]
	v_mfma_f32_16x16x32_bf16 v[118:121], v[146:149], v[186:189], v[118:121]
	v_mfma_f32_16x16x32_bf16 v[110:113], v[154:157], v[186:189], v[110:113]
	v_mfma_f32_16x16x32_bf16 v[102:105], v[146:149], v[202:205], v[102:105]
	v_mfma_f32_16x16x32_bf16 v[94:97], v[154:157], v[202:205], v[94:97]
	v_mfma_f32_16x16x32_bf16 v[86:89], v[146:149], v[210:213], v[86:89]
	v_mfma_f32_16x16x32_bf16 v[78:81], v[154:157], v[210:213], v[78:81]
	v_mfma_f32_16x16x32_bf16 v[126:129], v[150:153], v[182:185], v[126:129]
	v_mfma_f32_16x16x32_bf16 v[122:125], v[158:161], v[182:185], v[122:125]
	v_mfma_f32_16x16x32_bf16 v[118:121], v[150:153], v[190:193], v[118:121]
	v_mfma_f32_16x16x32_bf16 v[110:113], v[158:161], v[190:193], v[110:113]
	v_mfma_f32_16x16x32_bf16 v[102:105], v[150:153], v[206:209], v[102:105]
	v_mfma_f32_16x16x32_bf16 v[94:97], v[158:161], v[206:209], v[94:97]
	v_mfma_f32_16x16x32_bf16 v[86:89], v[150:153], v[214:217], v[86:89]
	v_mfma_f32_16x16x32_bf16 v[78:81], v[158:161], v[214:217], v[78:81]
	v_mfma_f32_16x16x32_bf16 v[114:117], v[162:165], v[178:181], v[114:117]
	v_mfma_f32_16x16x32_bf16 v[106:109], v[170:173], v[178:181], v[106:109]
	v_mfma_f32_16x16x32_bf16 v[98:101], v[162:165], v[186:189], v[98:101]
	v_mfma_f32_16x16x32_bf16 v[90:93], v[170:173], v[186:189], v[90:93]
	v_mfma_f32_16x16x32_bf16 v[82:85], v[162:165], v[202:205], v[82:85]
	v_mfma_f32_16x16x32_bf16 v[74:77], v[170:173], v[202:205], v[74:77]
	v_mfma_f32_16x16x32_bf16 v[70:73], v[162:165], v[210:213], v[70:73]
	v_mfma_f32_16x16x32_bf16 v[66:69], v[170:173], v[210:213], v[66:69]
	v_mfma_f32_16x16x32_bf16 v[114:117], v[166:169], v[182:185], v[114:117]
	v_mfma_f32_16x16x32_bf16 v[106:109], v[174:177], v[182:185], v[106:109]
	v_mfma_f32_16x16x32_bf16 v[98:101], v[166:169], v[190:193], v[98:101]
	v_mfma_f32_16x16x32_bf16 v[90:93], v[174:177], v[190:193], v[90:93]
	v_mfma_f32_16x16x32_bf16 v[82:85], v[166:169], v[206:209], v[82:85]
	v_mfma_f32_16x16x32_bf16 v[74:77], v[174:177], v[206:209], v[74:77]
	v_mfma_f32_16x16x32_bf16 v[70:73], v[166:169], v[214:217], v[70:73]
	v_mfma_f32_16x16x32_bf16 v[66:69], v[174:177], v[214:217], v[66:69]
	s_setprio 0
	s_barrier
	s_add_i32 s18, s30, s24
	v_lshl_add_u64 v[140:141], s[52:53], 0, v[0:1]
	s_mov_b32 m0, s18
	ds_read_b128 v[178:181], v145 offset:16384
	ds_read_b128 v[182:185], v145 offset:17408
	ds_read_b128 v[186:189], v145 offset:18432
	ds_read_b128 v[190:193], v145 offset:19456
	ds_read_b128 v[202:205], v145 offset:20480
	ds_read_b128 v[206:209], v145 offset:21504
	ds_read_b128 v[210:213], v145 offset:22528
	ds_read_b128 v[214:217], v145 offset:23552
	global_load_lds_dwordx4 v[140:141], off
	s_add_i32 m0, s18, 0x2000
	s_add_u32 s18, s52, 0x20000
	v_lshl_add_u64 v[194:195], s[52:53], 0, v[134:135]
	s_addc_u32 s19, s53, 0
	s_add_i32 s30, s31, s24
	global_load_lds_dwordx4 v[194:195], off
	v_lshl_add_u64 v[218:219], s[18:19], 0, v[0:1]
	s_mov_b32 m0, s30
	v_lshl_add_u64 v[220:221], s[72:73], 0, v[132:133]
	global_load_lds_dwordx4 v[218:219], off
	v_lshl_add_u64 v[218:219], s[18:19], 0, v[134:135]
	s_add_i32 m0, s30, 0x2000
	s_nop 0
	global_load_lds_dwordx4 v[218:219], off
	v_lshl_add_u64 v[218:219], s[72:73], 0, v[130:131]
	s_mov_b32 m0, s13
	s_nop 0
	global_load_lds_dwordx4 v[218:219], off
	s_mov_b32 m0, s25
	s_nop 0
	global_load_lds_dwordx4 v[220:221], off
	s_waitcnt vmcnt(8)
	s_waitcnt lgkmcnt(0)
	s_barrier
; #define PG8_STAGE(bufoff, gbase, voff) do { _Pragma("unroll") for (int _i = 0; _i < 2; ++_i) \
;         __builtin_amdgcn_global_load_lds((const unsigned*)((const char*)(gbase) + (voff)[_i]), (LAS unsigned*)(lds + (bufoff) + ldsw + _i * 8192), 16, 0, 0); } while (0)
; #define PG8_WAIT_V(n) asm volatile("s_waitcnt vmcnt(" #n ")" ::: "memory")
; #define PG8_WAIT_L(n) asm volatile("s_waitcnt lgkmcnt(" #n ")" ::: "memory")
; #define PG8_BAR __builtin_amdgcn_s_barrier()
; #define PG8_SCHED __builtin_amdgcn_sched_barrier(0)
; template <bool F8 = false, class Epi, class Sched>
; __device__ __forceinline__ void gemm_phase(LAS unsigned char* lds, const int lda, const int ldb, const int K, const Sched& S, const Epi& E) {
;     ...
;             PG8_WAIT_V(8); PG8_WAIT_L(0); PG8_BAR; PG8_MMA(1, 0, At, B0); PG8_MMA(1, 1, At, B1); PG8_BAR; PG8_SCHED;
;             PG8_LDB(B0, 1, 0); PG8_LDB(B1, 1, 1); PG8_SCHED; PG8_LDA(At, 1, 0); PG8_STAGE(PG8_SA(0, 1), a2 + hstepA, voffA);
;             PG8_WAIT_V(8); PG8_WAIT_L(0); PG8_BAR; PG8_MMA(0, 0, At, B0); PG8_MMA(0, 1, At, B1); PG8_BAR; PG8_SCHED;
;             PG8_LDA(At, 1, 1); PG8_STAGE(PG8_SB(1, 0), b3, voffB); PG8_STAGE(PG8_SB(1, 1), b3 + hstepB, voffB); PG8_STAGE(PG8_SA(1, 0), a3, voffA);
	s_setprio 1
	v_mfma_f32_16x16x32_bf16 v[62:65], v[146:149], v[178:181], v[62:65]
	v_mfma_f32_16x16x32_bf16 v[58:61], v[154:157], v[178:181], v[58:61]
	v_mfma_f32_16x16x32_bf16 v[54:57], v[146:149], v[186:189], v[54:57]
	v_mfma_f32_16x16x32_bf16 v[46:49], v[154:157], v[186:189], v[46:49]
	v_mfma_f32_16x16x32_bf16 v[38:41], v[146:149], v[202:205], v[38:41]
	v_mfma_f32_16x16x32_bf16 v[30:33], v[154:157], v[202:205], v[30:33]
	v_mfma_f32_16x16x32_bf16 v[22:25], v[146:149], v[210:213], v[22:25]
	v_mfma_f32_16x16x32_bf16 v[14:17], v[154:157], v[210:213], v[14:17]
	v_mfma_f32_16x16x32_bf16 v[62:65], v[150:153], v[182:185], v[62:65]
	v_mfma_f32_16x16x32_bf16 v[58:61], v[158:161], v[182:185], v[58:61]
	v_mfma_f32_16x16x32_bf16 v[54:57], v[150:153], v[190:193], v[54:57]
	v_mfma_f32_16x16x32_bf16 v[46:49], v[158:161], v[190:193], v[46:49]
	v_mfma_f32_16x16x32_bf16 v[38:41], v[150:153], v[206:209], v[38:41]
	v_mfma_f32_16x16x32_bf16 v[30:33], v[158:161], v[206:209], v[30:33]
	v_mfma_f32_16x16x32_bf16 v[22:25], v[150:153], v[214:217], v[22:25]
	v_mfma_f32_16x16x32_bf16 v[14:17], v[158:161], v[214:217], v[14:17]
	v_mfma_f32_16x16x32_bf16 v[50:53], v[162:165], v[178:181], v[50:53]
	v_mfma_f32_16x16x32_bf16 v[42:45], v[170:173], v[178:181], v[42:45]
	v_mfma_f32_16x16x32_bf16 v[34:37], v[162:165], v[186:189], v[34:37]
	v_mfma_f32_16x16x32_bf16 v[26:29], v[170:173], v[186:189], v[26:29]
	v_mfma_f32_16x16x32_bf16 v[18:21], v[162:165], v[202:205], v[18:21]
	v_mfma_f32_16x16x32_bf16 v[10:13], v[170:173], v[202:205], v[10:13]
	v_mfma_f32_16x16x32_bf16 v[6:9], v[162:165], v[210:213], v[6:9]
	v_mfma_f32_16x16x32_bf16 v[2:5], v[170:173], v[210:213], v[2:5]
	v_mfma_f32_16x16x32_bf16 v[50:53], v[166:169], v[182:185], v[50:53]
	v_mfma_f32_16x16x32_bf16 v[42:45], v[174:177], v[182:185], v[42:45]
	v_mfma_f32_16x16x32_bf16 v[34:37], v[166:169], v[190:193], v[34:37]
	v_mfma_f32_16x16x32_bf16 v[26:29], v[174:177], v[190:193], v[26:29]
	v_mfma_f32_16x16x32_bf16 v[18:21], v[166:169], v[206:209], v[18:21]
	v_mfma_f32_16x16x32_bf16 v[10:13], v[174:177], v[206:209], v[10:13]
	v_mfma_f32_16x16x32_bf16 v[6:9], v[166:169], v[214:217], v[6:9]
	v_mfma_f32_16x16x32_bf16 v[2:5], v[174:177], v[214:217], v[2:5]
	s_setprio 0
	s_barrier
	s_add_i32 s30, 0, 0x18000
	s_add_i32 s31, 0, 0x1c000
	v_add_u32_e32 v158, s30, v143
	v_add_u32_e32 v174, s31, v143
	ds_read_b128 v[146:149], v158
	ds_read_b128 v[150:153], v158 offset:1024
	ds_read_b128 v[154:157], v158 offset:2048
	ds_read_b128 v[158:161], v158 offset:3072
	ds_read_b128 v[162:165], v174
	ds_read_b128 v[166:169], v174 offset:1024
	ds_read_b128 v[170:173], v174 offset:2048
	ds_read_b128 v[174:177], v174 offset:3072
	s_add_u32 s18, s72, 0x2e4000
	s_addc_u32 s19, s73, 0
	s_mov_b32 m0, s26
	v_lshl_add_u64 v[222:223], s[18:19], 0, v[130:131]
	ds_read_b128 v[178:181], v145 offset:32768
	ds_read_b128 v[182:185], v145 offset:33792
	ds_read_b128 v[186:189], v145 offset:34816
	ds_read_b128 v[190:193], v145 offset:35840
	ds_read_b128 v[202:205], v145 offset:36864
	ds_read_b128 v[206:209], v145 offset:37888
	ds_read_b128 v[210:213], v145 offset:38912
	ds_read_b128 v[214:217], v145 offset:39936
	global_load_lds_dwordx4 v[222:223], off
	v_lshl_add_u64 v[222:223], s[18:19], 0, v[132:133]
	s_mov_b32 m0, s27
	s_nop 0
	global_load_lds_dwordx4 v[222:223], off
	s_waitcnt vmcnt(8)
	s_waitcnt lgkmcnt(0)
	s_barrier
	s_setprio 1
	v_mfma_f32_16x16x32_bf16 v[126:129], v[146:149], v[178:181], v[126:129]
	v_mfma_f32_16x16x32_bf16 v[122:125], v[154:157], v[178:181], v[122:125]
	v_mfma_f32_16x16x32_bf16 v[118:121], v[146:149], v[186:189], v[118:121]
	v_mfma_f32_16x16x32_bf16 v[110:113], v[154:157], v[186:189], v[110:113]
	v_mfma_f32_16x16x32_bf16 v[102:105], v[146:149], v[202:205], v[102:105]
	v_mfma_f32_16x16x32_bf16 v[94:97], v[154:157], v[202:205], v[94:97]
	v_mfma_f32_16x16x32_bf16 v[86:89], v[146:149], v[210:213], v[86:89]
	v_mfma_f32_16x16x32_bf16 v[78:81], v[154:157], v[210:213], v[78:81]
	v_mfma_f32_16x16x32_bf16 v[126:129], v[150:153], v[182:185], v[126:129]
	v_mfma_f32_16x16x32_bf16 v[122:125], v[158:161], v[182:185], v[122:125]
	v_mfma_f32_16x16x32_bf16 v[118:121], v[150:153], v[190:193], v[118:121]
	v_mfma_f32_16x16x32_bf16 v[110:113], v[158:161], v[190:193], v[110:113]
	v_mfma_f32_16x16x32_bf16 v[102:105], v[150:153], v[206:209], v[102:105]
	v_mfma_f32_16x16x32_bf16 v[94:97], v[158:161], v[206:209], v[94:97]
	v_mfma_f32_16x16x32_bf16 v[86:89], v[150:153], v[214:217], v[86:89]
	v_mfma_f32_16x16x32_bf16 v[78:81], v[158:161], v[214:217], v[78:81]
	v_mfma_f32_16x16x32_bf16 v[114:117], v[162:165], v[178:181], v[114:117]
	v_mfma_f32_16x16x32_bf16 v[106:109], v[170:173], v[178:181], v[106:109]
	v_mfma_f32_16x16x32_bf16 v[98:101], v[162:165], v[186:189], v[98:101]
	v_mfma_f32_16x16x32_bf16 v[90:93], v[170:173], v[186:189], v[90:93]
	v_mfma_f32_16x16x32_bf16 v[82:85], v[162:165], v[202:205], v[82:85]
	v_mfma_f32_16x16x32_bf16 v[74:77], v[170:173], v[202:205], v[74:77]
	v_mfma_f32_16x16x32_bf16 v[70:73], v[162:165], v[210:213], v[70:73]
	v_mfma_f32_16x16x32_bf16 v[66:69], v[170:173], v[210:213], v[66:69]
	v_mfma_f32_16x16x32_bf16 v[114:117], v[166:169], v[182:185], v[114:117]
	v_mfma_f32_16x16x32_bf16 v[106:109], v[174:177], v[182:185], v[106:109]
	v_mfma_f32_16x16x32_bf16 v[98:101], v[166:169], v[190:193], v[98:101]
	v_mfma_f32_16x16x32_bf16 v[90:93], v[174:177], v[190:193], v[90:93]
	v_mfma_f32_16x16x32_bf16 v[82:85], v[166:169], v[206:209], v[82:85]
	v_mfma_f32_16x16x32_bf16 v[74:77], v[174:177], v[206:209], v[74:77]
	v_mfma_f32_16x16x32_bf16 v[70:73], v[166:169], v[214:217], v[70:73]
	v_mfma_f32_16x16x32_bf16 v[66:69], v[174:177], v[214:217], v[66:69]
	s_setprio 0
	s_barrier
; #define PG8_STAGE(bufoff, gbase, voff) do { _Pragma("unroll") for (int _i = 0; _i < 2; ++_i) \
;         __builtin_amdgcn_global_load_lds((const unsigned*)((const char*)(gbase) + (voff)[_i]), (LAS unsigned*)(lds + (bufoff) + ldsw + _i * 8192), 16, 0, 0); } while (0)
; #define PG8_WAIT_V(n) asm volatile("s_waitcnt vmcnt(" #n ")" ::: "memory")
; #define PG8_WAIT_L(n) asm volatile("s_waitcnt lgkmcnt(" #n ")" ::: "memory")
; #define PG8_BAR __builtin_amdgcn_s_barrier()
; #define PG8_SCHED __builtin_amdgcn_sched_barrier(0)
; template <bool F8 = false, class Epi, class Sched>
; __device__ __forceinline__ void gemm_phase(LAS unsigned char* lds, const int lda, const int ldb, const int K, const Sched& S, const Epi& E) {
;     ...
;             PG8_LDA(At, 1, 1); PG8_STAGE(PG8_SB(1, 0), b3, voffB); PG8_STAGE(PG8_SB(1, 1), b3 + hstepB, voffB); PG8_STAGE(PG8_SA(1, 0), a3, voffA);
;             PG8_WAIT_V(8); PG8_WAIT_L(0); PG8_BAR; PG8_MMA(1, 0, At, B0); PG8_MMA(1, 1, At, B1); PG8_BAR; PG8_SCHED;
;         }
;         if (wr == 0) PG8_BAR;
	s_add_i32 s18, s30, s24
	v_lshl_add_u64 v[140:141], v[140:141], 0, s[40:41]
	s_mov_b32 m0, s18
	ds_read_b128 v[178:181], v145 offset:49152
	ds_read_b128 v[182:185], v145 offset:50176
	ds_read_b128 v[186:189], v145 offset:51200
	ds_read_b128 v[190:193], v145 offset:52224
	ds_read_b128 v[202:205], v145 offset:53248
	ds_read_b128 v[206:209], v145 offset:54272
	ds_read_b128 v[210:213], v145 offset:55296
	ds_read_b128 v[214:217], v145 offset:56320
	global_load_lds_dwordx4 v[140:141], off
	s_add_i32 m0, s18, 0x2000
	s_add_u32 s18, s52, 0x20080
	v_lshl_add_u64 v[140:141], v[194:195], 0, s[40:41]
	s_addc_u32 s19, s53, 0
	s_add_i32 s30, s31, s24
	global_load_lds_dwordx4 v[140:141], off
	v_lshl_add_u64 v[140:141], s[18:19], 0, v[0:1]
	s_mov_b32 m0, s30
	s_nop 0
	global_load_lds_dwordx4 v[140:141], off
	v_lshl_add_u64 v[140:141], s[18:19], 0, v[134:135]
	s_add_i32 m0, s30, 0x2000
	s_nop 0
	global_load_lds_dwordx4 v[140:141], off
	v_lshl_add_u64 v[140:141], v[218:219], 0, s[40:41]
	s_mov_b32 m0, s44
	s_nop 0
	global_load_lds_dwordx4 v[140:141], off
	v_lshl_add_u64 v[140:141], v[220:221], 0, s[40:41]
	s_mov_b32 m0, s56
	s_nop 0
	global_load_lds_dwordx4 v[140:141], off
	s_waitcnt vmcnt(8)
	s_waitcnt lgkmcnt(0)
	s_barrier
	s_setprio 1
	v_mfma_f32_16x16x32_bf16 v[62:65], v[146:149], v[178:181], v[62:65]
	v_mfma_f32_16x16x32_bf16 v[58:61], v[154:157], v[178:181], v[58:61]
	v_mfma_f32_16x16x32_bf16 v[54:57], v[146:149], v[186:189], v[54:57]
	v_mfma_f32_16x16x32_bf16 v[46:49], v[154:157], v[186:189], v[46:49]
	v_mfma_f32_16x16x32_bf16 v[38:41], v[146:149], v[202:205], v[38:41]
	v_mfma_f32_16x16x32_bf16 v[30:33], v[154:157], v[202:205], v[30:33]
	v_mfma_f32_16x16x32_bf16 v[22:25], v[146:149], v[210:213], v[22:25]
	v_mfma_f32_16x16x32_bf16 v[14:17], v[154:157], v[210:213], v[14:17]
	v_mfma_f32_16x16x32_bf16 v[62:65], v[150:153], v[182:185], v[62:65]
	v_mfma_f32_16x16x32_bf16 v[58:61], v[158:161], v[182:185], v[58:61]
	v_mfma_f32_16x16x32_bf16 v[54:57], v[150:153], v[190:193], v[54:57]
	v_mfma_f32_16x16x32_bf16 v[46:49], v[158:161], v[190:193], v[46:49]
	v_mfma_f32_16x16x32_bf16 v[38:41], v[150:153], v[206:209], v[38:41]
	v_mfma_f32_16x16x32_bf16 v[30:33], v[158:161], v[206:209], v[30:33]
	v_mfma_f32_16x16x32_bf16 v[22:25], v[150:153], v[214:217], v[22:25]
	v_mfma_f32_16x16x32_bf16 v[14:17], v[158:161], v[214:217], v[14:17]
	v_mfma_f32_16x16x32_bf16 v[50:53], v[162:165], v[178:181], v[50:53]
	v_mfma_f32_16x16x32_bf16 v[42:45], v[170:173], v[178:181], v[42:45]
	v_mfma_f32_16x16x32_bf16 v[34:37], v[162:165], v[186:189], v[34:37]
	v_mfma_f32_16x16x32_bf16 v[26:29], v[170:173], v[186:189], v[26:29]
	v_mfma_f32_16x16x32_bf16 v[18:21], v[162:165], v[202:205], v[18:21]
	v_mfma_f32_16x16x32_bf16 v[10:13], v[170:173], v[202:205], v[10:13]
	v_mfma_f32_16x16x32_bf16 v[6:9], v[162:165], v[210:213], v[6:9]
	v_mfma_f32_16x16x32_bf16 v[2:5], v[170:173], v[210:213], v[2:5]
	v_mfma_f32_16x16x32_bf16 v[50:53], v[166:169], v[182:185], v[50:53]
	v_mfma_f32_16x16x32_bf16 v[42:45], v[174:177], v[182:185], v[42:45]
	v_mfma_f32_16x16x32_bf16 v[34:37], v[166:169], v[190:193], v[34:37]
	v_mfma_f32_16x16x32_bf16 v[26:29], v[174:177], v[190:193], v[26:29]
	v_mfma_f32_16x16x32_bf16 v[18:21], v[166:169], v[206:209], v[18:21]
	v_mfma_f32_16x16x32_bf16 v[10:13], v[174:177], v[206:209], v[10:13]
	v_mfma_f32_16x16x32_bf16 v[6:9], v[166:169], v[214:217], v[6:9]
	v_mfma_f32_16x16x32_bf16 v[2:5], v[174:177], v[214:217], v[2:5]
	s_setprio 0
	s_barrier
	s_add_i32 s29, s29, 2
	s_add_u32 s11, s11, 0x100
	s_addc_u32 s28, s28, 0
	s_cmp_gt_u32 s29, 5
	s_mov_b64 s[18:19], s[20:21]
	s_cbranch_scc0 .LBB0_436
	s_and_b64 vcc, exec, s[8:9]
	s_cbranch_vccz .LBB0_439
	s_barrier

; #define PG8_STAGE(bufoff, gbase, voff) do { _Pragma("unroll") for (int _i = 0; _i < 2; ++_i) \
;         __builtin_amdgcn_global_load_lds((const unsigned*)((const char*)(gbase) + (voff)[_i]), (LAS unsigned*)(lds + (bufoff) + ldsw + _i * 8192), 16, 0, 0); } while (0)
; #define PG8_WAIT_V(n) asm volatile("s_waitcnt vmcnt(" #n ")" ::: "memory")
; #define PG8_WAIT_L(n) asm volatile("s_waitcnt lgkmcnt(" #n ")" ::: "memory")
; #define PG8_BAR __builtin_amdgcn_s_barrier()
; #define PG8_SCHED __builtin_amdgcn_sched_barrier(0)
; template <bool F8 = false, class Epi, class Sched>
; __device__ __forceinline__ void gemm_phase(LAS unsigned char* lds, const int lda, const int ldb, const int K, const Sched& S, const Epi& E) {
;     ...
;         for (int t = 0; t < nt; t += 2) {
;             const bool last = (t == nt - 2);
;             const char* a1 = cA + (size_t)(t + 1) * kstep;
;             const char* a2 = last ? nA : cA + (size_t)(t + 2) * kstep; const char* b2 = last ? nB : cB + (size_t)(t + 2) * kstep;
;             const char* a3 = a2 + kstep; const char* b3 = b2 + kstep;
;             PG8_LDB(B0, 0, 0); PG8_LDB(B1, 0, 1); PG8_SCHED; PG8_LDA(At, 0, 0); PG8_STAGE(PG8_SA(1, 1), a1 + hstepA, voffA);
;             PG8_WAIT_V(8); PG8_WAIT_L(0); PG8_BAR; PG8_MMA(0, 0, At, B0); PG8_MMA(0, 1, At, B1); PG8_BAR; PG8_SCHED;
;             PG8_LDA(At, 0, 1); PG8_STAGE(PG8_SB(0, 0), b2, voffB); PG8_STAGE(PG8_SB(0, 1), b2 + hstepB, voffB); PG8_STAGE(PG8_SA(0, 0), a2, voffA);
;             PG8_WAIT_V(8); PG8_WAIT_L(0); PG8_BAR; PG8_MMA(1, 0, At, B0); PG8_MMA(1, 1, At, B1); PG8_BAR; PG8_SCHED;
.LBB0_690:
	s_add_u32 s52, s18, 0x100
	s_addc_u32 s53, s19, 0
	s_add_i32 s29, 0, 0x10000
	s_cmp_eq_u32 s28, 12
	s_cselect_b32 s75, s21, s53
	s_cselect_b32 s74, s20, s52
	s_cselect_b32 s73, s11, s17
	s_cselect_b32 s72, s10, s15
	s_add_i32 s30, 0, 0x14000
	v_add_u32_e32 v142, s29, v245
	v_add_u32_e32 v158, s30, v245
	ds_read_b128 v[130:133], v142
	ds_read_b128 v[134:137], v142 offset:1024
	ds_read_b128 v[138:141], v142 offset:2048
	ds_read_b128 v[142:145], v142 offset:3072
	ds_read_b128 v[146:149], v158
	ds_read_b128 v[150:153], v158 offset:1024
	ds_read_b128 v[154:157], v158 offset:2048
	ds_read_b128 v[158:161], v158 offset:3072
	v_lshl_add_u64 v[194:195], s[18:19], 0, v[208:209]
	s_add_i32 m0, s95, 0xc000
	ds_read_b128 v[162:165], v247
	ds_read_b128 v[166:169], v247 offset:1024
	ds_read_b128 v[170:173], v247 offset:2048
	ds_read_b128 v[174:177], v247 offset:3072
	ds_read_b128 v[178:181], v247 offset:4096
	ds_read_b128 v[182:185], v247 offset:5120
	ds_read_b128 v[186:189], v247 offset:6144
	ds_read_b128 v[190:193], v247 offset:7168
	global_load_lds_dwordx4 v[194:195], off
	v_lshl_add_u64 v[194:195], s[18:19], 0, v[210:211]
	s_add_i32 m0, s95, 0xe000
	s_nop 0
	global_load_lds_dwordx4 v[194:195], off
	s_waitcnt vmcnt(8)
	s_waitcnt lgkmcnt(0)
	s_barrier
	s_setprio 1
	v_mfma_f32_16x16x32_bf16 v[126:129], v[130:133], v[162:165], v[126:129]
	v_mfma_f32_16x16x32_bf16 v[122:125], v[138:141], v[162:165], v[122:125]
	v_mfma_f32_16x16x32_bf16 v[110:113], v[130:133], v[170:173], v[110:113]
	v_mfma_f32_16x16x32_bf16 v[106:109], v[138:141], v[170:173], v[106:109]
	v_mfma_f32_16x16x32_bf16 v[94:97], v[130:133], v[178:181], v[94:97]
	v_mfma_f32_16x16x32_bf16 v[90:93], v[138:141], v[178:181], v[90:93]
	v_mfma_f32_16x16x32_bf16 v[78:81], v[130:133], v[186:189], v[78:81]
	v_mfma_f32_16x16x32_bf16 v[74:77], v[138:141], v[186:189], v[74:77]
	v_mfma_f32_16x16x32_bf16 v[126:129], v[134:137], v[166:169], v[126:129]
	v_mfma_f32_16x16x32_bf16 v[122:125], v[142:145], v[166:169], v[122:125]
	v_mfma_f32_16x16x32_bf16 v[110:113], v[134:137], v[174:177], v[110:113]
	v_mfma_f32_16x16x32_bf16 v[106:109], v[142:145], v[174:177], v[106:109]
	v_mfma_f32_16x16x32_bf16 v[94:97], v[134:137], v[182:185], v[94:97]
	v_mfma_f32_16x16x32_bf16 v[90:93], v[142:145], v[182:185], v[90:93]
	v_mfma_f32_16x16x32_bf16 v[78:81], v[134:137], v[190:193], v[78:81]
	v_mfma_f32_16x16x32_bf16 v[74:77], v[142:145], v[190:193], v[74:77]
	v_mfma_f32_16x16x32_bf16 v[118:121], v[146:149], v[162:165], v[118:121]
	v_mfma_f32_16x16x32_bf16 v[114:117], v[154:157], v[162:165], v[114:117]
	v_mfma_f32_16x16x32_bf16 v[102:105], v[146:149], v[170:173], v[102:105]
	v_mfma_f32_16x16x32_bf16 v[98:101], v[154:157], v[170:173], v[98:101]
	v_mfma_f32_16x16x32_bf16 v[86:89], v[146:149], v[178:181], v[86:89]
	v_mfma_f32_16x16x32_bf16 v[82:85], v[154:157], v[178:181], v[82:85]
	v_mfma_f32_16x16x32_bf16 v[70:73], v[146:149], v[186:189], v[70:73]
	v_mfma_f32_16x16x32_bf16 v[66:69], v[154:157], v[186:189], v[66:69]
	v_mfma_f32_16x16x32_bf16 v[118:121], v[150:153], v[166:169], v[118:121]
	v_mfma_f32_16x16x32_bf16 v[114:117], v[158:161], v[166:169], v[114:117]
	v_mfma_f32_16x16x32_bf16 v[102:105], v[150:153], v[174:177], v[102:105]
	v_mfma_f32_16x16x32_bf16 v[98:101], v[158:161], v[174:177], v[98:101]
	v_mfma_f32_16x16x32_bf16 v[86:89], v[150:153], v[182:185], v[86:89]
	v_mfma_f32_16x16x32_bf16 v[82:85], v[158:161], v[182:185], v[82:85]
	v_mfma_f32_16x16x32_bf16 v[70:73], v[150:153], v[190:193], v[70:73]
	v_mfma_f32_16x16x32_bf16 v[66:69], v[158:161], v[190:193], v[66:69]
	s_setprio 0
	s_barrier
	s_add_i32 s18, s29, s94
	v_lshl_add_u64 v[194:195], s[72:73], 0, v[0:1]
	s_mov_b32 m0, s18
	ds_read_b128 v[162:165], v247 offset:16384
	ds_read_b128 v[166:169], v247 offset:17408
	ds_read_b128 v[170:173], v247 offset:18432
	ds_read_b128 v[174:177], v247 offset:19456
	ds_read_b128 v[178:181], v247 offset:20480
	ds_read_b128 v[182:185], v247 offset:21504
	ds_read_b128 v[186:189], v247 offset:22528
	ds_read_b128 v[190:193], v247 offset:23552
	global_load_lds_dwordx4 v[194:195], off
	s_add_i32 m0, s18, 0x2000
	s_add_u32 s18, s72, 0x40000
	v_lshl_add_u64 v[212:213], s[72:73], 0, v[206:207]
	s_addc_u32 s19, s73, 0
	s_add_i32 s29, s30, s94
	global_load_lds_dwordx4 v[212:213], off
	v_lshl_add_u64 v[214:215], s[18:19], 0, v[0:1]
	s_mov_b32 m0, s29
	v_lshl_add_u64 v[216:217], s[74:75], 0, v[204:205]
	global_load_lds_dwordx4 v[214:215], off
	v_lshl_add_u64 v[214:215], s[18:19], 0, v[206:207]
	s_add_i32 m0, s29, 0x2000
	s_nop 0
	global_load_lds_dwordx4 v[214:215], off
	v_lshl_add_u64 v[214:215], s[74:75], 0, v[202:203]
	s_mov_b32 m0, s95
	s_nop 0
	global_load_lds_dwordx4 v[214:215], off
	s_mov_b32 m0, s96
	s_nop 0
	global_load_lds_dwordx4 v[216:217], off
	s_waitcnt vmcnt(8)
	s_waitcnt lgkmcnt(0)
	s_barrier
; #define PG8_STAGE(bufoff, gbase, voff) do { _Pragma("unroll") for (int _i = 0; _i < 2; ++_i) \
;         __builtin_amdgcn_global_load_lds((const unsigned*)((const char*)(gbase) + (voff)[_i]), (LAS unsigned*)(lds + (bufoff) + ldsw + _i * 8192), 16, 0, 0); } while (0)
; #define PG8_WAIT_V(n) asm volatile("s_waitcnt vmcnt(" #n ")" ::: "memory")
; #define PG8_WAIT_L(n) asm volatile("s_waitcnt lgkmcnt(" #n ")" ::: "memory")
; #define PG8_BAR __builtin_amdgcn_s_barrier()
; #define PG8_SCHED __builtin_amdgcn_sched_barrier(0)
; template <bool F8 = false, class Epi, class Sched>
; __device__ __forceinline__ void gemm_phase(LAS unsigned char* lds, const int lda, const int ldb, const int K, const Sched& S, const Epi& E) {
;     ...
;             PG8_WAIT_V(8); PG8_WAIT_L(0); PG8_BAR; PG8_MMA(1, 0, At, B0); PG8_MMA(1, 1, At, B1); PG8_BAR; PG8_SCHED;
;             PG8_LDB(B0, 1, 0); PG8_LDB(B1, 1, 1); PG8_SCHED; PG8_LDA(At, 1, 0); PG8_STAGE(PG8_SA(0, 1), a2 + hstepA, voffA);
;             PG8_WAIT_V(8); PG8_WAIT_L(0); PG8_BAR; PG8_MMA(0, 0, At, B0); PG8_MMA(0, 1, At, B1); PG8_BAR; PG8_SCHED;
;             PG8_LDA(At, 1, 1); PG8_STAGE(PG8_SB(1, 0), b3, voffB); PG8_STAGE(PG8_SB(1, 1), b3 + hstepB, voffB); PG8_STAGE(PG8_SA(1, 0), a3, voffA);
	s_setprio 1
	v_mfma_f32_16x16x32_bf16 v[62:65], v[130:133], v[162:165], v[62:65]
	v_mfma_f32_16x16x32_bf16 v[58:61], v[138:141], v[162:165], v[58:61]
	v_mfma_f32_16x16x32_bf16 v[46:49], v[130:133], v[170:173], v[46:49]
	v_mfma_f32_16x16x32_bf16 v[42:45], v[138:141], v[170:173], v[42:45]
	v_mfma_f32_16x16x32_bf16 v[30:33], v[130:133], v[178:181], v[30:33]
	v_mfma_f32_16x16x32_bf16 v[26:29], v[138:141], v[178:181], v[26:29]
	v_mfma_f32_16x16x32_bf16 v[14:17], v[130:133], v[186:189], v[14:17]
	v_mfma_f32_16x16x32_bf16 v[10:13], v[138:141], v[186:189], v[10:13]
	v_mfma_f32_16x16x32_bf16 v[62:65], v[134:137], v[166:169], v[62:65]
	v_mfma_f32_16x16x32_bf16 v[58:61], v[142:145], v[166:169], v[58:61]
	v_mfma_f32_16x16x32_bf16 v[46:49], v[134:137], v[174:177], v[46:49]
	v_mfma_f32_16x16x32_bf16 v[42:45], v[142:145], v[174:177], v[42:45]
	v_mfma_f32_16x16x32_bf16 v[30:33], v[134:137], v[182:185], v[30:33]
	v_mfma_f32_16x16x32_bf16 v[26:29], v[142:145], v[182:185], v[26:29]
	v_mfma_f32_16x16x32_bf16 v[14:17], v[134:137], v[190:193], v[14:17]
	v_mfma_f32_16x16x32_bf16 v[10:13], v[142:145], v[190:193], v[10:13]
	v_mfma_f32_16x16x32_bf16 v[54:57], v[146:149], v[162:165], v[54:57]
	v_mfma_f32_16x16x32_bf16 v[50:53], v[154:157], v[162:165], v[50:53]
	v_mfma_f32_16x16x32_bf16 v[38:41], v[146:149], v[170:173], v[38:41]
	v_mfma_f32_16x16x32_bf16 v[34:37], v[154:157], v[170:173], v[34:37]
	v_mfma_f32_16x16x32_bf16 v[22:25], v[146:149], v[178:181], v[22:25]
	v_mfma_f32_16x16x32_bf16 v[18:21], v[154:157], v[178:181], v[18:21]
	v_mfma_f32_16x16x32_bf16 v[6:9], v[146:149], v[186:189], v[6:9]
	v_mfma_f32_16x16x32_bf16 v[2:5], v[154:157], v[186:189], v[2:5]
	v_mfma_f32_16x16x32_bf16 v[54:57], v[150:153], v[166:169], v[54:57]
	v_mfma_f32_16x16x32_bf16 v[50:53], v[158:161], v[166:169], v[50:53]
	v_mfma_f32_16x16x32_bf16 v[38:41], v[150:153], v[174:177], v[38:41]
	v_mfma_f32_16x16x32_bf16 v[34:37], v[158:161], v[174:177], v[34:37]
	v_mfma_f32_16x16x32_bf16 v[22:25], v[150:153], v[182:185], v[22:25]
	v_mfma_f32_16x16x32_bf16 v[18:21], v[158:161], v[182:185], v[18:21]
	v_mfma_f32_16x16x32_bf16 v[6:9], v[150:153], v[190:193], v[6:9]
	v_mfma_f32_16x16x32_bf16 v[2:5], v[158:161], v[190:193], v[2:5]
	s_setprio 0
	s_barrier
	s_add_i32 s29, 0, 0x18000
	s_add_i32 s30, 0, 0x1c000
	v_add_u32_e32 v142, s29, v245
	v_add_u32_e32 v158, s30, v245
	ds_read_b128 v[130:133], v142
	ds_read_b128 v[134:137], v142 offset:1024
	ds_read_b128 v[138:141], v142 offset:2048
	ds_read_b128 v[142:145], v142 offset:3072
	ds_read_b128 v[146:149], v158
	ds_read_b128 v[150:153], v158 offset:1024
	ds_read_b128 v[154:157], v158 offset:2048
	ds_read_b128 v[158:161], v158 offset:3072
	s_add_u32 s18, s74, 0xc0000
	s_addc_u32 s19, s75, 0
	s_mov_b32 m0, s97
	v_lshl_add_u64 v[218:219], s[18:19], 0, v[202:203]
	ds_read_b128 v[162:165], v247 offset:32768
	ds_read_b128 v[166:169], v247 offset:33792
	ds_read_b128 v[170:173], v247 offset:34816
	ds_read_b128 v[174:177], v247 offset:35840
	ds_read_b128 v[178:181], v247 offset:36864
	ds_read_b128 v[182:185], v247 offset:37888
	ds_read_b128 v[186:189], v247 offset:38912
	ds_read_b128 v[190:193], v247 offset:39936
	global_load_lds_dwordx4 v[218:219], off
	v_lshl_add_u64 v[218:219], s[18:19], 0, v[204:205]
	s_mov_b32 m0, s56
	s_nop 0
	global_load_lds_dwordx4 v[218:219], off
	s_waitcnt vmcnt(8)
	s_waitcnt lgkmcnt(0)
	s_barrier
	s_setprio 1
	v_mfma_f32_16x16x32_bf16 v[126:129], v[130:133], v[162:165], v[126:129]
	v_mfma_f32_16x16x32_bf16 v[122:125], v[138:141], v[162:165], v[122:125]
	v_mfma_f32_16x16x32_bf16 v[110:113], v[130:133], v[170:173], v[110:113]
	v_mfma_f32_16x16x32_bf16 v[106:109], v[138:141], v[170:173], v[106:109]
	v_mfma_f32_16x16x32_bf16 v[94:97], v[130:133], v[178:181], v[94:97]
	v_mfma_f32_16x16x32_bf16 v[90:93], v[138:141], v[178:181], v[90:93]
	v_mfma_f32_16x16x32_bf16 v[78:81], v[130:133], v[186:189], v[78:81]
	v_mfma_f32_16x16x32_bf16 v[74:77], v[138:141], v[186:189], v[74:77]
	v_mfma_f32_16x16x32_bf16 v[126:129], v[134:137], v[166:169], v[126:129]
	v_mfma_f32_16x16x32_bf16 v[122:125], v[142:145], v[166:169], v[122:125]
	v_mfma_f32_16x16x32_bf16 v[110:113], v[134:137], v[174:177], v[110:113]
	v_mfma_f32_16x16x32_bf16 v[106:109], v[142:145], v[174:177], v[106:109]
	v_mfma_f32_16x16x32_bf16 v[94:97], v[134:137], v[182:185], v[94:97]
	v_mfma_f32_16x16x32_bf16 v[90:93], v[142:145], v[182:185], v[90:93]
	v_mfma_f32_16x16x32_bf16 v[78:81], v[134:137], v[190:193], v[78:81]
	v_mfma_f32_16x16x32_bf16 v[74:77], v[142:145], v[190:193], v[74:77]
	v_mfma_f32_16x16x32_bf16 v[118:121], v[146:149], v[162:165], v[118:121]
	v_mfma_f32_16x16x32_bf16 v[114:117], v[154:157], v[162:165], v[114:117]
	v_mfma_f32_16x16x32_bf16 v[102:105], v[146:149], v[170:173], v[102:105]
	v_mfma_f32_16x16x32_bf16 v[98:101], v[154:157], v[170:173], v[98:101]
	v_mfma_f32_16x16x32_bf16 v[86:89], v[146:149], v[178:181], v[86:89]
	v_mfma_f32_16x16x32_bf16 v[82:85], v[154:157], v[178:181], v[82:85]
	v_mfma_f32_16x16x32_bf16 v[70:73], v[146:149], v[186:189], v[70:73]
	v_mfma_f32_16x16x32_bf16 v[66:69], v[154:157], v[186:189], v[66:69]
	v_mfma_f32_16x16x32_bf16 v[118:121], v[150:153], v[166:169], v[118:121]
	v_mfma_f32_16x16x32_bf16 v[114:117], v[158:161], v[166:169], v[114:117]
	v_mfma_f32_16x16x32_bf16 v[102:105], v[150:153], v[174:177], v[102:105]
	v_mfma_f32_16x16x32_bf16 v[98:101], v[158:161], v[174:177], v[98:101]
	v_mfma_f32_16x16x32_bf16 v[86:89], v[150:153], v[182:185], v[86:89]
	v_mfma_f32_16x16x32_bf16 v[82:85], v[158:161], v[182:185], v[82:85]
	v_mfma_f32_16x16x32_bf16 v[70:73], v[150:153], v[190:193], v[70:73]
	v_mfma_f32_16x16x32_bf16 v[66:69], v[158:161], v[190:193], v[66:69]
	s_setprio 0
	s_barrier
; #define PG8_STAGE(bufoff, gbase, voff) do { _Pragma("unroll") for (int _i = 0; _i < 2; ++_i) \
;         __builtin_amdgcn_global_load_lds((const unsigned*)((const char*)(gbase) + (voff)[_i]), (LAS unsigned*)(lds + (bufoff) + ldsw + _i * 8192), 16, 0, 0); } while (0)
; #define PG8_WAIT_V(n) asm volatile("s_waitcnt vmcnt(" #n ")" ::: "memory")
; #define PG8_WAIT_L(n) asm volatile("s_waitcnt lgkmcnt(" #n ")" ::: "memory")
; #define PG8_BAR __builtin_amdgcn_s_barrier()
; #define PG8_SCHED __builtin_amdgcn_sched_barrier(0)
; template <bool F8 = false, class Epi, class Sched>
; __device__ __forceinline__ void gemm_phase(LAS unsigned char* lds, const int lda, const int ldb, const int K, const Sched& S, const Epi& E) {
;     ...
;             PG8_LDA(At, 1, 1); PG8_STAGE(PG8_SB(1, 0), b3, voffB); PG8_STAGE(PG8_SB(1, 1), b3 + hstepB, voffB); PG8_STAGE(PG8_SA(1, 0), a3, voffA);
;             PG8_WAIT_V(8); PG8_WAIT_L(0); PG8_BAR; PG8_MMA(1, 0, At, B0); PG8_MMA(1, 1, At, B1); PG8_BAR; PG8_SCHED;
;         }
;         if (wr == 0) PG8_BAR;
	s_add_i32 s18, s29, s94
	v_lshl_add_u64 v[194:195], v[194:195], 0, s[40:41]
	s_mov_b32 m0, s18
	ds_read_b128 v[162:165], v247 offset:49152
	ds_read_b128 v[166:169], v247 offset:50176
	ds_read_b128 v[170:173], v247 offset:51200
	ds_read_b128 v[174:177], v247 offset:52224
	ds_read_b128 v[178:181], v247 offset:53248
	ds_read_b128 v[182:185], v247 offset:54272
	ds_read_b128 v[186:189], v247 offset:55296
	ds_read_b128 v[190:193], v247 offset:56320
	global_load_lds_dwordx4 v[194:195], off
	s_add_i32 m0, s18, 0x2000
	s_add_u32 s18, s72, 0x40080
	v_lshl_add_u64 v[194:195], v[212:213], 0, s[40:41]
	s_addc_u32 s19, s73, 0
	s_add_i32 s29, s30, s94
	global_load_lds_dwordx4 v[194:195], off
	v_lshl_add_u64 v[194:195], s[18:19], 0, v[0:1]
	s_mov_b32 m0, s29
	s_nop 0
	global_load_lds_dwordx4 v[194:195], off
	v_lshl_add_u64 v[194:195], s[18:19], 0, v[206:207]
	s_add_i32 m0, s29, 0x2000
	s_nop 0
	global_load_lds_dwordx4 v[194:195], off
	v_lshl_add_u64 v[194:195], v[214:215], 0, s[40:41]
	s_mov_b32 m0, s57
	s_nop 0
	global_load_lds_dwordx4 v[194:195], off
	v_lshl_add_u64 v[194:195], v[216:217], 0, s[40:41]
	s_mov_b32 m0, s24
	s_nop 0
	global_load_lds_dwordx4 v[194:195], off
	s_waitcnt vmcnt(8)
	s_waitcnt lgkmcnt(0)
	s_barrier
	s_setprio 1
	v_mfma_f32_16x16x32_bf16 v[62:65], v[130:133], v[162:165], v[62:65]
	v_mfma_f32_16x16x32_bf16 v[58:61], v[138:141], v[162:165], v[58:61]
	v_mfma_f32_16x16x32_bf16 v[46:49], v[130:133], v[170:173], v[46:49]
	v_mfma_f32_16x16x32_bf16 v[42:45], v[138:141], v[170:173], v[42:45]
	v_mfma_f32_16x16x32_bf16 v[30:33], v[130:133], v[178:181], v[30:33]
	v_mfma_f32_16x16x32_bf16 v[26:29], v[138:141], v[178:181], v[26:29]
	v_mfma_f32_16x16x32_bf16 v[14:17], v[130:133], v[186:189], v[14:17]
	v_mfma_f32_16x16x32_bf16 v[10:13], v[138:141], v[186:189], v[10:13]
	v_mfma_f32_16x16x32_bf16 v[62:65], v[134:137], v[166:169], v[62:65]
	v_mfma_f32_16x16x32_bf16 v[58:61], v[142:145], v[166:169], v[58:61]
	v_mfma_f32_16x16x32_bf16 v[46:49], v[134:137], v[174:177], v[46:49]
	v_mfma_f32_16x16x32_bf16 v[42:45], v[142:145], v[174:177], v[42:45]
	v_mfma_f32_16x16x32_bf16 v[30:33], v[134:137], v[182:185], v[30:33]
	v_mfma_f32_16x16x32_bf16 v[26:29], v[142:145], v[182:185], v[26:29]
	v_mfma_f32_16x16x32_bf16 v[14:17], v[134:137], v[190:193], v[14:17]
	v_mfma_f32_16x16x32_bf16 v[10:13], v[142:145], v[190:193], v[10:13]
	v_mfma_f32_16x16x32_bf16 v[54:57], v[146:149], v[162:165], v[54:57]
	v_mfma_f32_16x16x32_bf16 v[50:53], v[154:157], v[162:165], v[50:53]
	v_mfma_f32_16x16x32_bf16 v[38:41], v[146:149], v[170:173], v[38:41]
	v_mfma_f32_16x16x32_bf16 v[34:37], v[154:157], v[170:173], v[34:37]
	v_mfma_f32_16x16x32_bf16 v[22:25], v[146:149], v[178:181], v[22:25]
	v_mfma_f32_16x16x32_bf16 v[18:21], v[154:157], v[178:181], v[18:21]
	v_mfma_f32_16x16x32_bf16 v[6:9], v[146:149], v[186:189], v[6:9]
	v_mfma_f32_16x16x32_bf16 v[2:5], v[154:157], v[186:189], v[2:5]
	v_mfma_f32_16x16x32_bf16 v[54:57], v[150:153], v[166:169], v[54:57]
	v_mfma_f32_16x16x32_bf16 v[50:53], v[158:161], v[166:169], v[50:53]
	v_mfma_f32_16x16x32_bf16 v[38:41], v[150:153], v[174:177], v[38:41]
	v_mfma_f32_16x16x32_bf16 v[34:37], v[158:161], v[174:177], v[34:37]
	v_mfma_f32_16x16x32_bf16 v[22:25], v[150:153], v[182:185], v[22:25]
	v_mfma_f32_16x16x32_bf16 v[18:21], v[158:161], v[182:185], v[18:21]
	v_mfma_f32_16x16x32_bf16 v[6:9], v[150:153], v[190:193], v[6:9]
	v_mfma_f32_16x16x32_bf16 v[2:5], v[158:161], v[190:193], v[2:5]
	s_setprio 0
	s_barrier
	s_add_i32 s28, s28, 2
	s_add_u32 s15, s15, 0x100
	s_addc_u32 s17, s17, 0
	s_cmp_gt_u32 s28, 13
	s_mov_b64 s[18:19], s[52:53]
	s_cbranch_scc0 .LBB0_690
	s_and_b64 vcc, exec, s[12:13]
	s_cbranch_vccz .LBB0_693
	s_barrier

; #define PG8_STAGE(bufoff, gbase, voff) do { _Pragma("unroll") for (int _i = 0; _i < 2; ++_i) \
;         __builtin_amdgcn_global_load_lds((const unsigned*)((const char*)(gbase) + (voff)[_i]), (LAS unsigned*)(lds + (bufoff) + ldsw + _i * 8192), 16, 0, 0); } while (0)
; #define PG8_WAIT_V(n) asm volatile("s_waitcnt vmcnt(" #n ")" ::: "memory")
; #define PG8_WAIT_L(n) asm volatile("s_waitcnt lgkmcnt(" #n ")" ::: "memory")
; #define PG8_BAR __builtin_amdgcn_s_barrier()
; #define PG8_SCHED __builtin_amdgcn_sched_barrier(0)
; template <bool F8 = false, class Epi, class Sched>
; __device__ __forceinline__ void gemm_phase(LAS unsigned char* lds, const int lda, const int ldb, const int K, const Sched& S, const Epi& E) {
;     ...
;         for (int t = 0; t < nt; t += 2) {
;             const bool last = (t == nt - 2);
;             const char* a1 = cA + (size_t)(t + 1) * kstep;
;             const char* a2 = last ? nA : cA + (size_t)(t + 2) * kstep; const char* b2 = last ? nB : cB + (size_t)(t + 2) * kstep;
;             const char* a3 = a2 + kstep; const char* b3 = b2 + kstep;
;             PG8_LDB(B0, 0, 0); PG8_LDB(B1, 0, 1); PG8_SCHED; PG8_LDA(At, 0, 0); PG8_STAGE(PG8_SA(1, 1), a1 + hstepA, voffA);
;             PG8_WAIT_V(8); PG8_WAIT_L(0); PG8_BAR; PG8_MMA(0, 0, At, B0); PG8_MMA(0, 1, At, B1); PG8_BAR; PG8_SCHED;
;             PG8_LDA(At, 0, 1); PG8_STAGE(PG8_SB(0, 0), b2, voffB); PG8_STAGE(PG8_SB(0, 1), b2 + hstepB, voffB); PG8_STAGE(PG8_SA(0, 0), a2, voffA);
;             PG8_WAIT_V(8); PG8_WAIT_L(0); PG8_BAR; PG8_MMA(1, 0, At, B0); PG8_MMA(1, 1, At, B1); PG8_BAR; PG8_SCHED;
.LBB0_807:
	s_add_u32 s20, s18, 0xfff80080
	s_addc_u32 s21, s19, -1
	s_add_i32 s29, 0, 0x10000
	s_cmp_eq_u32 s28, 28
	s_cselect_b32 s53, s11, s21
	s_cselect_b32 s52, s75, s20
	v_add_u32_e32 v140, s29, v143
	s_cselect_b32 s21, s9, s96
	s_cselect_b32 s20, s94, s95
	s_add_i32 s33, 0, 0x14000
	ds_read_b128 v[146:149], v140
	ds_read_b128 v[150:153], v140 offset:1024
	ds_read_b128 v[154:157], v140 offset:2048
	ds_read_b128 v[158:161], v140 offset:3072
	v_add_u32_e32 v140, s33, v143
	ds_read_b128 v[162:165], v140
	ds_read_b128 v[166:169], v140 offset:1024
	ds_read_b128 v[170:173], v140 offset:2048
	ds_read_b128 v[174:177], v140 offset:3072
	v_lshl_add_u64 v[140:141], s[18:19], 0, v[136:137]
	s_add_i32 m0, s25, 0xc000
	ds_read_b128 v[178:181], v145
	ds_read_b128 v[182:185], v145 offset:1024
	ds_read_b128 v[186:189], v145 offset:2048
	ds_read_b128 v[190:193], v145 offset:3072
	ds_read_b128 v[202:205], v145 offset:4096
	ds_read_b128 v[206:209], v145 offset:5120
	ds_read_b128 v[210:213], v145 offset:6144
	ds_read_b128 v[214:217], v145 offset:7168
	global_load_lds_dwordx4 v[140:141], off
	v_lshl_add_u64 v[140:141], s[18:19], 0, v[138:139]
	s_add_i32 m0, s25, 0xe000
	s_nop 0
	global_load_lds_dwordx4 v[140:141], off
	s_waitcnt vmcnt(8)
	s_waitcnt lgkmcnt(0)
	s_barrier
	s_setprio 1
	v_mfma_f32_16x16x32_bf16 v[126:129], v[146:149], v[178:181], v[126:129]
	v_mfma_f32_16x16x32_bf16 v[122:125], v[154:157], v[178:181], v[122:125]
	v_mfma_f32_16x16x32_bf16 v[118:121], v[146:149], v[186:189], v[118:121]
	v_mfma_f32_16x16x32_bf16 v[110:113], v[154:157], v[186:189], v[110:113]
	v_mfma_f32_16x16x32_bf16 v[102:105], v[146:149], v[202:205], v[102:105]
	v_mfma_f32_16x16x32_bf16 v[94:97], v[154:157], v[202:205], v[94:97]
	v_mfma_f32_16x16x32_bf16 v[86:89], v[146:149], v[210:213], v[86:89]
	v_mfma_f32_16x16x32_bf16 v[78:81], v[154:157], v[210:213], v[78:81]
	v_mfma_f32_16x16x32_bf16 v[126:129], v[150:153], v[182:185], v[126:129]
	v_mfma_f32_16x16x32_bf16 v[122:125], v[158:161], v[182:185], v[122:125]
	v_mfma_f32_16x16x32_bf16 v[118:121], v[150:153], v[190:193], v[118:121]
	v_mfma_f32_16x16x32_bf16 v[110:113], v[158:161], v[190:193], v[110:113]
	v_mfma_f32_16x16x32_bf16 v[102:105], v[150:153], v[206:209], v[102:105]
	v_mfma_f32_16x16x32_bf16 v[94:97], v[158:161], v[206:209], v[94:97]
	v_mfma_f32_16x16x32_bf16 v[86:89], v[150:153], v[214:217], v[86:89]
	v_mfma_f32_16x16x32_bf16 v[78:81], v[158:161], v[214:217], v[78:81]
	v_mfma_f32_16x16x32_bf16 v[114:117], v[162:165], v[178:181], v[114:117]
	v_mfma_f32_16x16x32_bf16 v[106:109], v[170:173], v[178:181], v[106:109]
	v_mfma_f32_16x16x32_bf16 v[98:101], v[162:165], v[186:189], v[98:101]
	v_mfma_f32_16x16x32_bf16 v[90:93], v[170:173], v[186:189], v[90:93]
	v_mfma_f32_16x16x32_bf16 v[82:85], v[162:165], v[202:205], v[82:85]
	v_mfma_f32_16x16x32_bf16 v[74:77], v[170:173], v[202:205], v[74:77]
	v_mfma_f32_16x16x32_bf16 v[70:73], v[162:165], v[210:213], v[70:73]
	v_mfma_f32_16x16x32_bf16 v[66:69], v[170:173], v[210:213], v[66:69]
	v_mfma_f32_16x16x32_bf16 v[114:117], v[166:169], v[182:185], v[114:117]
	v_mfma_f32_16x16x32_bf16 v[106:109], v[174:177], v[182:185], v[106:109]
	v_mfma_f32_16x16x32_bf16 v[98:101], v[166:169], v[190:193], v[98:101]
	v_mfma_f32_16x16x32_bf16 v[90:93], v[174:177], v[190:193], v[90:93]
	v_mfma_f32_16x16x32_bf16 v[82:85], v[166:169], v[206:209], v[82:85]
	v_mfma_f32_16x16x32_bf16 v[74:77], v[174:177], v[206:209], v[74:77]
	v_mfma_f32_16x16x32_bf16 v[70:73], v[166:169], v[214:217], v[70:73]
	v_mfma_f32_16x16x32_bf16 v[66:69], v[174:177], v[214:217], v[66:69]
	s_setprio 0
	s_barrier
	s_add_i32 s29, s29, s24
	v_lshl_add_u64 v[140:141], s[20:21], 0, v[0:1]
	s_mov_b32 m0, s29
	ds_read_b128 v[178:181], v145 offset:16384
	ds_read_b128 v[182:185], v145 offset:17408
	ds_read_b128 v[186:189], v145 offset:18432
	ds_read_b128 v[190:193], v145 offset:19456
	ds_read_b128 v[202:205], v145 offset:20480
	ds_read_b128 v[206:209], v145 offset:21504
	ds_read_b128 v[210:213], v145 offset:22528
	ds_read_b128 v[214:217], v145 offset:23552
	global_load_lds_dwordx4 v[140:141], off
	s_add_i32 m0, s29, 0x2000
	s_add_u32 s30, s20, 0x80000
	v_lshl_add_u64 v[194:195], s[20:21], 0, v[130:131]
	s_addc_u32 s31, s21, 0
	s_add_i32 s29, s33, s24
	global_load_lds_dwordx4 v[194:195], off
	v_lshl_add_u64 v[218:219], s[30:31], 0, v[0:1]
	s_mov_b32 m0, s29
	v_lshl_add_u64 v[220:221], s[52:53], 0, v[132:133]
	global_load_lds_dwordx4 v[218:219], off
	v_lshl_add_u64 v[218:219], s[30:31], 0, v[130:131]
	s_add_i32 m0, s29, 0x2000
	s_nop 0
	global_load_lds_dwordx4 v[218:219], off
	v_lshl_add_u64 v[218:219], s[52:53], 0, v[134:135]
	s_mov_b32 m0, s25
	s_nop 0
	global_load_lds_dwordx4 v[218:219], off
	s_mov_b32 m0, s26
	s_nop 0
	global_load_lds_dwordx4 v[220:221], off
	s_waitcnt vmcnt(8)
	s_waitcnt lgkmcnt(0)
	s_barrier
; #define PG8_STAGE(bufoff, gbase, voff) do { _Pragma("unroll") for (int _i = 0; _i < 2; ++_i) \
;         __builtin_amdgcn_global_load_lds((const unsigned*)((const char*)(gbase) + (voff)[_i]), (LAS unsigned*)(lds + (bufoff) + ldsw + _i * 8192), 16, 0, 0); } while (0)
; #define PG8_WAIT_V(n) asm volatile("s_waitcnt vmcnt(" #n ")" ::: "memory")
; #define PG8_WAIT_L(n) asm volatile("s_waitcnt lgkmcnt(" #n ")" ::: "memory")
; #define PG8_BAR __builtin_amdgcn_s_barrier()
; #define PG8_SCHED __builtin_amdgcn_sched_barrier(0)
; template <bool F8 = false, class Epi, class Sched>
; __device__ __forceinline__ void gemm_phase(LAS unsigned char* lds, const int lda, const int ldb, const int K, const Sched& S, const Epi& E) {
;     ...
;             PG8_WAIT_V(8); PG8_WAIT_L(0); PG8_BAR; PG8_MMA(1, 0, At, B0); PG8_MMA(1, 1, At, B1); PG8_BAR; PG8_SCHED;
;             PG8_LDB(B0, 1, 0); PG8_LDB(B1, 1, 1); PG8_SCHED; PG8_LDA(At, 1, 0); PG8_STAGE(PG8_SA(0, 1), a2 + hstepA, voffA);
;             PG8_WAIT_V(8); PG8_WAIT_L(0); PG8_BAR; PG8_MMA(0, 0, At, B0); PG8_MMA(0, 1, At, B1); PG8_BAR; PG8_SCHED;
;             PG8_LDA(At, 1, 1); PG8_STAGE(PG8_SB(1, 0), b3, voffB); PG8_STAGE(PG8_SB(1, 1), b3 + hstepB, voffB); PG8_STAGE(PG8_SA(1, 0), a3, voffA);
	s_setprio 1
	v_mfma_f32_16x16x32_bf16 v[62:65], v[146:149], v[178:181], v[62:65]
	v_mfma_f32_16x16x32_bf16 v[58:61], v[154:157], v[178:181], v[58:61]
	v_mfma_f32_16x16x32_bf16 v[54:57], v[146:149], v[186:189], v[54:57]
	v_mfma_f32_16x16x32_bf16 v[46:49], v[154:157], v[186:189], v[46:49]
	v_mfma_f32_16x16x32_bf16 v[38:41], v[146:149], v[202:205], v[38:41]
	v_mfma_f32_16x16x32_bf16 v[30:33], v[154:157], v[202:205], v[30:33]
	v_mfma_f32_16x16x32_bf16 v[22:25], v[146:149], v[210:213], v[22:25]
	v_mfma_f32_16x16x32_bf16 v[14:17], v[154:157], v[210:213], v[14:17]
	v_mfma_f32_16x16x32_bf16 v[62:65], v[150:153], v[182:185], v[62:65]
	v_mfma_f32_16x16x32_bf16 v[58:61], v[158:161], v[182:185], v[58:61]
	v_mfma_f32_16x16x32_bf16 v[54:57], v[150:153], v[190:193], v[54:57]
	v_mfma_f32_16x16x32_bf16 v[46:49], v[158:161], v[190:193], v[46:49]
	v_mfma_f32_16x16x32_bf16 v[38:41], v[150:153], v[206:209], v[38:41]
	v_mfma_f32_16x16x32_bf16 v[30:33], v[158:161], v[206:209], v[30:33]
	v_mfma_f32_16x16x32_bf16 v[22:25], v[150:153], v[214:217], v[22:25]
	v_mfma_f32_16x16x32_bf16 v[14:17], v[158:161], v[214:217], v[14:17]
	v_mfma_f32_16x16x32_bf16 v[50:53], v[162:165], v[178:181], v[50:53]
	v_mfma_f32_16x16x32_bf16 v[42:45], v[170:173], v[178:181], v[42:45]
	v_mfma_f32_16x16x32_bf16 v[34:37], v[162:165], v[186:189], v[34:37]
	v_mfma_f32_16x16x32_bf16 v[26:29], v[170:173], v[186:189], v[26:29]
	v_mfma_f32_16x16x32_bf16 v[18:21], v[162:165], v[202:205], v[18:21]
	v_mfma_f32_16x16x32_bf16 v[10:13], v[170:173], v[202:205], v[10:13]
	v_mfma_f32_16x16x32_bf16 v[6:9], v[162:165], v[210:213], v[6:9]
	v_mfma_f32_16x16x32_bf16 v[2:5], v[170:173], v[210:213], v[2:5]
	v_mfma_f32_16x16x32_bf16 v[50:53], v[166:169], v[182:185], v[50:53]
	v_mfma_f32_16x16x32_bf16 v[42:45], v[174:177], v[182:185], v[42:45]
	v_mfma_f32_16x16x32_bf16 v[34:37], v[166:169], v[190:193], v[34:37]
	v_mfma_f32_16x16x32_bf16 v[26:29], v[174:177], v[190:193], v[26:29]
	v_mfma_f32_16x16x32_bf16 v[18:21], v[166:169], v[206:209], v[18:21]
	v_mfma_f32_16x16x32_bf16 v[10:13], v[174:177], v[206:209], v[10:13]
	v_mfma_f32_16x16x32_bf16 v[6:9], v[166:169], v[214:217], v[6:9]
	v_mfma_f32_16x16x32_bf16 v[2:5], v[174:177], v[214:217], v[2:5]
	s_setprio 0
	s_barrier
	s_add_i32 s29, 0, 0x18000
	s_add_i32 s33, 0, 0x1c000
	v_add_u32_e32 v158, s29, v143
	v_add_u32_e32 v174, s33, v143
	ds_read_b128 v[146:149], v158
	ds_read_b128 v[150:153], v158 offset:1024
	ds_read_b128 v[154:157], v158 offset:2048
	ds_read_b128 v[158:161], v158 offset:3072
	ds_read_b128 v[162:165], v174
	ds_read_b128 v[166:169], v174 offset:1024
	ds_read_b128 v[170:173], v174 offset:2048
	ds_read_b128 v[174:177], v174 offset:3072
	s_add_u32 s30, s52, 0x80000
	s_addc_u32 s31, s53, 0
	s_mov_b32 m0, s27
	v_lshl_add_u64 v[222:223], s[30:31], 0, v[134:135]
	ds_read_b128 v[178:181], v145 offset:32768
	ds_read_b128 v[182:185], v145 offset:33792
	ds_read_b128 v[186:189], v145 offset:34816
	ds_read_b128 v[190:193], v145 offset:35840
	ds_read_b128 v[202:205], v145 offset:36864
	ds_read_b128 v[206:209], v145 offset:37888
	ds_read_b128 v[210:213], v145 offset:38912
	ds_read_b128 v[214:217], v145 offset:39936
	global_load_lds_dwordx4 v[222:223], off
	v_lshl_add_u64 v[222:223], s[30:31], 0, v[132:133]
	s_mov_b32 m0, s44
	s_nop 0
	global_load_lds_dwordx4 v[222:223], off
	s_waitcnt vmcnt(8)
	s_waitcnt lgkmcnt(0)
	s_barrier
	s_setprio 1
	v_mfma_f32_16x16x32_bf16 v[126:129], v[146:149], v[178:181], v[126:129]
	v_mfma_f32_16x16x32_bf16 v[122:125], v[154:157], v[178:181], v[122:125]
	v_mfma_f32_16x16x32_bf16 v[118:121], v[146:149], v[186:189], v[118:121]
	v_mfma_f32_16x16x32_bf16 v[110:113], v[154:157], v[186:189], v[110:113]
	v_mfma_f32_16x16x32_bf16 v[102:105], v[146:149], v[202:205], v[102:105]
	v_mfma_f32_16x16x32_bf16 v[94:97], v[154:157], v[202:205], v[94:97]
	v_mfma_f32_16x16x32_bf16 v[86:89], v[146:149], v[210:213], v[86:89]
	v_mfma_f32_16x16x32_bf16 v[78:81], v[154:157], v[210:213], v[78:81]
	v_mfma_f32_16x16x32_bf16 v[126:129], v[150:153], v[182:185], v[126:129]
	v_mfma_f32_16x16x32_bf16 v[122:125], v[158:161], v[182:185], v[122:125]
	v_mfma_f32_16x16x32_bf16 v[118:121], v[150:153], v[190:193], v[118:121]
	v_mfma_f32_16x16x32_bf16 v[110:113], v[158:161], v[190:193], v[110:113]
	v_mfma_f32_16x16x32_bf16 v[102:105], v[150:153], v[206:209], v[102:105]
	v_mfma_f32_16x16x32_bf16 v[94:97], v[158:161], v[206:209], v[94:97]
	v_mfma_f32_16x16x32_bf16 v[86:89], v[150:153], v[214:217], v[86:89]
	v_mfma_f32_16x16x32_bf16 v[78:81], v[158:161], v[214:217], v[78:81]
	v_mfma_f32_16x16x32_bf16 v[114:117], v[162:165], v[178:181], v[114:117]
	v_mfma_f32_16x16x32_bf16 v[106:109], v[170:173], v[178:181], v[106:109]
	v_mfma_f32_16x16x32_bf16 v[98:101], v[162:165], v[186:189], v[98:101]
	v_mfma_f32_16x16x32_bf16 v[90:93], v[170:173], v[186:189], v[90:93]
	v_mfma_f32_16x16x32_bf16 v[82:85], v[162:165], v[202:205], v[82:85]
	v_mfma_f32_16x16x32_bf16 v[74:77], v[170:173], v[202:205], v[74:77]
	v_mfma_f32_16x16x32_bf16 v[70:73], v[162:165], v[210:213], v[70:73]
	v_mfma_f32_16x16x32_bf16 v[66:69], v[170:173], v[210:213], v[66:69]
	v_mfma_f32_16x16x32_bf16 v[114:117], v[166:169], v[182:185], v[114:117]
	v_mfma_f32_16x16x32_bf16 v[106:109], v[174:177], v[182:185], v[106:109]
	v_mfma_f32_16x16x32_bf16 v[98:101], v[166:169], v[190:193], v[98:101]
	v_mfma_f32_16x16x32_bf16 v[90:93], v[174:177], v[190:193], v[90:93]
	v_mfma_f32_16x16x32_bf16 v[82:85], v[166:169], v[206:209], v[82:85]
	v_mfma_f32_16x16x32_bf16 v[74:77], v[174:177], v[206:209], v[74:77]
	v_mfma_f32_16x16x32_bf16 v[70:73], v[166:169], v[214:217], v[70:73]
	v_mfma_f32_16x16x32_bf16 v[66:69], v[174:177], v[214:217], v[66:69]
	s_setprio 0
	s_barrier
; #define PG8_STAGE(bufoff, gbase, voff) do { _Pragma("unroll") for (int _i = 0; _i < 2; ++_i) \
;         __builtin_amdgcn_global_load_lds((const unsigned*)((const char*)(gbase) + (voff)[_i]), (LAS unsigned*)(lds + (bufoff) + ldsw + _i * 8192), 16, 0, 0); } while (0)
; #define PG8_WAIT_V(n) asm volatile("s_waitcnt vmcnt(" #n ")" ::: "memory")
; #define PG8_WAIT_L(n) asm volatile("s_waitcnt lgkmcnt(" #n ")" ::: "memory")
; #define PG8_BAR __builtin_amdgcn_s_barrier()
; #define PG8_SCHED __builtin_amdgcn_sched_barrier(0)
; template <bool F8 = false, class Epi, class Sched>
; __device__ __forceinline__ void gemm_phase(LAS unsigned char* lds, const int lda, const int ldb, const int K, const Sched& S, const Epi& E) {
;     ...
;             PG8_LDA(At, 1, 1); PG8_STAGE(PG8_SB(1, 0), b3, voffB); PG8_STAGE(PG8_SB(1, 1), b3 + hstepB, voffB); PG8_STAGE(PG8_SA(1, 0), a3, voffA);
;             PG8_WAIT_V(8); PG8_WAIT_L(0); PG8_BAR; PG8_MMA(1, 0, At, B0); PG8_MMA(1, 1, At, B1); PG8_BAR; PG8_SCHED;
;         }
;         if (wr == 0) PG8_BAR;
	s_add_i32 s29, s29, s24
	v_lshl_add_u64 v[140:141], v[140:141], 0, s[40:41]
	s_mov_b32 m0, s29
	ds_read_b128 v[178:181], v145 offset:49152
	ds_read_b128 v[182:185], v145 offset:50176
	ds_read_b128 v[186:189], v145 offset:51200
	ds_read_b128 v[190:193], v145 offset:52224
	ds_read_b128 v[202:205], v145 offset:53248
	ds_read_b128 v[206:209], v145 offset:54272
	ds_read_b128 v[210:213], v145 offset:55296
	ds_read_b128 v[214:217], v145 offset:56320
	global_load_lds_dwordx4 v[140:141], off
	s_add_i32 m0, s29, 0x2000
	s_add_u32 s20, s20, 0x80080
	v_lshl_add_u64 v[140:141], v[194:195], 0, s[40:41]
	s_addc_u32 s21, s21, 0
	s_add_i32 s29, s33, s24
	global_load_lds_dwordx4 v[140:141], off
	v_lshl_add_u64 v[140:141], s[20:21], 0, v[0:1]
	s_mov_b32 m0, s29
	s_nop 0
	global_load_lds_dwordx4 v[140:141], off
	v_lshl_add_u64 v[140:141], s[20:21], 0, v[130:131]
	s_add_i32 m0, s29, 0x2000
	s_nop 0
	global_load_lds_dwordx4 v[140:141], off
	v_lshl_add_u64 v[140:141], v[218:219], 0, s[40:41]
	s_mov_b32 m0, s56
	s_nop 0
	global_load_lds_dwordx4 v[140:141], off
	v_lshl_add_u64 v[140:141], v[220:221], 0, s[40:41]
	s_mov_b32 m0, s57
	s_nop 0
	global_load_lds_dwordx4 v[140:141], off
	s_waitcnt vmcnt(8)
	s_waitcnt lgkmcnt(0)
	s_barrier
	s_setprio 1
	v_mfma_f32_16x16x32_bf16 v[62:65], v[146:149], v[178:181], v[62:65]
	v_mfma_f32_16x16x32_bf16 v[58:61], v[154:157], v[178:181], v[58:61]
	v_mfma_f32_16x16x32_bf16 v[54:57], v[146:149], v[186:189], v[54:57]
	v_mfma_f32_16x16x32_bf16 v[46:49], v[154:157], v[186:189], v[46:49]
	v_mfma_f32_16x16x32_bf16 v[38:41], v[146:149], v[202:205], v[38:41]
	v_mfma_f32_16x16x32_bf16 v[30:33], v[154:157], v[202:205], v[30:33]
	v_mfma_f32_16x16x32_bf16 v[22:25], v[146:149], v[210:213], v[22:25]
	v_mfma_f32_16x16x32_bf16 v[14:17], v[154:157], v[210:213], v[14:17]
	v_mfma_f32_16x16x32_bf16 v[62:65], v[150:153], v[182:185], v[62:65]
	v_mfma_f32_16x16x32_bf16 v[58:61], v[158:161], v[182:185], v[58:61]
	v_mfma_f32_16x16x32_bf16 v[54:57], v[150:153], v[190:193], v[54:57]
	v_mfma_f32_16x16x32_bf16 v[46:49], v[158:161], v[190:193], v[46:49]
	v_mfma_f32_16x16x32_bf16 v[38:41], v[150:153], v[206:209], v[38:41]
	v_mfma_f32_16x16x32_bf16 v[30:33], v[158:161], v[206:209], v[30:33]
	v_mfma_f32_16x16x32_bf16 v[22:25], v[150:153], v[214:217], v[22:25]
	v_mfma_f32_16x16x32_bf16 v[14:17], v[158:161], v[214:217], v[14:17]
	v_mfma_f32_16x16x32_bf16 v[50:53], v[162:165], v[178:181], v[50:53]
	v_mfma_f32_16x16x32_bf16 v[42:45], v[170:173], v[178:181], v[42:45]
	v_mfma_f32_16x16x32_bf16 v[34:37], v[162:165], v[186:189], v[34:37]
	v_mfma_f32_16x16x32_bf16 v[26:29], v[170:173], v[186:189], v[26:29]
	v_mfma_f32_16x16x32_bf16 v[18:21], v[162:165], v[202:205], v[18:21]
	v_mfma_f32_16x16x32_bf16 v[10:13], v[170:173], v[202:205], v[10:13]
	v_mfma_f32_16x16x32_bf16 v[6:9], v[162:165], v[210:213], v[6:9]
	v_mfma_f32_16x16x32_bf16 v[2:5], v[170:173], v[210:213], v[2:5]
	v_mfma_f32_16x16x32_bf16 v[50:53], v[166:169], v[182:185], v[50:53]
	v_mfma_f32_16x16x32_bf16 v[42:45], v[174:177], v[182:185], v[42:45]
	v_mfma_f32_16x16x32_bf16 v[34:37], v[166:169], v[190:193], v[34:37]
	v_mfma_f32_16x16x32_bf16 v[26:29], v[174:177], v[190:193], v[26:29]
	v_mfma_f32_16x16x32_bf16 v[18:21], v[166:169], v[206:209], v[18:21]
	v_mfma_f32_16x16x32_bf16 v[10:13], v[174:177], v[206:209], v[10:13]
	v_mfma_f32_16x16x32_bf16 v[6:9], v[166:169], v[214:217], v[6:9]
	v_mfma_f32_16x16x32_bf16 v[2:5], v[174:177], v[214:217], v[2:5]
	s_setprio 0
	s_barrier
	s_add_i32 s28, s28, 2
	s_add_u32 s18, s18, 0x100
	s_addc_u32 s19, s19, 0
	s_add_u32 s95, s95, 0x100
	s_addc_u32 s96, s96, 0
	s_cmp_gt_u32 s28, 29
	s_cbranch_scc0 .LBB0_807
	s_and_b64 vcc, exec, s[6:7]
	s_cbranch_vccz .LBB0_810
	s_barrier

; #define PG8_STAGE(bufoff, gbase, voff) do { _Pragma("unroll") for (int _i = 0; _i < 2; ++_i) \
;         __builtin_amdgcn_global_load_lds((const unsigned*)((const char*)(gbase) + (voff)[_i]), (LAS unsigned*)(lds + (bufoff) + ldsw + _i * 8192), 16, 0, 0); } while (0)
; #define PG8_WAIT_V(n) asm volatile("s_waitcnt vmcnt(" #n ")" ::: "memory")
; #define PG8_WAIT_L(n) asm volatile("s_waitcnt lgkmcnt(" #n ")" ::: "memory")
; #define PG8_BAR __builtin_amdgcn_s_barrier()
; #define PG8_SCHED __builtin_amdgcn_sched_barrier(0)
; template <bool F8 = false, class Epi, class Sched>
; __device__ __forceinline__ void gemm_phase(LAS unsigned char* lds, const int lda, const int ldb, const int K, const Sched& S, const Epi& E) {
;     ...
;         for (int t = 0; t < nt; t += 2) {
;             const bool last = (t == nt - 2);
;             const char* a1 = cA + (size_t)(t + 1) * kstep;
;             const char* a2 = last ? nA : cA + (size_t)(t + 2) * kstep; const char* b2 = last ? nB : cB + (size_t)(t + 2) * kstep;
;             const char* a3 = a2 + kstep; const char* b3 = b2 + kstep;
;             PG8_LDB(B0, 0, 0); PG8_LDB(B1, 0, 1); PG8_SCHED; PG8_LDA(At, 0, 0); PG8_STAGE(PG8_SA(1, 1), a1 + hstepA, voffA);
;             PG8_WAIT_V(8); PG8_WAIT_L(0); PG8_BAR; PG8_MMA(0, 0, At, B0); PG8_MMA(0, 1, At, B1); PG8_BAR; PG8_SCHED;
;             PG8_LDA(At, 0, 1); PG8_STAGE(PG8_SB(0, 0), b2, voffB); PG8_STAGE(PG8_SB(0, 1), b2 + hstepB, voffB); PG8_STAGE(PG8_SA(0, 0), a2, voffA);
;             PG8_WAIT_V(8); PG8_WAIT_L(0); PG8_BAR; PG8_MMA(1, 0, At, B0); PG8_MMA(1, 1, At, B1); PG8_BAR; PG8_SCHED;
.LBB0_835:
	s_add_u32 s18, s16, 0xfff80080
	s_addc_u32 s19, s17, -1
	s_add_i32 s29, 0, 0x10000
	s_cmp_eq_u32 s28, 4
	s_cselect_b32 s21, s13, s19
	s_cselect_b32 s20, s12, s18
	v_add_u32_e32 v0, s29, v140
	s_cselect_b32 s19, s75, s96
	s_cselect_b32 s18, s94, s95
	s_add_i32 s33, 0, 0x14000
	ds_read_b128 v[144:147], v0
	ds_read_b128 v[148:151], v0 offset:1024
	ds_read_b128 v[152:155], v0 offset:2048
	ds_read_b128 v[156:159], v0 offset:3072
	v_add_u32_e32 v0, s33, v140
	ds_read_b128 v[160:163], v0
	ds_read_b128 v[164:167], v0 offset:1024
	ds_read_b128 v[168:171], v0 offset:2048
	ds_read_b128 v[172:175], v0 offset:3072
	v_lshl_add_u64 v[138:139], s[16:17], 0, v[134:135]
	s_add_i32 m0, s25, 0xc000
	ds_read_b128 v[176:179], v142
	ds_read_b128 v[180:183], v142 offset:1024
	ds_read_b128 v[184:187], v142 offset:2048
	ds_read_b128 v[188:191], v142 offset:3072
	ds_read_b128 v[192:195], v142 offset:4096
	ds_read_b128 v[202:205], v142 offset:5120
	ds_read_b128 v[206:209], v142 offset:6144
	ds_read_b128 v[210:213], v142 offset:7168
	global_load_lds_dwordx4 v[138:139], off
	v_lshl_add_u64 v[138:139], s[16:17], 0, v[136:137]
	s_add_i32 m0, s25, 0xe000
	s_nop 0
	global_load_lds_dwordx4 v[138:139], off
	s_waitcnt vmcnt(8)
	s_waitcnt lgkmcnt(0)
	s_barrier
	s_setprio 1
	v_mfma_f32_16x16x32_bf16 v[126:129], v[144:147], v[176:179], v[126:129]
	v_mfma_f32_16x16x32_bf16 v[122:125], v[152:155], v[176:179], v[122:125]
	v_mfma_f32_16x16x32_bf16 v[118:121], v[144:147], v[184:187], v[118:121]
	v_mfma_f32_16x16x32_bf16 v[110:113], v[152:155], v[184:187], v[110:113]
	v_mfma_f32_16x16x32_bf16 v[102:105], v[144:147], v[192:195], v[102:105]
	v_mfma_f32_16x16x32_bf16 v[94:97], v[152:155], v[192:195], v[94:97]
	v_mfma_f32_16x16x32_bf16 v[86:89], v[144:147], v[206:209], v[86:89]
	v_mfma_f32_16x16x32_bf16 v[78:81], v[152:155], v[206:209], v[78:81]
	v_mfma_f32_16x16x32_bf16 v[126:129], v[148:151], v[180:183], v[126:129]
	v_mfma_f32_16x16x32_bf16 v[122:125], v[156:159], v[180:183], v[122:125]
	v_mfma_f32_16x16x32_bf16 v[118:121], v[148:151], v[188:191], v[118:121]
	v_mfma_f32_16x16x32_bf16 v[110:113], v[156:159], v[188:191], v[110:113]
	v_mfma_f32_16x16x32_bf16 v[102:105], v[148:151], v[202:205], v[102:105]
	v_mfma_f32_16x16x32_bf16 v[94:97], v[156:159], v[202:205], v[94:97]
	v_mfma_f32_16x16x32_bf16 v[86:89], v[148:151], v[210:213], v[86:89]
	v_mfma_f32_16x16x32_bf16 v[78:81], v[156:159], v[210:213], v[78:81]
	v_mfma_f32_16x16x32_bf16 v[114:117], v[160:163], v[176:179], v[114:117]
	v_mfma_f32_16x16x32_bf16 v[106:109], v[168:171], v[176:179], v[106:109]
	v_mfma_f32_16x16x32_bf16 v[98:101], v[160:163], v[184:187], v[98:101]
	v_mfma_f32_16x16x32_bf16 v[90:93], v[168:171], v[184:187], v[90:93]
	v_mfma_f32_16x16x32_bf16 v[82:85], v[160:163], v[192:195], v[82:85]
	v_mfma_f32_16x16x32_bf16 v[74:77], v[168:171], v[192:195], v[74:77]
	v_mfma_f32_16x16x32_bf16 v[70:73], v[160:163], v[206:209], v[70:73]
	v_mfma_f32_16x16x32_bf16 v[66:69], v[168:171], v[206:209], v[66:69]
	v_mfma_f32_16x16x32_bf16 v[114:117], v[164:167], v[180:183], v[114:117]
	v_mfma_f32_16x16x32_bf16 v[106:109], v[172:175], v[180:183], v[106:109]
	v_mfma_f32_16x16x32_bf16 v[98:101], v[164:167], v[188:191], v[98:101]
	v_mfma_f32_16x16x32_bf16 v[90:93], v[172:175], v[188:191], v[90:93]
	v_mfma_f32_16x16x32_bf16 v[82:85], v[164:167], v[202:205], v[82:85]
	v_mfma_f32_16x16x32_bf16 v[74:77], v[172:175], v[202:205], v[74:77]
	v_mfma_f32_16x16x32_bf16 v[70:73], v[164:167], v[210:213], v[70:73]
	v_mfma_f32_16x16x32_bf16 v[66:69], v[172:175], v[210:213], v[66:69]
	s_setprio 0
	s_barrier
	s_add_i32 s29, s29, s24
	v_lshl_add_u64 v[138:139], s[18:19], 0, v[132:133]
	s_mov_b32 m0, s29
	ds_read_b128 v[176:179], v142 offset:16384
	ds_read_b128 v[180:183], v142 offset:17408
	ds_read_b128 v[184:187], v142 offset:18432
	ds_read_b128 v[188:191], v142 offset:19456
	ds_read_b128 v[192:195], v142 offset:20480
	ds_read_b128 v[202:205], v142 offset:21504
	ds_read_b128 v[206:209], v142 offset:22528
	ds_read_b128 v[210:213], v142 offset:23552
	global_load_lds_dwordx4 v[138:139], off
	s_add_i32 m0, s29, 0x2000
	s_add_u32 s30, s18, 0x80000
	v_lshl_add_u64 v[214:215], s[18:19], 0, v[130:131]
	s_addc_u32 s31, s19, 0
	s_add_i32 s29, s33, s24
	global_load_lds_dwordx4 v[214:215], off
	v_lshl_add_u64 v[216:217], s[30:31], 0, v[132:133]
	s_mov_b32 m0, s29
	v_lshl_add_u64 v[218:219], s[20:21], 0, v[130:131]
	global_load_lds_dwordx4 v[216:217], off
	v_lshl_add_u64 v[216:217], s[30:31], 0, v[130:131]
	s_add_i32 m0, s29, 0x2000
	s_nop 0
	global_load_lds_dwordx4 v[216:217], off
	v_lshl_add_u64 v[216:217], s[20:21], 0, v[132:133]
	s_mov_b32 m0, s25
	s_nop 0
	global_load_lds_dwordx4 v[216:217], off
	s_mov_b32 m0, s26
	s_nop 0
	global_load_lds_dwordx4 v[218:219], off
	s_waitcnt vmcnt(8)
	s_waitcnt lgkmcnt(0)
	s_barrier
; #define PG8_STAGE(bufoff, gbase, voff) do { _Pragma("unroll") for (int _i = 0; _i < 2; ++_i) \
;         __builtin_amdgcn_global_load_lds((const unsigned*)((const char*)(gbase) + (voff)[_i]), (LAS unsigned*)(lds + (bufoff) + ldsw + _i * 8192), 16, 0, 0); } while (0)
; #define PG8_WAIT_V(n) asm volatile("s_waitcnt vmcnt(" #n ")" ::: "memory")
; #define PG8_WAIT_L(n) asm volatile("s_waitcnt lgkmcnt(" #n ")" ::: "memory")
; #define PG8_BAR __builtin_amdgcn_s_barrier()
; #define PG8_SCHED __builtin_amdgcn_sched_barrier(0)
; template <bool F8 = false, class Epi, class Sched>
; __device__ __forceinline__ void gemm_phase(LAS unsigned char* lds, const int lda, const int ldb, const int K, const Sched& S, const Epi& E) {
;     ...
;             PG8_WAIT_V(8); PG8_WAIT_L(0); PG8_BAR; PG8_MMA(1, 0, At, B0); PG8_MMA(1, 1, At, B1); PG8_BAR; PG8_SCHED;
;             PG8_LDB(B0, 1, 0); PG8_LDB(B1, 1, 1); PG8_SCHED; PG8_LDA(At, 1, 0); PG8_STAGE(PG8_SA(0, 1), a2 + hstepA, voffA);
;             PG8_WAIT_V(8); PG8_WAIT_L(0); PG8_BAR; PG8_MMA(0, 0, At, B0); PG8_MMA(0, 1, At, B1); PG8_BAR; PG8_SCHED;
;             PG8_LDA(At, 1, 1); PG8_STAGE(PG8_SB(1, 0), b3, voffB); PG8_STAGE(PG8_SB(1, 1), b3 + hstepB, voffB); PG8_STAGE(PG8_SA(1, 0), a3, voffA);
	s_setprio 1
	v_mfma_f32_16x16x32_bf16 v[62:65], v[144:147], v[176:179], v[62:65]
	v_mfma_f32_16x16x32_bf16 v[58:61], v[152:155], v[176:179], v[58:61]
	v_mfma_f32_16x16x32_bf16 v[54:57], v[144:147], v[184:187], v[54:57]
	v_mfma_f32_16x16x32_bf16 v[42:45], v[152:155], v[184:187], v[42:45]
	v_mfma_f32_16x16x32_bf16 v[38:41], v[144:147], v[192:195], v[38:41]
	v_mfma_f32_16x16x32_bf16 v[26:29], v[152:155], v[192:195], v[26:29]
	v_mfma_f32_16x16x32_bf16 v[22:25], v[144:147], v[206:209], v[22:25]
	v_mfma_f32_16x16x32_bf16 v[10:13], v[152:155], v[206:209], v[10:13]
	v_mfma_f32_16x16x32_bf16 v[62:65], v[148:151], v[180:183], v[62:65]
	v_mfma_f32_16x16x32_bf16 v[58:61], v[156:159], v[180:183], v[58:61]
	v_mfma_f32_16x16x32_bf16 v[54:57], v[148:151], v[188:191], v[54:57]
	v_mfma_f32_16x16x32_bf16 v[42:45], v[156:159], v[188:191], v[42:45]
	v_mfma_f32_16x16x32_bf16 v[38:41], v[148:151], v[202:205], v[38:41]
	v_mfma_f32_16x16x32_bf16 v[26:29], v[156:159], v[202:205], v[26:29]
	v_mfma_f32_16x16x32_bf16 v[22:25], v[148:151], v[210:213], v[22:25]
	v_mfma_f32_16x16x32_bf16 v[10:13], v[156:159], v[210:213], v[10:13]
	v_mfma_f32_16x16x32_bf16 v[50:53], v[160:163], v[176:179], v[50:53]
	v_mfma_f32_16x16x32_bf16 v[46:49], v[168:171], v[176:179], v[46:49]
	v_mfma_f32_16x16x32_bf16 v[34:37], v[160:163], v[184:187], v[34:37]
	v_mfma_f32_16x16x32_bf16 v[30:33], v[168:171], v[184:187], v[30:33]
	v_mfma_f32_16x16x32_bf16 v[18:21], v[160:163], v[192:195], v[18:21]
	v_mfma_f32_16x16x32_bf16 v[14:17], v[168:171], v[192:195], v[14:17]
	v_mfma_f32_16x16x32_bf16 v[6:9], v[160:163], v[206:209], v[6:9]
	v_mfma_f32_16x16x32_bf16 v[2:5], v[168:171], v[206:209], v[2:5]
	v_mfma_f32_16x16x32_bf16 v[50:53], v[164:167], v[180:183], v[50:53]
	v_mfma_f32_16x16x32_bf16 v[46:49], v[172:175], v[180:183], v[46:49]
	v_mfma_f32_16x16x32_bf16 v[34:37], v[164:167], v[188:191], v[34:37]
	v_mfma_f32_16x16x32_bf16 v[30:33], v[172:175], v[188:191], v[30:33]
	v_mfma_f32_16x16x32_bf16 v[18:21], v[164:167], v[202:205], v[18:21]
	v_mfma_f32_16x16x32_bf16 v[14:17], v[172:175], v[202:205], v[14:17]
	v_mfma_f32_16x16x32_bf16 v[6:9], v[164:167], v[210:213], v[6:9]
	v_mfma_f32_16x16x32_bf16 v[2:5], v[172:175], v[210:213], v[2:5]
	s_setprio 0
	s_barrier
	s_add_i32 s29, 0, 0x18000
	v_add_u32_e32 v0, s29, v140
	s_add_i32 s30, 0, 0x1c000
	ds_read_b128 v[144:147], v0
	ds_read_b128 v[148:151], v0 offset:1024
	ds_read_b128 v[152:155], v0 offset:2048
	ds_read_b128 v[156:159], v0 offset:3072
	v_add_u32_e32 v0, s30, v140
	ds_read_b128 v[160:163], v0
	ds_read_b128 v[164:167], v0 offset:1024
	ds_read_b128 v[168:171], v0 offset:2048
	ds_read_b128 v[172:175], v0 offset:3072
	s_add_u32 s20, s20, 0x80000
	s_addc_u32 s21, s21, 0
	s_mov_b32 m0, s27
	v_lshl_add_u64 v[220:221], s[20:21], 0, v[132:133]
	ds_read_b128 v[176:179], v142 offset:32768
	ds_read_b128 v[180:183], v142 offset:33792
	ds_read_b128 v[184:187], v142 offset:34816
	ds_read_b128 v[188:191], v142 offset:35840
	ds_read_b128 v[192:195], v142 offset:36864
	ds_read_b128 v[202:205], v142 offset:37888
	ds_read_b128 v[206:209], v142 offset:38912
	ds_read_b128 v[210:213], v142 offset:39936
	global_load_lds_dwordx4 v[220:221], off
	v_lshl_add_u64 v[220:221], s[20:21], 0, v[130:131]
	s_mov_b32 m0, s44
	s_nop 0
	global_load_lds_dwordx4 v[220:221], off
	s_waitcnt vmcnt(8)
	s_waitcnt lgkmcnt(0)
	s_barrier
	s_setprio 1
	v_mfma_f32_16x16x32_bf16 v[126:129], v[144:147], v[176:179], v[126:129]
	v_mfma_f32_16x16x32_bf16 v[122:125], v[152:155], v[176:179], v[122:125]
	v_mfma_f32_16x16x32_bf16 v[118:121], v[144:147], v[184:187], v[118:121]
	v_mfma_f32_16x16x32_bf16 v[110:113], v[152:155], v[184:187], v[110:113]
	v_mfma_f32_16x16x32_bf16 v[102:105], v[144:147], v[192:195], v[102:105]
	v_mfma_f32_16x16x32_bf16 v[94:97], v[152:155], v[192:195], v[94:97]
	v_mfma_f32_16x16x32_bf16 v[86:89], v[144:147], v[206:209], v[86:89]
	v_mfma_f32_16x16x32_bf16 v[78:81], v[152:155], v[206:209], v[78:81]
	v_mfma_f32_16x16x32_bf16 v[126:129], v[148:151], v[180:183], v[126:129]
	v_mfma_f32_16x16x32_bf16 v[122:125], v[156:159], v[180:183], v[122:125]
	v_mfma_f32_16x16x32_bf16 v[118:121], v[148:151], v[188:191], v[118:121]
	v_mfma_f32_16x16x32_bf16 v[110:113], v[156:159], v[188:191], v[110:113]
	v_mfma_f32_16x16x32_bf16 v[102:105], v[148:151], v[202:205], v[102:105]
	v_mfma_f32_16x16x32_bf16 v[94:97], v[156:159], v[202:205], v[94:97]
	v_mfma_f32_16x16x32_bf16 v[86:89], v[148:151], v[210:213], v[86:89]
	v_mfma_f32_16x16x32_bf16 v[78:81], v[156:159], v[210:213], v[78:81]
	v_mfma_f32_16x16x32_bf16 v[114:117], v[160:163], v[176:179], v[114:117]
	v_mfma_f32_16x16x32_bf16 v[106:109], v[168:171], v[176:179], v[106:109]
	v_mfma_f32_16x16x32_bf16 v[98:101], v[160:163], v[184:187], v[98:101]
	v_mfma_f32_16x16x32_bf16 v[90:93], v[168:171], v[184:187], v[90:93]
	v_mfma_f32_16x16x32_bf16 v[82:85], v[160:163], v[192:195], v[82:85]
	v_mfma_f32_16x16x32_bf16 v[74:77], v[168:171], v[192:195], v[74:77]
	v_mfma_f32_16x16x32_bf16 v[70:73], v[160:163], v[206:209], v[70:73]
	v_mfma_f32_16x16x32_bf16 v[66:69], v[168:171], v[206:209], v[66:69]
	v_mfma_f32_16x16x32_bf16 v[114:117], v[164:167], v[180:183], v[114:117]
	v_mfma_f32_16x16x32_bf16 v[106:109], v[172:175], v[180:183], v[106:109]
	v_mfma_f32_16x16x32_bf16 v[98:101], v[164:167], v[188:191], v[98:101]
	v_mfma_f32_16x16x32_bf16 v[90:93], v[172:175], v[188:191], v[90:93]
	v_mfma_f32_16x16x32_bf16 v[82:85], v[164:167], v[202:205], v[82:85]
	v_mfma_f32_16x16x32_bf16 v[74:77], v[172:175], v[202:205], v[74:77]
	v_mfma_f32_16x16x32_bf16 v[70:73], v[164:167], v[210:213], v[70:73]
	v_mfma_f32_16x16x32_bf16 v[66:69], v[172:175], v[210:213], v[66:69]
	s_setprio 0
	s_barrier
; #define PG8_STAGE(bufoff, gbase, voff) do { _Pragma("unroll") for (int _i = 0; _i < 2; ++_i) \
;         __builtin_amdgcn_global_load_lds((const unsigned*)((const char*)(gbase) + (voff)[_i]), (LAS unsigned*)(lds + (bufoff) + ldsw + _i * 8192), 16, 0, 0); } while (0)
; #define PG8_WAIT_V(n) asm volatile("s_waitcnt vmcnt(" #n ")" ::: "memory")
; #define PG8_WAIT_L(n) asm volatile("s_waitcnt lgkmcnt(" #n ")" ::: "memory")
; #define PG8_BAR __builtin_amdgcn_s_barrier()
; #define PG8_SCHED __builtin_amdgcn_sched_barrier(0)
; template <bool F8 = false, class Epi, class Sched>
; __device__ __forceinline__ void gemm_phase(LAS unsigned char* lds, const int lda, const int ldb, const int K, const Sched& S, const Epi& E) {
;     ...
;             PG8_LDA(At, 1, 1); PG8_STAGE(PG8_SB(1, 0), b3, voffB); PG8_STAGE(PG8_SB(1, 1), b3 + hstepB, voffB); PG8_STAGE(PG8_SA(1, 0), a3, voffA);
;             PG8_WAIT_V(8); PG8_WAIT_L(0); PG8_BAR; PG8_MMA(1, 0, At, B0); PG8_MMA(1, 1, At, B1); PG8_BAR; PG8_SCHED;
;         }
;         if (wr == 0) PG8_BAR;
	s_add_i32 s20, s29, s24
	v_lshl_add_u64 v[138:139], v[138:139], 0, s[40:41]
	s_mov_b32 m0, s20
	ds_read_b128 v[176:179], v142 offset:49152
	ds_read_b128 v[180:183], v142 offset:50176
	ds_read_b128 v[184:187], v142 offset:51200
	ds_read_b128 v[188:191], v142 offset:52224
	ds_read_b128 v[192:195], v142 offset:53248
	ds_read_b128 v[202:205], v142 offset:54272
	ds_read_b128 v[206:209], v142 offset:55296
	ds_read_b128 v[210:213], v142 offset:56320
	global_load_lds_dwordx4 v[138:139], off
	s_add_i32 m0, s20, 0x2000
	s_add_u32 s18, s18, 0x80080
	v_lshl_add_u64 v[138:139], v[214:215], 0, s[40:41]
	s_addc_u32 s19, s19, 0
	s_add_i32 s20, s30, s24
	global_load_lds_dwordx4 v[138:139], off
	v_lshl_add_u64 v[138:139], s[18:19], 0, v[132:133]
	s_mov_b32 m0, s20
	s_nop 0
	global_load_lds_dwordx4 v[138:139], off
	v_lshl_add_u64 v[138:139], s[18:19], 0, v[130:131]
	s_add_i32 m0, s20, 0x2000
	s_nop 0
	global_load_lds_dwordx4 v[138:139], off
	v_lshl_add_u64 v[138:139], v[216:217], 0, s[40:41]
	s_mov_b32 m0, s52
	s_nop 0
	global_load_lds_dwordx4 v[138:139], off
	v_lshl_add_u64 v[138:139], v[218:219], 0, s[40:41]
	s_mov_b32 m0, s53
	s_nop 0
	global_load_lds_dwordx4 v[138:139], off
	s_waitcnt vmcnt(8)
	s_waitcnt lgkmcnt(0)
	s_barrier
	s_setprio 1
	v_mfma_f32_16x16x32_bf16 v[62:65], v[144:147], v[176:179], v[62:65]
	v_mfma_f32_16x16x32_bf16 v[58:61], v[152:155], v[176:179], v[58:61]
	v_mfma_f32_16x16x32_bf16 v[54:57], v[144:147], v[184:187], v[54:57]
	v_mfma_f32_16x16x32_bf16 v[42:45], v[152:155], v[184:187], v[42:45]
	v_mfma_f32_16x16x32_bf16 v[38:41], v[144:147], v[192:195], v[38:41]
	v_mfma_f32_16x16x32_bf16 v[26:29], v[152:155], v[192:195], v[26:29]
	v_mfma_f32_16x16x32_bf16 v[22:25], v[144:147], v[206:209], v[22:25]
	v_mfma_f32_16x16x32_bf16 v[10:13], v[152:155], v[206:209], v[10:13]
	v_mfma_f32_16x16x32_bf16 v[62:65], v[148:151], v[180:183], v[62:65]
	v_mfma_f32_16x16x32_bf16 v[58:61], v[156:159], v[180:183], v[58:61]
	v_mfma_f32_16x16x32_bf16 v[54:57], v[148:151], v[188:191], v[54:57]
	v_mfma_f32_16x16x32_bf16 v[42:45], v[156:159], v[188:191], v[42:45]
	v_mfma_f32_16x16x32_bf16 v[38:41], v[148:151], v[202:205], v[38:41]
	v_mfma_f32_16x16x32_bf16 v[26:29], v[156:159], v[202:205], v[26:29]
	v_mfma_f32_16x16x32_bf16 v[22:25], v[148:151], v[210:213], v[22:25]
	v_mfma_f32_16x16x32_bf16 v[10:13], v[156:159], v[210:213], v[10:13]
	v_mfma_f32_16x16x32_bf16 v[50:53], v[160:163], v[176:179], v[50:53]
	v_mfma_f32_16x16x32_bf16 v[46:49], v[168:171], v[176:179], v[46:49]
	v_mfma_f32_16x16x32_bf16 v[34:37], v[160:163], v[184:187], v[34:37]
	v_mfma_f32_16x16x32_bf16 v[30:33], v[168:171], v[184:187], v[30:33]
	v_mfma_f32_16x16x32_bf16 v[18:21], v[160:163], v[192:195], v[18:21]
	v_mfma_f32_16x16x32_bf16 v[14:17], v[168:171], v[192:195], v[14:17]
	v_mfma_f32_16x16x32_bf16 v[6:9], v[160:163], v[206:209], v[6:9]
	v_mfma_f32_16x16x32_bf16 v[2:5], v[168:171], v[206:209], v[2:5]
	v_mfma_f32_16x16x32_bf16 v[50:53], v[164:167], v[180:183], v[50:53]
	v_mfma_f32_16x16x32_bf16 v[46:49], v[172:175], v[180:183], v[46:49]
	v_mfma_f32_16x16x32_bf16 v[34:37], v[164:167], v[188:191], v[34:37]
	v_mfma_f32_16x16x32_bf16 v[30:33], v[172:175], v[188:191], v[30:33]
	v_mfma_f32_16x16x32_bf16 v[18:21], v[164:167], v[202:205], v[18:21]
	v_mfma_f32_16x16x32_bf16 v[14:17], v[172:175], v[202:205], v[14:17]
	v_mfma_f32_16x16x32_bf16 v[6:9], v[164:167], v[210:213], v[6:9]
	v_mfma_f32_16x16x32_bf16 v[2:5], v[172:175], v[210:213], v[2:5]
	s_setprio 0
	s_barrier
	s_add_i32 s28, s28, 2
	s_add_u32 s16, s16, 0x100
	s_addc_u32 s17, s17, 0
	s_add_u32 s95, s95, 0x100
	s_addc_u32 s96, s96, 0
	s_cmp_gt_u32 s28, 5
	s_cbranch_scc0 .LBB0_835
	s_and_b64 vcc, exec, s[6:7]
	s_cbranch_vccz .LBB0_838
	s_barrier

; #define PG8_STAGE(bufoff, gbase, voff) do { _Pragma("unroll") for (int _i = 0; _i < 2; ++_i) \
;         __builtin_amdgcn_global_load_lds((const unsigned*)((const char*)(gbase) + (voff)[_i]), (LAS unsigned*)(lds + (bufoff) + ldsw + _i * 8192), 16, 0, 0); } while (0)
; #define PG8_WAIT_V(n) asm volatile("s_waitcnt vmcnt(" #n ")" ::: "memory")
; #define PG8_WAIT_L(n) asm volatile("s_waitcnt lgkmcnt(" #n ")" ::: "memory")
; #define PG8_BAR __builtin_amdgcn_s_barrier()
; #define PG8_SCHED __builtin_amdgcn_sched_barrier(0)
; template <bool F8 = false, class Epi, class Sched>
; __device__ __forceinline__ void gemm_phase(LAS unsigned char* lds, const int lda, const int ldb, const int K, const Sched& S, const Epi& E) {
;     ...
;         for (int t = 0; t < nt; t += 2) {
;             const bool last = (t == nt - 2);
;             const char* a1 = cA + (size_t)(t + 1) * kstep;
;             const char* a2 = last ? nA : cA + (size_t)(t + 2) * kstep; const char* b2 = last ? nB : cB + (size_t)(t + 2) * kstep;
;             const char* a3 = a2 + kstep; const char* b3 = b2 + kstep;
;             PG8_LDB(B0, 0, 0); PG8_LDB(B1, 0, 1); PG8_SCHED; PG8_LDA(At, 0, 0); PG8_STAGE(PG8_SA(1, 1), a1 + hstepA, voffA);
;             PG8_WAIT_V(8); PG8_WAIT_L(0); PG8_BAR; PG8_MMA(0, 0, At, B0); PG8_MMA(0, 1, At, B1); PG8_BAR; PG8_SCHED;
;             PG8_LDA(At, 0, 1); PG8_STAGE(PG8_SB(0, 0), b2, voffB); PG8_STAGE(PG8_SB(0, 1), b2 + hstepB, voffB); PG8_STAGE(PG8_SA(0, 0), a2, voffA);
;             PG8_WAIT_V(8); PG8_WAIT_L(0); PG8_BAR; PG8_MMA(1, 0, At, B0); PG8_MMA(1, 1, At, B1); PG8_BAR; PG8_SCHED;
.LBB0_1062:
	s_add_u32 s30, vcc_lo, 0xfff80080
	s_addc_u32 s31, vcc_hi, -1
	s_add_i32 s33, 0, 0x10000
	s_cmp_eq_u32 s29, 28
	s_cselect_b32 s75, s13, s31
	s_cselect_b32 s74, s26, s30
	s_cselect_b32 s53, s9, s28
	s_cselect_b32 s52, s27, s73
	s_add_i32 s93, 0, 0x14000
	v_add_u32_e32 v152, s33, v141
	v_add_u32_e32 v168, s93, v141
	ds_read_b128 v[136:139], v152
	ds_read_b128 v[144:147], v152 offset:1024
	ds_read_b128 v[148:151], v152 offset:2048
	ds_read_b128 v[152:155], v152 offset:3072
	ds_read_b128 v[156:159], v168
	ds_read_b128 v[160:163], v168 offset:1024
	ds_read_b128 v[164:167], v168 offset:2048
	ds_read_b128 v[168:171], v168 offset:3072
	v_lshl_add_u64 v[210:211], vcc, 0, v[132:133]
	s_add_i32 m0, s19, 0xc000
	ds_read_b128 v[172:175], v143
	ds_read_b128 v[176:179], v143 offset:1024
	ds_read_b128 v[180:183], v143 offset:2048
	ds_read_b128 v[184:187], v143 offset:3072
	ds_read_b128 v[188:191], v143 offset:4096
	ds_read_b128 v[192:195], v143 offset:5120
	ds_read_b128 v[202:205], v143 offset:6144
	ds_read_b128 v[206:209], v143 offset:7168
	global_load_lds_dwordx4 v[210:211], off
	v_lshl_add_u64 v[210:211], vcc, 0, v[134:135]
	s_add_i32 m0, s19, 0xe000
	s_nop 0
	global_load_lds_dwordx4 v[210:211], off
	s_waitcnt vmcnt(8)
	s_waitcnt lgkmcnt(0)
	s_barrier
	s_setprio 1
	v_mfma_f32_16x16x32_bf16 v[126:129], v[136:139], v[172:175], v[126:129]
	v_mfma_f32_16x16x32_bf16 v[122:125], v[148:151], v[172:175], v[122:125]
	v_mfma_f32_16x16x32_bf16 v[110:113], v[136:139], v[180:183], v[110:113]
	v_mfma_f32_16x16x32_bf16 v[106:109], v[148:151], v[180:183], v[106:109]
	v_mfma_f32_16x16x32_bf16 v[94:97], v[136:139], v[188:191], v[94:97]
	v_mfma_f32_16x16x32_bf16 v[90:93], v[148:151], v[188:191], v[90:93]
	v_mfma_f32_16x16x32_bf16 v[78:81], v[136:139], v[202:205], v[78:81]
	v_mfma_f32_16x16x32_bf16 v[74:77], v[148:151], v[202:205], v[74:77]
	v_mfma_f32_16x16x32_bf16 v[126:129], v[144:147], v[176:179], v[126:129]
	v_mfma_f32_16x16x32_bf16 v[122:125], v[152:155], v[176:179], v[122:125]
	v_mfma_f32_16x16x32_bf16 v[110:113], v[144:147], v[184:187], v[110:113]
	v_mfma_f32_16x16x32_bf16 v[106:109], v[152:155], v[184:187], v[106:109]
	v_mfma_f32_16x16x32_bf16 v[94:97], v[144:147], v[192:195], v[94:97]
	v_mfma_f32_16x16x32_bf16 v[90:93], v[152:155], v[192:195], v[90:93]
	v_mfma_f32_16x16x32_bf16 v[78:81], v[144:147], v[206:209], v[78:81]
	v_mfma_f32_16x16x32_bf16 v[74:77], v[152:155], v[206:209], v[74:77]
	v_mfma_f32_16x16x32_bf16 v[118:121], v[156:159], v[172:175], v[118:121]
	v_mfma_f32_16x16x32_bf16 v[114:117], v[164:167], v[172:175], v[114:117]
	v_mfma_f32_16x16x32_bf16 v[102:105], v[156:159], v[180:183], v[102:105]
	v_mfma_f32_16x16x32_bf16 v[98:101], v[164:167], v[180:183], v[98:101]
	v_mfma_f32_16x16x32_bf16 v[86:89], v[156:159], v[188:191], v[86:89]
	v_mfma_f32_16x16x32_bf16 v[82:85], v[164:167], v[188:191], v[82:85]
	v_mfma_f32_16x16x32_bf16 v[70:73], v[156:159], v[202:205], v[70:73]
	v_mfma_f32_16x16x32_bf16 v[66:69], v[164:167], v[202:205], v[66:69]
	v_mfma_f32_16x16x32_bf16 v[118:121], v[160:163], v[176:179], v[118:121]
	v_mfma_f32_16x16x32_bf16 v[114:117], v[168:171], v[176:179], v[114:117]
	v_mfma_f32_16x16x32_bf16 v[102:105], v[160:163], v[184:187], v[102:105]
	v_mfma_f32_16x16x32_bf16 v[98:101], v[168:171], v[184:187], v[98:101]
	v_mfma_f32_16x16x32_bf16 v[86:89], v[160:163], v[192:195], v[86:89]
	v_mfma_f32_16x16x32_bf16 v[82:85], v[168:171], v[192:195], v[82:85]
	v_mfma_f32_16x16x32_bf16 v[70:73], v[160:163], v[206:209], v[70:73]
	v_mfma_f32_16x16x32_bf16 v[66:69], v[168:171], v[206:209], v[66:69]
	s_setprio 0
	s_barrier
	s_add_i32 s30, s33, s94
	v_lshl_add_u64 v[210:211], s[52:53], 0, v[0:1]
	s_mov_b32 m0, s30
	ds_read_b128 v[172:175], v143 offset:16384
	ds_read_b128 v[176:179], v143 offset:17408
	ds_read_b128 v[180:183], v143 offset:18432
	ds_read_b128 v[184:187], v143 offset:19456
	ds_read_b128 v[188:191], v143 offset:20480
	ds_read_b128 v[192:195], v143 offset:21504
	ds_read_b128 v[202:205], v143 offset:22528
	ds_read_b128 v[206:209], v143 offset:23552
	global_load_lds_dwordx4 v[210:211], off
	s_add_i32 m0, s30, 0x2000
	s_add_u32 s30, s52, 0x80000
	v_lshl_add_u64 v[212:213], s[52:53], 0, v[130:131]
	s_addc_u32 s31, s53, 0
	s_add_i32 s33, s93, s94
	global_load_lds_dwordx4 v[212:213], off
	v_lshl_add_u64 v[214:215], s[30:31], 0, v[0:1]
	s_mov_b32 m0, s33
	v_lshl_add_u64 v[216:217], s[74:75], 0, v[130:131]
	global_load_lds_dwordx4 v[214:215], off
	v_lshl_add_u64 v[214:215], s[30:31], 0, v[130:131]
	s_add_i32 m0, s33, 0x2000
	s_nop 0
	global_load_lds_dwordx4 v[214:215], off
	v_lshl_add_u64 v[214:215], s[74:75], 0, v[0:1]
	s_mov_b32 m0, s19
	s_nop 0
	global_load_lds_dwordx4 v[214:215], off
	s_mov_b32 m0, s56
	s_nop 0
	global_load_lds_dwordx4 v[216:217], off
	s_waitcnt vmcnt(8)
	s_waitcnt lgkmcnt(0)
	s_barrier
; #define PG8_STAGE(bufoff, gbase, voff) do { _Pragma("unroll") for (int _i = 0; _i < 2; ++_i) \
;         __builtin_amdgcn_global_load_lds((const unsigned*)((const char*)(gbase) + (voff)[_i]), (LAS unsigned*)(lds + (bufoff) + ldsw + _i * 8192), 16, 0, 0); } while (0)
; #define PG8_WAIT_V(n) asm volatile("s_waitcnt vmcnt(" #n ")" ::: "memory")
; #define PG8_WAIT_L(n) asm volatile("s_waitcnt lgkmcnt(" #n ")" ::: "memory")
; #define PG8_BAR __builtin_amdgcn_s_barrier()
; #define PG8_SCHED __builtin_amdgcn_sched_barrier(0)
; template <bool F8 = false, class Epi, class Sched>
; __device__ __forceinline__ void gemm_phase(LAS unsigned char* lds, const int lda, const int ldb, const int K, const Sched& S, const Epi& E) {
;     ...
;             PG8_WAIT_V(8); PG8_WAIT_L(0); PG8_BAR; PG8_MMA(1, 0, At, B0); PG8_MMA(1, 1, At, B1); PG8_BAR; PG8_SCHED;
;             PG8_LDB(B0, 1, 0); PG8_LDB(B1, 1, 1); PG8_SCHED; PG8_LDA(At, 1, 0); PG8_STAGE(PG8_SA(0, 1), a2 + hstepA, voffA);
;             PG8_WAIT_V(8); PG8_WAIT_L(0); PG8_BAR; PG8_MMA(0, 0, At, B0); PG8_MMA(0, 1, At, B1); PG8_BAR; PG8_SCHED;
;             PG8_LDA(At, 1, 1); PG8_STAGE(PG8_SB(1, 0), b3, voffB); PG8_STAGE(PG8_SB(1, 1), b3 + hstepB, voffB); PG8_STAGE(PG8_SA(1, 0), a3, voffA);
	s_setprio 1
	v_mfma_f32_16x16x32_bf16 v[62:65], v[136:139], v[172:175], v[62:65]
	v_mfma_f32_16x16x32_bf16 v[58:61], v[148:151], v[172:175], v[58:61]
	v_mfma_f32_16x16x32_bf16 v[46:49], v[136:139], v[180:183], v[46:49]
	v_mfma_f32_16x16x32_bf16 v[42:45], v[148:151], v[180:183], v[42:45]
	v_mfma_f32_16x16x32_bf16 v[30:33], v[136:139], v[188:191], v[30:33]
	v_mfma_f32_16x16x32_bf16 v[26:29], v[148:151], v[188:191], v[26:29]
	v_mfma_f32_16x16x32_bf16 v[14:17], v[136:139], v[202:205], v[14:17]
	v_mfma_f32_16x16x32_bf16 v[10:13], v[148:151], v[202:205], v[10:13]
	v_mfma_f32_16x16x32_bf16 v[62:65], v[144:147], v[176:179], v[62:65]
	v_mfma_f32_16x16x32_bf16 v[58:61], v[152:155], v[176:179], v[58:61]
	v_mfma_f32_16x16x32_bf16 v[46:49], v[144:147], v[184:187], v[46:49]
	v_mfma_f32_16x16x32_bf16 v[42:45], v[152:155], v[184:187], v[42:45]
	v_mfma_f32_16x16x32_bf16 v[30:33], v[144:147], v[192:195], v[30:33]
	v_mfma_f32_16x16x32_bf16 v[26:29], v[152:155], v[192:195], v[26:29]
	v_mfma_f32_16x16x32_bf16 v[14:17], v[144:147], v[206:209], v[14:17]
	v_mfma_f32_16x16x32_bf16 v[10:13], v[152:155], v[206:209], v[10:13]
	v_mfma_f32_16x16x32_bf16 v[54:57], v[156:159], v[172:175], v[54:57]
	v_mfma_f32_16x16x32_bf16 v[50:53], v[164:167], v[172:175], v[50:53]
	v_mfma_f32_16x16x32_bf16 v[38:41], v[156:159], v[180:183], v[38:41]
	v_mfma_f32_16x16x32_bf16 v[34:37], v[164:167], v[180:183], v[34:37]
	v_mfma_f32_16x16x32_bf16 v[22:25], v[156:159], v[188:191], v[22:25]
	v_mfma_f32_16x16x32_bf16 v[18:21], v[164:167], v[188:191], v[18:21]
	v_mfma_f32_16x16x32_bf16 v[6:9], v[156:159], v[202:205], v[6:9]
	v_mfma_f32_16x16x32_bf16 v[2:5], v[164:167], v[202:205], v[2:5]
	v_mfma_f32_16x16x32_bf16 v[54:57], v[160:163], v[176:179], v[54:57]
	v_mfma_f32_16x16x32_bf16 v[50:53], v[168:171], v[176:179], v[50:53]
	v_mfma_f32_16x16x32_bf16 v[38:41], v[160:163], v[184:187], v[38:41]
	v_mfma_f32_16x16x32_bf16 v[34:37], v[168:171], v[184:187], v[34:37]
	v_mfma_f32_16x16x32_bf16 v[22:25], v[160:163], v[192:195], v[22:25]
	v_mfma_f32_16x16x32_bf16 v[18:21], v[168:171], v[192:195], v[18:21]
	v_mfma_f32_16x16x32_bf16 v[6:9], v[160:163], v[206:209], v[6:9]
	v_mfma_f32_16x16x32_bf16 v[2:5], v[168:171], v[206:209], v[2:5]
	s_setprio 0
	s_barrier
	s_add_i32 s33, 0, 0x18000
	s_add_i32 s93, 0, 0x1c000
	v_add_u32_e32 v152, s33, v141
	v_add_u32_e32 v168, s93, v141
	ds_read_b128 v[136:139], v152
	ds_read_b128 v[144:147], v152 offset:1024
	ds_read_b128 v[148:151], v152 offset:2048
	ds_read_b128 v[152:155], v152 offset:3072
	ds_read_b128 v[156:159], v168
	ds_read_b128 v[160:163], v168 offset:1024
	ds_read_b128 v[164:167], v168 offset:2048
	ds_read_b128 v[168:171], v168 offset:3072
	s_add_u32 s30, s74, 0x80000
	s_addc_u32 s31, s75, 0
	s_mov_b32 m0, s57
	v_lshl_add_u64 v[218:219], s[30:31], 0, v[0:1]
	ds_read_b128 v[172:175], v143 offset:32768
	ds_read_b128 v[176:179], v143 offset:33792
	ds_read_b128 v[180:183], v143 offset:34816
	ds_read_b128 v[184:187], v143 offset:35840
	ds_read_b128 v[188:191], v143 offset:36864
	ds_read_b128 v[192:195], v143 offset:37888
	ds_read_b128 v[202:205], v143 offset:38912
	ds_read_b128 v[206:209], v143 offset:39936
	global_load_lds_dwordx4 v[218:219], off
	v_lshl_add_u64 v[218:219], s[30:31], 0, v[130:131]
	s_mov_b32 m0, s96
	s_nop 0
	global_load_lds_dwordx4 v[218:219], off
	s_waitcnt vmcnt(8)
	s_waitcnt lgkmcnt(0)
	s_barrier
	s_setprio 1
	v_mfma_f32_16x16x32_bf16 v[126:129], v[136:139], v[172:175], v[126:129]
	v_mfma_f32_16x16x32_bf16 v[122:125], v[148:151], v[172:175], v[122:125]
	v_mfma_f32_16x16x32_bf16 v[110:113], v[136:139], v[180:183], v[110:113]
	v_mfma_f32_16x16x32_bf16 v[106:109], v[148:151], v[180:183], v[106:109]
	v_mfma_f32_16x16x32_bf16 v[94:97], v[136:139], v[188:191], v[94:97]
	v_mfma_f32_16x16x32_bf16 v[90:93], v[148:151], v[188:191], v[90:93]
	v_mfma_f32_16x16x32_bf16 v[78:81], v[136:139], v[202:205], v[78:81]
	v_mfma_f32_16x16x32_bf16 v[74:77], v[148:151], v[202:205], v[74:77]
	v_mfma_f32_16x16x32_bf16 v[126:129], v[144:147], v[176:179], v[126:129]
	v_mfma_f32_16x16x32_bf16 v[122:125], v[152:155], v[176:179], v[122:125]
	v_mfma_f32_16x16x32_bf16 v[110:113], v[144:147], v[184:187], v[110:113]
	v_mfma_f32_16x16x32_bf16 v[106:109], v[152:155], v[184:187], v[106:109]
	v_mfma_f32_16x16x32_bf16 v[94:97], v[144:147], v[192:195], v[94:97]
	v_mfma_f32_16x16x32_bf16 v[90:93], v[152:155], v[192:195], v[90:93]
	v_mfma_f32_16x16x32_bf16 v[78:81], v[144:147], v[206:209], v[78:81]
	v_mfma_f32_16x16x32_bf16 v[74:77], v[152:155], v[206:209], v[74:77]
	v_mfma_f32_16x16x32_bf16 v[118:121], v[156:159], v[172:175], v[118:121]
	v_mfma_f32_16x16x32_bf16 v[114:117], v[164:167], v[172:175], v[114:117]
	v_mfma_f32_16x16x32_bf16 v[102:105], v[156:159], v[180:183], v[102:105]
	v_mfma_f32_16x16x32_bf16 v[98:101], v[164:167], v[180:183], v[98:101]
	v_mfma_f32_16x16x32_bf16 v[86:89], v[156:159], v[188:191], v[86:89]
	v_mfma_f32_16x16x32_bf16 v[82:85], v[164:167], v[188:191], v[82:85]
	v_mfma_f32_16x16x32_bf16 v[70:73], v[156:159], v[202:205], v[70:73]
	v_mfma_f32_16x16x32_bf16 v[66:69], v[164:167], v[202:205], v[66:69]
	v_mfma_f32_16x16x32_bf16 v[118:121], v[160:163], v[176:179], v[118:121]
	v_mfma_f32_16x16x32_bf16 v[114:117], v[168:171], v[176:179], v[114:117]
	v_mfma_f32_16x16x32_bf16 v[102:105], v[160:163], v[184:187], v[102:105]
	v_mfma_f32_16x16x32_bf16 v[98:101], v[168:171], v[184:187], v[98:101]
	v_mfma_f32_16x16x32_bf16 v[86:89], v[160:163], v[192:195], v[86:89]
	v_mfma_f32_16x16x32_bf16 v[82:85], v[168:171], v[192:195], v[82:85]
	v_mfma_f32_16x16x32_bf16 v[70:73], v[160:163], v[206:209], v[70:73]
	v_mfma_f32_16x16x32_bf16 v[66:69], v[168:171], v[206:209], v[66:69]
	s_setprio 0
	s_barrier
; #define PG8_STAGE(bufoff, gbase, voff) do { _Pragma("unroll") for (int _i = 0; _i < 2; ++_i) \
;         __builtin_amdgcn_global_load_lds((const unsigned*)((const char*)(gbase) + (voff)[_i]), (LAS unsigned*)(lds + (bufoff) + ldsw + _i * 8192), 16, 0, 0); } while (0)
; #define PG8_WAIT_V(n) asm volatile("s_waitcnt vmcnt(" #n ")" ::: "memory")
; #define PG8_WAIT_L(n) asm volatile("s_waitcnt lgkmcnt(" #n ")" ::: "memory")
; #define PG8_BAR __builtin_amdgcn_s_barrier()
; #define PG8_SCHED __builtin_amdgcn_sched_barrier(0)
; template <bool F8 = false, class Epi, class Sched>
; __device__ __forceinline__ void gemm_phase(LAS unsigned char* lds, const int lda, const int ldb, const int K, const Sched& S, const Epi& E) {
;     ...
;             PG8_LDA(At, 1, 1); PG8_STAGE(PG8_SB(1, 0), b3, voffB); PG8_STAGE(PG8_SB(1, 1), b3 + hstepB, voffB); PG8_STAGE(PG8_SA(1, 0), a3, voffA);
;             PG8_WAIT_V(8); PG8_WAIT_L(0); PG8_BAR; PG8_MMA(1, 0, At, B0); PG8_MMA(1, 1, At, B1); PG8_BAR; PG8_SCHED;
;         }
;         if (wr == 0) PG8_BAR;
	s_add_i32 s30, s33, s94
	v_lshl_add_u64 v[210:211], v[210:211], 0, s[40:41]
	s_mov_b32 m0, s30
	ds_read_b128 v[172:175], v143 offset:49152
	ds_read_b128 v[176:179], v143 offset:50176
	ds_read_b128 v[180:183], v143 offset:51200
	ds_read_b128 v[184:187], v143 offset:52224
	ds_read_b128 v[188:191], v143 offset:53248
	ds_read_b128 v[192:195], v143 offset:54272
	ds_read_b128 v[202:205], v143 offset:55296
	ds_read_b128 v[206:209], v143 offset:56320
	global_load_lds_dwordx4 v[210:211], off
	s_add_i32 m0, s30, 0x2000
	s_add_u32 s30, s52, 0x80080
	v_lshl_add_u64 v[210:211], v[212:213], 0, s[40:41]
	s_addc_u32 s31, s53, 0
	s_add_i32 s33, s93, s94
	global_load_lds_dwordx4 v[210:211], off
	v_lshl_add_u64 v[210:211], s[30:31], 0, v[0:1]
	s_mov_b32 m0, s33
	s_nop 0
	global_load_lds_dwordx4 v[210:211], off
	v_lshl_add_u64 v[210:211], s[30:31], 0, v[130:131]
	s_add_i32 m0, s33, 0x2000
	s_nop 0
	global_load_lds_dwordx4 v[210:211], off
	v_lshl_add_u64 v[210:211], v[214:215], 0, s[40:41]
	s_mov_b32 m0, s24
	s_nop 0
	global_load_lds_dwordx4 v[210:211], off
	v_lshl_add_u64 v[210:211], v[216:217], 0, s[40:41]
	s_mov_b32 m0, s25
	s_nop 0
	global_load_lds_dwordx4 v[210:211], off
	s_waitcnt vmcnt(8)
	s_waitcnt lgkmcnt(0)
	s_barrier
	s_setprio 1
	v_mfma_f32_16x16x32_bf16 v[62:65], v[136:139], v[172:175], v[62:65]
	v_mfma_f32_16x16x32_bf16 v[58:61], v[148:151], v[172:175], v[58:61]
	v_mfma_f32_16x16x32_bf16 v[46:49], v[136:139], v[180:183], v[46:49]
	v_mfma_f32_16x16x32_bf16 v[42:45], v[148:151], v[180:183], v[42:45]
	v_mfma_f32_16x16x32_bf16 v[30:33], v[136:139], v[188:191], v[30:33]
	v_mfma_f32_16x16x32_bf16 v[26:29], v[148:151], v[188:191], v[26:29]
	v_mfma_f32_16x16x32_bf16 v[14:17], v[136:139], v[202:205], v[14:17]
	v_mfma_f32_16x16x32_bf16 v[10:13], v[148:151], v[202:205], v[10:13]
	v_mfma_f32_16x16x32_bf16 v[62:65], v[144:147], v[176:179], v[62:65]
	v_mfma_f32_16x16x32_bf16 v[58:61], v[152:155], v[176:179], v[58:61]
	v_mfma_f32_16x16x32_bf16 v[46:49], v[144:147], v[184:187], v[46:49]
	v_mfma_f32_16x16x32_bf16 v[42:45], v[152:155], v[184:187], v[42:45]
	v_mfma_f32_16x16x32_bf16 v[30:33], v[144:147], v[192:195], v[30:33]
	v_mfma_f32_16x16x32_bf16 v[26:29], v[152:155], v[192:195], v[26:29]
	v_mfma_f32_16x16x32_bf16 v[14:17], v[144:147], v[206:209], v[14:17]
	v_mfma_f32_16x16x32_bf16 v[10:13], v[152:155], v[206:209], v[10:13]
	v_mfma_f32_16x16x32_bf16 v[54:57], v[156:159], v[172:175], v[54:57]
	v_mfma_f32_16x16x32_bf16 v[50:53], v[164:167], v[172:175], v[50:53]
	v_mfma_f32_16x16x32_bf16 v[38:41], v[156:159], v[180:183], v[38:41]
	v_mfma_f32_16x16x32_bf16 v[34:37], v[164:167], v[180:183], v[34:37]
	v_mfma_f32_16x16x32_bf16 v[22:25], v[156:159], v[188:191], v[22:25]
	v_mfma_f32_16x16x32_bf16 v[18:21], v[164:167], v[188:191], v[18:21]
	v_mfma_f32_16x16x32_bf16 v[6:9], v[156:159], v[202:205], v[6:9]
	v_mfma_f32_16x16x32_bf16 v[2:5], v[164:167], v[202:205], v[2:5]
	v_mfma_f32_16x16x32_bf16 v[54:57], v[160:163], v[176:179], v[54:57]
	v_mfma_f32_16x16x32_bf16 v[50:53], v[168:171], v[176:179], v[50:53]
	v_mfma_f32_16x16x32_bf16 v[38:41], v[160:163], v[184:187], v[38:41]
	v_mfma_f32_16x16x32_bf16 v[34:37], v[168:171], v[184:187], v[34:37]
	v_mfma_f32_16x16x32_bf16 v[22:25], v[160:163], v[192:195], v[22:25]
	v_mfma_f32_16x16x32_bf16 v[18:21], v[168:171], v[192:195], v[18:21]
	v_mfma_f32_16x16x32_bf16 v[6:9], v[160:163], v[206:209], v[6:9]
	v_mfma_f32_16x16x32_bf16 v[2:5], v[168:171], v[206:209], v[2:5]
	s_setprio 0
	s_barrier
	s_add_i32 s29, s29, 2
	s_add_u32 vcc_lo, vcc_lo, 0x100
	s_addc_u32 vcc_hi, vcc_hi, 0
	s_add_u32 s73, s73, 0x100
	s_addc_u32 s28, s28, 0
	s_cmp_gt_u32 s29, 29
	s_cbranch_scc0 .LBB0_1062
	s_and_b64 vcc, exec, s[6:7]
	s_cbranch_vccz .LBB0_1065
	s_barrier

; #define PG8_STAGE(bufoff, gbase, voff) do { _Pragma("unroll") for (int _i = 0; _i < 2; ++_i) \
;         __builtin_amdgcn_global_load_lds((const unsigned*)((const char*)(gbase) + (voff)[_i]), (LAS unsigned*)(lds + (bufoff) + ldsw + _i * 8192), 16, 0, 0); } while (0)
; #define PG8_WAIT_V(n) asm volatile("s_waitcnt vmcnt(" #n ")" ::: "memory")
; #define PG8_WAIT_L(n) asm volatile("s_waitcnt lgkmcnt(" #n ")" ::: "memory")
; #define PG8_BAR __builtin_amdgcn_s_barrier()
; #define PG8_SCHED __builtin_amdgcn_sched_barrier(0)
; template <bool F8 = false, class Epi, class Sched>
; __device__ __forceinline__ void gemm_phase(LAS unsigned char* lds, const int lda, const int ldb, const int K, const Sched& S, const Epi& E) {
;     ...
;         for (int t = 0; t < nt; t += 2) {
;             const bool last = (t == nt - 2);
;             const char* a1 = cA + (size_t)(t + 1) * kstep;
;             const char* a2 = last ? nA : cA + (size_t)(t + 2) * kstep; const char* b2 = last ? nB : cB + (size_t)(t + 2) * kstep;
;             const char* a3 = a2 + kstep; const char* b3 = b2 + kstep;
;             PG8_LDB(B0, 0, 0); PG8_LDB(B1, 0, 1); PG8_SCHED; PG8_LDA(At, 0, 0); PG8_STAGE(PG8_SA(1, 1), a1 + hstepA, voffA);
;             PG8_WAIT_V(8); PG8_WAIT_L(0); PG8_BAR; PG8_MMA(0, 0, At, B0); PG8_MMA(0, 1, At, B1); PG8_BAR; PG8_SCHED;
;             PG8_LDA(At, 0, 1); PG8_STAGE(PG8_SB(0, 0), b2, voffB); PG8_STAGE(PG8_SB(0, 1), b2 + hstepB, voffB); PG8_STAGE(PG8_SA(0, 0), a2, voffA);
;             PG8_WAIT_V(8); PG8_WAIT_L(0); PG8_BAR; PG8_MMA(1, 0, At, B0); PG8_MMA(1, 1, At, B1); PG8_BAR; PG8_SCHED;
.LBB0_1149:
	s_add_u32 s18, s16, 0x100
	s_addc_u32 s19, s17, 0
	s_add_i32 s30, 0, 0x10000
	s_cmpk_eq_i32 s94, 0x54
	s_cselect_b32 s53, s13, s19
	s_cselect_b32 s52, s12, s18
	v_add_u32_e32 v140, s30, v143
	s_cselect_b32 s21, s15, s29
	s_cselect_b32 s20, s14, s28
	s_add_i32 s31, 0, 0x14000
	ds_read_b128 v[146:149], v140
	ds_read_b128 v[150:153], v140 offset:1024
	ds_read_b128 v[154:157], v140 offset:2048
	ds_read_b128 v[158:161], v140 offset:3072
	v_add_u32_e32 v140, s31, v143
	ds_read_b128 v[162:165], v140
	ds_read_b128 v[166:169], v140 offset:1024
	ds_read_b128 v[170:173], v140 offset:2048
	ds_read_b128 v[174:177], v140 offset:3072
	v_lshl_add_u64 v[140:141], s[16:17], 0, v[136:137]
	s_add_i32 m0, s25, 0xc000
	ds_read_b128 v[178:181], v145
	ds_read_b128 v[182:185], v145 offset:1024
	ds_read_b128 v[186:189], v145 offset:2048
	ds_read_b128 v[190:193], v145 offset:3072
	ds_read_b128 v[202:205], v145 offset:4096
	ds_read_b128 v[206:209], v145 offset:5120
	ds_read_b128 v[210:213], v145 offset:6144
	ds_read_b128 v[214:217], v145 offset:7168
	global_load_lds_dwordx4 v[140:141], off
	v_lshl_add_u64 v[140:141], s[16:17], 0, v[138:139]
	s_add_i32 m0, s25, 0xe000
	s_nop 0
	global_load_lds_dwordx4 v[140:141], off
	s_waitcnt vmcnt(8)
	s_waitcnt lgkmcnt(0)
	s_barrier
	s_setprio 1
	v_mfma_f32_16x16x32_bf16 v[126:129], v[146:149], v[178:181], v[126:129]
	v_mfma_f32_16x16x32_bf16 v[122:125], v[154:157], v[178:181], v[122:125]
	v_mfma_f32_16x16x32_bf16 v[118:121], v[146:149], v[186:189], v[118:121]
	v_mfma_f32_16x16x32_bf16 v[110:113], v[154:157], v[186:189], v[110:113]
	v_mfma_f32_16x16x32_bf16 v[102:105], v[146:149], v[202:205], v[102:105]
	v_mfma_f32_16x16x32_bf16 v[94:97], v[154:157], v[202:205], v[94:97]
	v_mfma_f32_16x16x32_bf16 v[86:89], v[146:149], v[210:213], v[86:89]
	v_mfma_f32_16x16x32_bf16 v[78:81], v[154:157], v[210:213], v[78:81]
	v_mfma_f32_16x16x32_bf16 v[126:129], v[150:153], v[182:185], v[126:129]
	v_mfma_f32_16x16x32_bf16 v[122:125], v[158:161], v[182:185], v[122:125]
	v_mfma_f32_16x16x32_bf16 v[118:121], v[150:153], v[190:193], v[118:121]
	v_mfma_f32_16x16x32_bf16 v[110:113], v[158:161], v[190:193], v[110:113]
	v_mfma_f32_16x16x32_bf16 v[102:105], v[150:153], v[206:209], v[102:105]
	v_mfma_f32_16x16x32_bf16 v[94:97], v[158:161], v[206:209], v[94:97]
	v_mfma_f32_16x16x32_bf16 v[86:89], v[150:153], v[214:217], v[86:89]
	v_mfma_f32_16x16x32_bf16 v[78:81], v[158:161], v[214:217], v[78:81]
	v_mfma_f32_16x16x32_bf16 v[114:117], v[162:165], v[178:181], v[114:117]
	v_mfma_f32_16x16x32_bf16 v[106:109], v[170:173], v[178:181], v[106:109]
	v_mfma_f32_16x16x32_bf16 v[98:101], v[162:165], v[186:189], v[98:101]
	v_mfma_f32_16x16x32_bf16 v[90:93], v[170:173], v[186:189], v[90:93]
	v_mfma_f32_16x16x32_bf16 v[82:85], v[162:165], v[202:205], v[82:85]
	v_mfma_f32_16x16x32_bf16 v[74:77], v[170:173], v[202:205], v[74:77]
	v_mfma_f32_16x16x32_bf16 v[70:73], v[162:165], v[210:213], v[70:73]
	v_mfma_f32_16x16x32_bf16 v[66:69], v[170:173], v[210:213], v[66:69]
	v_mfma_f32_16x16x32_bf16 v[114:117], v[166:169], v[182:185], v[114:117]
	v_mfma_f32_16x16x32_bf16 v[106:109], v[174:177], v[182:185], v[106:109]
	v_mfma_f32_16x16x32_bf16 v[98:101], v[166:169], v[190:193], v[98:101]
	v_mfma_f32_16x16x32_bf16 v[90:93], v[174:177], v[190:193], v[90:93]
	v_mfma_f32_16x16x32_bf16 v[82:85], v[166:169], v[206:209], v[82:85]
	v_mfma_f32_16x16x32_bf16 v[74:77], v[174:177], v[206:209], v[74:77]
	v_mfma_f32_16x16x32_bf16 v[70:73], v[166:169], v[214:217], v[70:73]
	v_mfma_f32_16x16x32_bf16 v[66:69], v[174:177], v[214:217], v[66:69]
	s_setprio 0
	s_barrier
	s_add_i32 s16, s30, s24
	v_lshl_add_u64 v[140:141], s[20:21], 0, v[0:1]
	s_mov_b32 m0, s16
	ds_read_b128 v[178:181], v145 offset:16384
	ds_read_b128 v[182:185], v145 offset:17408
	ds_read_b128 v[186:189], v145 offset:18432
	ds_read_b128 v[190:193], v145 offset:19456
	ds_read_b128 v[202:205], v145 offset:20480
	ds_read_b128 v[206:209], v145 offset:21504
	ds_read_b128 v[210:213], v145 offset:22528
	ds_read_b128 v[214:217], v145 offset:23552
	global_load_lds_dwordx4 v[140:141], off
	s_add_i32 m0, s16, 0x2000
	s_add_u32 s16, s20, 0x160000
	v_lshl_add_u64 v[194:195], s[20:21], 0, v[130:131]
	s_addc_u32 s17, s21, 0
	s_add_i32 s30, s31, s24
	global_load_lds_dwordx4 v[194:195], off
	v_lshl_add_u64 v[218:219], s[16:17], 0, v[0:1]
	s_mov_b32 m0, s30
	v_lshl_add_u64 v[220:221], s[52:53], 0, v[132:133]
	global_load_lds_dwordx4 v[218:219], off
	v_lshl_add_u64 v[218:219], s[16:17], 0, v[130:131]
	s_add_i32 m0, s30, 0x2000
	s_nop 0
	global_load_lds_dwordx4 v[218:219], off
	v_lshl_add_u64 v[218:219], s[52:53], 0, v[134:135]
	s_mov_b32 m0, s25
	s_nop 0
	global_load_lds_dwordx4 v[218:219], off
	s_mov_b32 m0, s26
	s_nop 0
	global_load_lds_dwordx4 v[220:221], off
	s_waitcnt vmcnt(8)
	s_waitcnt lgkmcnt(0)
	s_barrier
; #define PG8_STAGE(bufoff, gbase, voff) do { _Pragma("unroll") for (int _i = 0; _i < 2; ++_i) \
;         __builtin_amdgcn_global_load_lds((const unsigned*)((const char*)(gbase) + (voff)[_i]), (LAS unsigned*)(lds + (bufoff) + ldsw + _i * 8192), 16, 0, 0); } while (0)
; #define PG8_WAIT_V(n) asm volatile("s_waitcnt vmcnt(" #n ")" ::: "memory")
; #define PG8_WAIT_L(n) asm volatile("s_waitcnt lgkmcnt(" #n ")" ::: "memory")
; #define PG8_BAR __builtin_amdgcn_s_barrier()
; #define PG8_SCHED __builtin_amdgcn_sched_barrier(0)
; template <bool F8 = false, class Epi, class Sched>
; __device__ __forceinline__ void gemm_phase(LAS unsigned char* lds, const int lda, const int ldb, const int K, const Sched& S, const Epi& E) {
;     ...
;             PG8_WAIT_V(8); PG8_WAIT_L(0); PG8_BAR; PG8_MMA(1, 0, At, B0); PG8_MMA(1, 1, At, B1); PG8_BAR; PG8_SCHED;
;             PG8_LDB(B0, 1, 0); PG8_LDB(B1, 1, 1); PG8_SCHED; PG8_LDA(At, 1, 0); PG8_STAGE(PG8_SA(0, 1), a2 + hstepA, voffA);
;             PG8_WAIT_V(8); PG8_WAIT_L(0); PG8_BAR; PG8_MMA(0, 0, At, B0); PG8_MMA(0, 1, At, B1); PG8_BAR; PG8_SCHED;
;             PG8_LDA(At, 1, 1); PG8_STAGE(PG8_SB(1, 0), b3, voffB); PG8_STAGE(PG8_SB(1, 1), b3 + hstepB, voffB); PG8_STAGE(PG8_SA(1, 0), a3, voffA);
	s_setprio 1
	v_mfma_f32_16x16x32_bf16 v[62:65], v[146:149], v[178:181], v[62:65]
	v_mfma_f32_16x16x32_bf16 v[58:61], v[154:157], v[178:181], v[58:61]
	v_mfma_f32_16x16x32_bf16 v[54:57], v[146:149], v[186:189], v[54:57]
	v_mfma_f32_16x16x32_bf16 v[46:49], v[154:157], v[186:189], v[46:49]
	v_mfma_f32_16x16x32_bf16 v[38:41], v[146:149], v[202:205], v[38:41]
	v_mfma_f32_16x16x32_bf16 v[30:33], v[154:157], v[202:205], v[30:33]
	v_mfma_f32_16x16x32_bf16 v[22:25], v[146:149], v[210:213], v[22:25]
	v_mfma_f32_16x16x32_bf16 v[14:17], v[154:157], v[210:213], v[14:17]
	v_mfma_f32_16x16x32_bf16 v[62:65], v[150:153], v[182:185], v[62:65]
	v_mfma_f32_16x16x32_bf16 v[58:61], v[158:161], v[182:185], v[58:61]
	v_mfma_f32_16x16x32_bf16 v[54:57], v[150:153], v[190:193], v[54:57]
	v_mfma_f32_16x16x32_bf16 v[46:49], v[158:161], v[190:193], v[46:49]
	v_mfma_f32_16x16x32_bf16 v[38:41], v[150:153], v[206:209], v[38:41]
	v_mfma_f32_16x16x32_bf16 v[30:33], v[158:161], v[206:209], v[30:33]
	v_mfma_f32_16x16x32_bf16 v[22:25], v[150:153], v[214:217], v[22:25]
	v_mfma_f32_16x16x32_bf16 v[14:17], v[158:161], v[214:217], v[14:17]
	v_mfma_f32_16x16x32_bf16 v[50:53], v[162:165], v[178:181], v[50:53]
	v_mfma_f32_16x16x32_bf16 v[42:45], v[170:173], v[178:181], v[42:45]
	v_mfma_f32_16x16x32_bf16 v[34:37], v[162:165], v[186:189], v[34:37]
	v_mfma_f32_16x16x32_bf16 v[26:29], v[170:173], v[186:189], v[26:29]
	v_mfma_f32_16x16x32_bf16 v[18:21], v[162:165], v[202:205], v[18:21]
	v_mfma_f32_16x16x32_bf16 v[10:13], v[170:173], v[202:205], v[10:13]
	v_mfma_f32_16x16x32_bf16 v[6:9], v[162:165], v[210:213], v[6:9]
	v_mfma_f32_16x16x32_bf16 v[2:5], v[170:173], v[210:213], v[2:5]
	v_mfma_f32_16x16x32_bf16 v[50:53], v[166:169], v[182:185], v[50:53]
	v_mfma_f32_16x16x32_bf16 v[42:45], v[174:177], v[182:185], v[42:45]
	v_mfma_f32_16x16x32_bf16 v[34:37], v[166:169], v[190:193], v[34:37]
	v_mfma_f32_16x16x32_bf16 v[26:29], v[174:177], v[190:193], v[26:29]
	v_mfma_f32_16x16x32_bf16 v[18:21], v[166:169], v[206:209], v[18:21]
	v_mfma_f32_16x16x32_bf16 v[10:13], v[174:177], v[206:209], v[10:13]
	v_mfma_f32_16x16x32_bf16 v[6:9], v[166:169], v[214:217], v[6:9]
	v_mfma_f32_16x16x32_bf16 v[2:5], v[174:177], v[214:217], v[2:5]
	s_setprio 0
	s_barrier
	s_add_i32 s30, 0, 0x18000
	s_add_i32 s31, 0, 0x1c000
	v_add_u32_e32 v158, s30, v143
	v_add_u32_e32 v174, s31, v143
	ds_read_b128 v[146:149], v158
	ds_read_b128 v[150:153], v158 offset:1024
	ds_read_b128 v[154:157], v158 offset:2048
	ds_read_b128 v[158:161], v158 offset:3072
	ds_read_b128 v[162:165], v174
	ds_read_b128 v[166:169], v174 offset:1024
	ds_read_b128 v[170:173], v174 offset:2048
	ds_read_b128 v[174:177], v174 offset:3072
	s_add_u32 s16, s52, 0x160000
	s_addc_u32 s17, s53, 0
	s_mov_b32 m0, s27
	v_lshl_add_u64 v[222:223], s[16:17], 0, v[134:135]
	ds_read_b128 v[178:181], v145 offset:32768
	ds_read_b128 v[182:185], v145 offset:33792
	ds_read_b128 v[186:189], v145 offset:34816
	ds_read_b128 v[190:193], v145 offset:35840
	ds_read_b128 v[202:205], v145 offset:36864
	ds_read_b128 v[206:209], v145 offset:37888
	ds_read_b128 v[210:213], v145 offset:38912
	ds_read_b128 v[214:217], v145 offset:39936
	global_load_lds_dwordx4 v[222:223], off
	v_lshl_add_u64 v[222:223], s[16:17], 0, v[132:133]
	s_mov_b32 m0, s44
	s_nop 0
	global_load_lds_dwordx4 v[222:223], off
	s_waitcnt vmcnt(8)
	s_waitcnt lgkmcnt(0)
	s_barrier
	s_setprio 1
	v_mfma_f32_16x16x32_bf16 v[126:129], v[146:149], v[178:181], v[126:129]
	v_mfma_f32_16x16x32_bf16 v[122:125], v[154:157], v[178:181], v[122:125]
	v_mfma_f32_16x16x32_bf16 v[118:121], v[146:149], v[186:189], v[118:121]
	v_mfma_f32_16x16x32_bf16 v[110:113], v[154:157], v[186:189], v[110:113]
	v_mfma_f32_16x16x32_bf16 v[102:105], v[146:149], v[202:205], v[102:105]
	v_mfma_f32_16x16x32_bf16 v[94:97], v[154:157], v[202:205], v[94:97]
	v_mfma_f32_16x16x32_bf16 v[86:89], v[146:149], v[210:213], v[86:89]
	v_mfma_f32_16x16x32_bf16 v[78:81], v[154:157], v[210:213], v[78:81]
	v_mfma_f32_16x16x32_bf16 v[126:129], v[150:153], v[182:185], v[126:129]
	v_mfma_f32_16x16x32_bf16 v[122:125], v[158:161], v[182:185], v[122:125]
	v_mfma_f32_16x16x32_bf16 v[118:121], v[150:153], v[190:193], v[118:121]
	v_mfma_f32_16x16x32_bf16 v[110:113], v[158:161], v[190:193], v[110:113]
	v_mfma_f32_16x16x32_bf16 v[102:105], v[150:153], v[206:209], v[102:105]
	v_mfma_f32_16x16x32_bf16 v[94:97], v[158:161], v[206:209], v[94:97]
	v_mfma_f32_16x16x32_bf16 v[86:89], v[150:153], v[214:217], v[86:89]
	v_mfma_f32_16x16x32_bf16 v[78:81], v[158:161], v[214:217], v[78:81]
	v_mfma_f32_16x16x32_bf16 v[114:117], v[162:165], v[178:181], v[114:117]
	v_mfma_f32_16x16x32_bf16 v[106:109], v[170:173], v[178:181], v[106:109]
	v_mfma_f32_16x16x32_bf16 v[98:101], v[162:165], v[186:189], v[98:101]
	v_mfma_f32_16x16x32_bf16 v[90:93], v[170:173], v[186:189], v[90:93]
	v_mfma_f32_16x16x32_bf16 v[82:85], v[162:165], v[202:205], v[82:85]
	v_mfma_f32_16x16x32_bf16 v[74:77], v[170:173], v[202:205], v[74:77]
	v_mfma_f32_16x16x32_bf16 v[70:73], v[162:165], v[210:213], v[70:73]
	v_mfma_f32_16x16x32_bf16 v[66:69], v[170:173], v[210:213], v[66:69]
	v_mfma_f32_16x16x32_bf16 v[114:117], v[166:169], v[182:185], v[114:117]
	v_mfma_f32_16x16x32_bf16 v[106:109], v[174:177], v[182:185], v[106:109]
	v_mfma_f32_16x16x32_bf16 v[98:101], v[166:169], v[190:193], v[98:101]
	v_mfma_f32_16x16x32_bf16 v[90:93], v[174:177], v[190:193], v[90:93]
	v_mfma_f32_16x16x32_bf16 v[82:85], v[166:169], v[206:209], v[82:85]
	v_mfma_f32_16x16x32_bf16 v[74:77], v[174:177], v[206:209], v[74:77]
	v_mfma_f32_16x16x32_bf16 v[70:73], v[166:169], v[214:217], v[70:73]
	v_mfma_f32_16x16x32_bf16 v[66:69], v[174:177], v[214:217], v[66:69]
	s_setprio 0
	s_barrier
; #define PG8_STAGE(bufoff, gbase, voff) do { _Pragma("unroll") for (int _i = 0; _i < 2; ++_i) \
;         __builtin_amdgcn_global_load_lds((const unsigned*)((const char*)(gbase) + (voff)[_i]), (LAS unsigned*)(lds + (bufoff) + ldsw + _i * 8192), 16, 0, 0); } while (0)
; #define PG8_WAIT_V(n) asm volatile("s_waitcnt vmcnt(" #n ")" ::: "memory")
; #define PG8_WAIT_L(n) asm volatile("s_waitcnt lgkmcnt(" #n ")" ::: "memory")
; #define PG8_BAR __builtin_amdgcn_s_barrier()
; #define PG8_SCHED __builtin_amdgcn_sched_barrier(0)
; template <bool F8 = false, class Epi, class Sched>
; __device__ __forceinline__ void gemm_phase(LAS unsigned char* lds, const int lda, const int ldb, const int K, const Sched& S, const Epi& E) {
;     ...
;             PG8_LDA(At, 1, 1); PG8_STAGE(PG8_SB(1, 0), b3, voffB); PG8_STAGE(PG8_SB(1, 1), b3 + hstepB, voffB); PG8_STAGE(PG8_SA(1, 0), a3, voffA);
;             PG8_WAIT_V(8); PG8_WAIT_L(0); PG8_BAR; PG8_MMA(1, 0, At, B0); PG8_MMA(1, 1, At, B1); PG8_BAR; PG8_SCHED;
;         }
;         if (wr == 0) PG8_BAR;
	s_add_i32 s16, s30, s24
	v_lshl_add_u64 v[140:141], v[140:141], 0, s[40:41]
	s_mov_b32 m0, s16
	ds_read_b128 v[178:181], v145 offset:49152
	ds_read_b128 v[182:185], v145 offset:50176
	ds_read_b128 v[186:189], v145 offset:51200
	ds_read_b128 v[190:193], v145 offset:52224
	ds_read_b128 v[202:205], v145 offset:53248
	ds_read_b128 v[206:209], v145 offset:54272
	ds_read_b128 v[210:213], v145 offset:55296
	ds_read_b128 v[214:217], v145 offset:56320
	global_load_lds_dwordx4 v[140:141], off
	s_add_i32 m0, s16, 0x2000
	s_add_u32 s16, s20, 0x160080
	v_lshl_add_u64 v[140:141], v[194:195], 0, s[40:41]
	s_addc_u32 s17, s21, 0
	s_add_i32 s20, s31, s24
	global_load_lds_dwordx4 v[140:141], off
	v_lshl_add_u64 v[140:141], s[16:17], 0, v[0:1]
	s_mov_b32 m0, s20
	s_nop 0
	global_load_lds_dwordx4 v[140:141], off
	v_lshl_add_u64 v[140:141], s[16:17], 0, v[130:131]
	s_add_i32 m0, s20, 0x2000
	s_nop 0
	global_load_lds_dwordx4 v[140:141], off
	v_lshl_add_u64 v[140:141], v[218:219], 0, s[40:41]
	s_mov_b32 m0, s56
	s_nop 0
	global_load_lds_dwordx4 v[140:141], off
	v_lshl_add_u64 v[140:141], v[220:221], 0, s[40:41]
	s_mov_b32 m0, s57
	s_nop 0
	global_load_lds_dwordx4 v[140:141], off
	s_waitcnt vmcnt(8)
	s_waitcnt lgkmcnt(0)
	s_barrier
	s_setprio 1
	v_mfma_f32_16x16x32_bf16 v[62:65], v[146:149], v[178:181], v[62:65]
	v_mfma_f32_16x16x32_bf16 v[58:61], v[154:157], v[178:181], v[58:61]
	v_mfma_f32_16x16x32_bf16 v[54:57], v[146:149], v[186:189], v[54:57]
	v_mfma_f32_16x16x32_bf16 v[46:49], v[154:157], v[186:189], v[46:49]
	v_mfma_f32_16x16x32_bf16 v[38:41], v[146:149], v[202:205], v[38:41]
	v_mfma_f32_16x16x32_bf16 v[30:33], v[154:157], v[202:205], v[30:33]
	v_mfma_f32_16x16x32_bf16 v[22:25], v[146:149], v[210:213], v[22:25]
	v_mfma_f32_16x16x32_bf16 v[14:17], v[154:157], v[210:213], v[14:17]
	v_mfma_f32_16x16x32_bf16 v[62:65], v[150:153], v[182:185], v[62:65]
	v_mfma_f32_16x16x32_bf16 v[58:61], v[158:161], v[182:185], v[58:61]
	v_mfma_f32_16x16x32_bf16 v[54:57], v[150:153], v[190:193], v[54:57]
	v_mfma_f32_16x16x32_bf16 v[46:49], v[158:161], v[190:193], v[46:49]
	v_mfma_f32_16x16x32_bf16 v[38:41], v[150:153], v[206:209], v[38:41]
	v_mfma_f32_16x16x32_bf16 v[30:33], v[158:161], v[206:209], v[30:33]
	v_mfma_f32_16x16x32_bf16 v[22:25], v[150:153], v[214:217], v[22:25]
	v_mfma_f32_16x16x32_bf16 v[14:17], v[158:161], v[214:217], v[14:17]
	v_mfma_f32_16x16x32_bf16 v[50:53], v[162:165], v[178:181], v[50:53]
	v_mfma_f32_16x16x32_bf16 v[42:45], v[170:173], v[178:181], v[42:45]
	v_mfma_f32_16x16x32_bf16 v[34:37], v[162:165], v[186:189], v[34:37]
	v_mfma_f32_16x16x32_bf16 v[26:29], v[170:173], v[186:189], v[26:29]
	v_mfma_f32_16x16x32_bf16 v[18:21], v[162:165], v[202:205], v[18:21]
	v_mfma_f32_16x16x32_bf16 v[10:13], v[170:173], v[202:205], v[10:13]
	v_mfma_f32_16x16x32_bf16 v[6:9], v[162:165], v[210:213], v[6:9]
	v_mfma_f32_16x16x32_bf16 v[2:5], v[170:173], v[210:213], v[2:5]
	v_mfma_f32_16x16x32_bf16 v[50:53], v[166:169], v[182:185], v[50:53]
	v_mfma_f32_16x16x32_bf16 v[42:45], v[174:177], v[182:185], v[42:45]
	v_mfma_f32_16x16x32_bf16 v[34:37], v[166:169], v[190:193], v[34:37]
	v_mfma_f32_16x16x32_bf16 v[26:29], v[174:177], v[190:193], v[26:29]
	v_mfma_f32_16x16x32_bf16 v[18:21], v[166:169], v[206:209], v[18:21]
	v_mfma_f32_16x16x32_bf16 v[10:13], v[174:177], v[206:209], v[10:13]
	v_mfma_f32_16x16x32_bf16 v[6:9], v[166:169], v[214:217], v[6:9]
	v_mfma_f32_16x16x32_bf16 v[2:5], v[174:177], v[214:217], v[2:5]
	s_setprio 0
	s_barrier
	s_add_i32 s94, s94, 2
	s_add_u32 s28, s28, 0x100
	s_addc_u32 s29, s29, 0
	s_cmpk_gt_u32 s94, 0x55
	s_mov_b64 s[16:17], s[18:19]
	s_cbranch_scc0 .LBB0_1149
	s_and_b64 vcc, exec, s[6:7]
	s_cbranch_vccz .LBB0_1152
	s_barrier

; #define PG8_STAGE(bufoff, gbase, voff) do { _Pragma("unroll") for (int _i = 0; _i < 2; ++_i) \
;         __builtin_amdgcn_global_load_lds((const unsigned*)((const char*)(gbase) + (voff)[_i]), (LAS unsigned*)(lds + (bufoff) + ldsw + _i * 8192), 16, 0, 0); } while (0)
; #define PG8_WAIT_V(n) asm volatile("s_waitcnt vmcnt(" #n ")" ::: "memory")
; #define PG8_WAIT_L(n) asm volatile("s_waitcnt lgkmcnt(" #n ")" ::: "memory")
; #define PG8_BAR __builtin_amdgcn_s_barrier()
; #define PG8_SCHED __builtin_amdgcn_sched_barrier(0)
; template <bool F8 = false, class Epi, class Sched>
; __device__ __forceinline__ void gemm_phase(LAS unsigned char* lds, const int lda, const int ldb, const int K, const Sched& S, const Epi& E) {
;     ...
;         for (int t = 0; t < nt; t += 2) {
;             const bool last = (t == nt - 2);
;             const char* a1 = cA + (size_t)(t + 1) * kstep;
;             const char* a2 = last ? nA : cA + (size_t)(t + 2) * kstep; const char* b2 = last ? nB : cB + (size_t)(t + 2) * kstep;
;             const char* a3 = a2 + kstep; const char* b3 = b2 + kstep;
;             PG8_LDB(B0, 0, 0); PG8_LDB(B1, 0, 1); PG8_SCHED; PG8_LDA(At, 0, 0); PG8_STAGE(PG8_SA(1, 1), a1 + hstepA, voffA);
;             PG8_WAIT_V(8); PG8_WAIT_L(0); PG8_BAR; PG8_MMA(0, 0, At, B0); PG8_MMA(0, 1, At, B1); PG8_BAR; PG8_SCHED;
;             PG8_LDA(At, 0, 1); PG8_STAGE(PG8_SB(0, 0), b2, voffB); PG8_STAGE(PG8_SB(0, 1), b2 + hstepB, voffB); PG8_STAGE(PG8_SA(0, 0), a2, voffA);
;             PG8_WAIT_V(8); PG8_WAIT_L(0); PG8_BAR; PG8_MMA(1, 0, At, B0); PG8_MMA(1, 1, At, B1); PG8_BAR; PG8_SCHED;
.LBB0_1177:
	s_add_u32 s18, s16, 0x100
	s_addc_u32 s19, s17, 0
	s_add_i32 s30, 0, 0x10000
	s_cmp_eq_u32 s96, 18
	s_cselect_b32 s53, s13, s19
	s_cselect_b32 s52, s12, s18
	v_add_u32_e32 v0, s30, v140
	s_cselect_b32 s21, s15, s29
	s_cselect_b32 s20, s14, s28
	s_add_i32 s31, 0, 0x14000
	ds_read_b128 v[144:147], v0
	ds_read_b128 v[148:151], v0 offset:1024
	ds_read_b128 v[152:155], v0 offset:2048
	ds_read_b128 v[156:159], v0 offset:3072
	v_add_u32_e32 v0, s31, v140
	ds_read_b128 v[160:163], v0
	ds_read_b128 v[164:167], v0 offset:1024
	ds_read_b128 v[168:171], v0 offset:2048
	ds_read_b128 v[172:175], v0 offset:3072
	v_lshl_add_u64 v[138:139], s[16:17], 0, v[134:135]
	s_add_i32 m0, s25, 0xc000
	ds_read_b128 v[176:179], v142
	ds_read_b128 v[180:183], v142 offset:1024
	ds_read_b128 v[184:187], v142 offset:2048
	ds_read_b128 v[188:191], v142 offset:3072
	ds_read_b128 v[192:195], v142 offset:4096
	ds_read_b128 v[202:205], v142 offset:5120
	ds_read_b128 v[206:209], v142 offset:6144
	ds_read_b128 v[210:213], v142 offset:7168
	global_load_lds_dwordx4 v[138:139], off
	v_lshl_add_u64 v[138:139], s[16:17], 0, v[136:137]
	s_add_i32 m0, s25, 0xe000
	s_nop 0
	global_load_lds_dwordx4 v[138:139], off
	s_waitcnt vmcnt(8)
	s_waitcnt lgkmcnt(0)
	s_barrier
	s_setprio 1
	v_mfma_f32_16x16x32_bf16 v[126:129], v[144:147], v[176:179], v[126:129]
	v_mfma_f32_16x16x32_bf16 v[122:125], v[152:155], v[176:179], v[122:125]
	v_mfma_f32_16x16x32_bf16 v[118:121], v[144:147], v[184:187], v[118:121]
	v_mfma_f32_16x16x32_bf16 v[110:113], v[152:155], v[184:187], v[110:113]
	v_mfma_f32_16x16x32_bf16 v[102:105], v[144:147], v[192:195], v[102:105]
	v_mfma_f32_16x16x32_bf16 v[94:97], v[152:155], v[192:195], v[94:97]
	v_mfma_f32_16x16x32_bf16 v[86:89], v[144:147], v[206:209], v[86:89]
	v_mfma_f32_16x16x32_bf16 v[78:81], v[152:155], v[206:209], v[78:81]
	v_mfma_f32_16x16x32_bf16 v[126:129], v[148:151], v[180:183], v[126:129]
	v_mfma_f32_16x16x32_bf16 v[122:125], v[156:159], v[180:183], v[122:125]
	v_mfma_f32_16x16x32_bf16 v[118:121], v[148:151], v[188:191], v[118:121]
	v_mfma_f32_16x16x32_bf16 v[110:113], v[156:159], v[188:191], v[110:113]
	v_mfma_f32_16x16x32_bf16 v[102:105], v[148:151], v[202:205], v[102:105]
	v_mfma_f32_16x16x32_bf16 v[94:97], v[156:159], v[202:205], v[94:97]
	v_mfma_f32_16x16x32_bf16 v[86:89], v[148:151], v[210:213], v[86:89]
	v_mfma_f32_16x16x32_bf16 v[78:81], v[156:159], v[210:213], v[78:81]
	v_mfma_f32_16x16x32_bf16 v[114:117], v[160:163], v[176:179], v[114:117]
	v_mfma_f32_16x16x32_bf16 v[106:109], v[168:171], v[176:179], v[106:109]
	v_mfma_f32_16x16x32_bf16 v[98:101], v[160:163], v[184:187], v[98:101]
	v_mfma_f32_16x16x32_bf16 v[90:93], v[168:171], v[184:187], v[90:93]
	v_mfma_f32_16x16x32_bf16 v[82:85], v[160:163], v[192:195], v[82:85]
	v_mfma_f32_16x16x32_bf16 v[74:77], v[168:171], v[192:195], v[74:77]
	v_mfma_f32_16x16x32_bf16 v[70:73], v[160:163], v[206:209], v[70:73]
	v_mfma_f32_16x16x32_bf16 v[66:69], v[168:171], v[206:209], v[66:69]
	v_mfma_f32_16x16x32_bf16 v[114:117], v[164:167], v[180:183], v[114:117]
	v_mfma_f32_16x16x32_bf16 v[106:109], v[172:175], v[180:183], v[106:109]
	v_mfma_f32_16x16x32_bf16 v[98:101], v[164:167], v[188:191], v[98:101]
	v_mfma_f32_16x16x32_bf16 v[90:93], v[172:175], v[188:191], v[90:93]
	v_mfma_f32_16x16x32_bf16 v[82:85], v[164:167], v[202:205], v[82:85]
	v_mfma_f32_16x16x32_bf16 v[74:77], v[172:175], v[202:205], v[74:77]
	v_mfma_f32_16x16x32_bf16 v[70:73], v[164:167], v[210:213], v[70:73]
	v_mfma_f32_16x16x32_bf16 v[66:69], v[172:175], v[210:213], v[66:69]
	s_setprio 0
	s_barrier
	s_add_i32 s16, s30, s24
	v_lshl_add_u64 v[138:139], s[20:21], 0, v[132:133]
	s_mov_b32 m0, s16
	ds_read_b128 v[176:179], v142 offset:16384
	ds_read_b128 v[180:183], v142 offset:17408
	ds_read_b128 v[184:187], v142 offset:18432
	ds_read_b128 v[188:191], v142 offset:19456
	ds_read_b128 v[192:195], v142 offset:20480
	ds_read_b128 v[202:205], v142 offset:21504
	ds_read_b128 v[206:209], v142 offset:22528
	ds_read_b128 v[210:213], v142 offset:23552
	global_load_lds_dwordx4 v[138:139], off
	s_add_i32 m0, s16, 0x2000
	s_add_u32 s16, s20, 0x160000
	v_lshl_add_u64 v[214:215], s[20:21], 0, v[130:131]
	s_addc_u32 s17, s21, 0
	s_add_i32 s30, s31, s24
	global_load_lds_dwordx4 v[214:215], off
	v_lshl_add_u64 v[216:217], s[16:17], 0, v[132:133]
	s_mov_b32 m0, s30
	v_lshl_add_u64 v[218:219], s[52:53], 0, v[130:131]
	global_load_lds_dwordx4 v[216:217], off
	v_lshl_add_u64 v[216:217], s[16:17], 0, v[130:131]
	s_add_i32 m0, s30, 0x2000
	s_nop 0
	global_load_lds_dwordx4 v[216:217], off
	v_lshl_add_u64 v[216:217], s[52:53], 0, v[132:133]
	s_mov_b32 m0, s25
	s_nop 0
	global_load_lds_dwordx4 v[216:217], off
	s_mov_b32 m0, s26
	s_nop 0
	global_load_lds_dwordx4 v[218:219], off
	s_waitcnt vmcnt(8)
	s_waitcnt lgkmcnt(0)
	s_barrier
; #define PG8_STAGE(bufoff, gbase, voff) do { _Pragma("unroll") for (int _i = 0; _i < 2; ++_i) \
;         __builtin_amdgcn_global_load_lds((const unsigned*)((const char*)(gbase) + (voff)[_i]), (LAS unsigned*)(lds + (bufoff) + ldsw + _i * 8192), 16, 0, 0); } while (0)
; #define PG8_WAIT_V(n) asm volatile("s_waitcnt vmcnt(" #n ")" ::: "memory")
; #define PG8_WAIT_L(n) asm volatile("s_waitcnt lgkmcnt(" #n ")" ::: "memory")
; #define PG8_BAR __builtin_amdgcn_s_barrier()
; #define PG8_SCHED __builtin_amdgcn_sched_barrier(0)
; template <bool F8 = false, class Epi, class Sched>
; __device__ __forceinline__ void gemm_phase(LAS unsigned char* lds, const int lda, const int ldb, const int K, const Sched& S, const Epi& E) {
;     ...
;             PG8_WAIT_V(8); PG8_WAIT_L(0); PG8_BAR; PG8_MMA(1, 0, At, B0); PG8_MMA(1, 1, At, B1); PG8_BAR; PG8_SCHED;
;             PG8_LDB(B0, 1, 0); PG8_LDB(B1, 1, 1); PG8_SCHED; PG8_LDA(At, 1, 0); PG8_STAGE(PG8_SA(0, 1), a2 + hstepA, voffA);
;             PG8_WAIT_V(8); PG8_WAIT_L(0); PG8_BAR; PG8_MMA(0, 0, At, B0); PG8_MMA(0, 1, At, B1); PG8_BAR; PG8_SCHED;
	s_setprio 1
	v_mfma_f32_16x16x32_bf16 v[62:65], v[144:147], v[176:179], v[62:65]
	v_mfma_f32_16x16x32_bf16 v[58:61], v[152:155], v[176:179], v[58:61]
	v_mfma_f32_16x16x32_bf16 v[54:57], v[144:147], v[184:187], v[54:57]
	v_mfma_f32_16x16x32_bf16 v[42:45], v[152:155], v[184:187], v[42:45]
	v_mfma_f32_16x16x32_bf16 v[38:41], v[144:147], v[192:195], v[38:41]
	v_mfma_f32_16x16x32_bf16 v[26:29], v[152:155], v[192:195], v[26:29]
	v_mfma_f32_16x16x32_bf16 v[22:25], v[144:147], v[206:209], v[22:25]
	v_mfma_f32_16x16x32_bf16 v[10:13], v[152:155], v[206:209], v[10:13]
	v_mfma_f32_16x16x32_bf16 v[62:65], v[148:151], v[180:183], v[62:65]
	v_mfma_f32_16x16x32_bf16 v[58:61], v[156:159], v[180:183], v[58:61]
	v_mfma_f32_16x16x32_bf16 v[54:57], v[148:151], v[188:191], v[54:57]
	v_mfma_f32_16x16x32_bf16 v[42:45], v[156:159], v[188:191], v[42:45]
	v_mfma_f32_16x16x32_bf16 v[38:41], v[148:151], v[202:205], v[38:41]
	v_mfma_f32_16x16x32_bf16 v[26:29], v[156:159], v[202:205], v[26:29]
	v_mfma_f32_16x16x32_bf16 v[22:25], v[148:151], v[210:213], v[22:25]
	v_mfma_f32_16x16x32_bf16 v[10:13], v[156:159], v[210:213], v[10:13]
	v_mfma_f32_16x16x32_bf16 v[50:53], v[160:163], v[176:179], v[50:53]
	v_mfma_f32_16x16x32_bf16 v[46:49], v[168:171], v[176:179], v[46:49]
	v_mfma_f32_16x16x32_bf16 v[34:37], v[160:163], v[184:187], v[34:37]
	v_mfma_f32_16x16x32_bf16 v[30:33], v[168:171], v[184:187], v[30:33]
	v_mfma_f32_16x16x32_bf16 v[18:21], v[160:163], v[192:195], v[18:21]
	v_mfma_f32_16x16x32_bf16 v[14:17], v[168:171], v[192:195], v[14:17]
	v_mfma_f32_16x16x32_bf16 v[6:9], v[160:163], v[206:209], v[6:9]
	v_mfma_f32_16x16x32_bf16 v[2:5], v[168:171], v[206:209], v[2:5]
	v_mfma_f32_16x16x32_bf16 v[50:53], v[164:167], v[180:183], v[50:53]
	v_mfma_f32_16x16x32_bf16 v[46:49], v[172:175], v[180:183], v[46:49]
	v_mfma_f32_16x16x32_bf16 v[34:37], v[164:167], v[188:191], v[34:37]
	v_mfma_f32_16x16x32_bf16 v[30:33], v[172:175], v[188:191], v[30:33]
	v_mfma_f32_16x16x32_bf16 v[18:21], v[164:167], v[202:205], v[18:21]
	v_mfma_f32_16x16x32_bf16 v[14:17], v[172:175], v[202:205], v[14:17]
	v_mfma_f32_16x16x32_bf16 v[6:9], v[164:167], v[210:213], v[6:9]
	v_mfma_f32_16x16x32_bf16 v[2:5], v[172:175], v[210:213], v[2:5]
	s_setprio 0
	s_barrier
	s_add_i32 s30, 0, 0x18000
	v_add_u32_e32 v0, s30, v140
	s_add_i32 s31, 0, 0x1c000
	ds_read_b128 v[144:147], v0
	ds_read_b128 v[148:151], v0 offset:1024
	ds_read_b128 v[152:155], v0 offset:2048
	ds_read_b128 v[156:159], v0 offset:3072
	v_add_u32_e32 v0, s31, v140
	ds_read_b128 v[160:163], v0
	ds_read_b128 v[164:167], v0 offset:1024
	ds_read_b128 v[168:171], v0 offset:2048
	ds_read_b128 v[172:175], v0 offset:3072
	s_add_u32 s16, s52, 0x160000
	s_addc_u32 s17, s53, 0
	s_mov_b32 m0, s27
	v_lshl_add_u64 v[220:221], s[16:17], 0, v[132:133]
	ds_read_b128 v[176:179], v142 offset:32768
	ds_read_b128 v[180:183], v142 offset:33792
	ds_read_b128 v[184:187], v142 offset:34816
	ds_read_b128 v[188:191], v142 offset:35840
	ds_read_b128 v[192:195], v142 offset:36864
	ds_read_b128 v[202:205], v142 offset:37888
	ds_read_b128 v[206:209], v142 offset:38912
	ds_read_b128 v[210:213], v142 offset:39936
	global_load_lds_dwordx4 v[220:221], off
	v_lshl_add_u64 v[220:221], s[16:17], 0, v[130:131]
	s_mov_b32 m0, s44
	s_nop 0
	global_load_lds_dwordx4 v[220:221], off
	s_waitcnt vmcnt(8)
	s_waitcnt lgkmcnt(0)
	s_barrier
	s_setprio 1
	v_mfma_f32_16x16x32_bf16 v[126:129], v[144:147], v[176:179], v[126:129]
	v_mfma_f32_16x16x32_bf16 v[122:125], v[152:155], v[176:179], v[122:125]
	v_mfma_f32_16x16x32_bf16 v[118:121], v[144:147], v[184:187], v[118:121]
	v_mfma_f32_16x16x32_bf16 v[110:113], v[152:155], v[184:187], v[110:113]
	v_mfma_f32_16x16x32_bf16 v[102:105], v[144:147], v[192:195], v[102:105]
	v_mfma_f32_16x16x32_bf16 v[94:97], v[152:155], v[192:195], v[94:97]
	v_mfma_f32_16x16x32_bf16 v[86:89], v[144:147], v[206:209], v[86:89]
	v_mfma_f32_16x16x32_bf16 v[78:81], v[152:155], v[206:209], v[78:81]
	v_mfma_f32_16x16x32_bf16 v[126:129], v[148:151], v[180:183], v[126:129]
	v_mfma_f32_16x16x32_bf16 v[122:125], v[156:159], v[180:183], v[122:125]
	v_mfma_f32_16x16x32_bf16 v[118:121], v[148:151], v[188:191], v[118:121]
	v_mfma_f32_16x16x32_bf16 v[110:113], v[156:159], v[188:191], v[110:113]
	v_mfma_f32_16x16x32_bf16 v[102:105], v[148:151], v[202:205], v[102:105]
	v_mfma_f32_16x16x32_bf16 v[94:97], v[156:159], v[202:205], v[94:97]
	v_mfma_f32_16x16x32_bf16 v[86:89], v[148:151], v[210:213], v[86:89]
	v_mfma_f32_16x16x32_bf16 v[78:81], v[156:159], v[210:213], v[78:81]
	v_mfma_f32_16x16x32_bf16 v[114:117], v[160:163], v[176:179], v[114:117]
	v_mfma_f32_16x16x32_bf16 v[106:109], v[168:171], v[176:179], v[106:109]
	v_mfma_f32_16x16x32_bf16 v[98:101], v[160:163], v[184:187], v[98:101]
	v_mfma_f32_16x16x32_bf16 v[90:93], v[168:171], v[184:187], v[90:93]
	v_mfma_f32_16x16x32_bf16 v[82:85], v[160:163], v[192:195], v[82:85]
	v_mfma_f32_16x16x32_bf16 v[74:77], v[168:171], v[192:195], v[74:77]
	v_mfma_f32_16x16x32_bf16 v[70:73], v[160:163], v[206:209], v[70:73]
	v_mfma_f32_16x16x32_bf16 v[66:69], v[168:171], v[206:209], v[66:69]
	v_mfma_f32_16x16x32_bf16 v[114:117], v[164:167], v[180:183], v[114:117]
	v_mfma_f32_16x16x32_bf16 v[106:109], v[172:175], v[180:183], v[106:109]
	v_mfma_f32_16x16x32_bf16 v[98:101], v[164:167], v[188:191], v[98:101]
	v_mfma_f32_16x16x32_bf16 v[90:93], v[172:175], v[188:191], v[90:93]
	v_mfma_f32_16x16x32_bf16 v[82:85], v[164:167], v[202:205], v[82:85]
	v_mfma_f32_16x16x32_bf16 v[74:77], v[172:175], v[202:205], v[74:77]
	v_mfma_f32_16x16x32_bf16 v[70:73], v[164:167], v[210:213], v[70:73]
	v_mfma_f32_16x16x32_bf16 v[66:69], v[172:175], v[210:213], v[66:69]
	s_setprio 0
	s_barrier
; #define PG8_STAGE(bufoff, gbase, voff) do { _Pragma("unroll") for (int _i = 0; _i < 2; ++_i) \
;         __builtin_amdgcn_global_load_lds((const unsigned*)((const char*)(gbase) + (voff)[_i]), (LAS unsigned*)(lds + (bufoff) + ldsw + _i * 8192), 16, 0, 0); } while (0)
; #define PG8_WAIT_V(n) asm volatile("s_waitcnt vmcnt(" #n ")" ::: "memory")
; #define PG8_WAIT_L(n) asm volatile("s_waitcnt lgkmcnt(" #n ")" ::: "memory")
; #define PG8_BAR __builtin_amdgcn_s_barrier()
; #define PG8_SCHED __builtin_amdgcn_sched_barrier(0)
; template <bool F8 = false, class Epi, class Sched>
; __device__ __forceinline__ void gemm_phase(LAS unsigned char* lds, const int lda, const int ldb, const int K, const Sched& S, const Epi& E) {
;     ...
;             PG8_LDA(At, 1, 1); PG8_STAGE(PG8_SB(1, 0), b3, voffB); PG8_STAGE(PG8_SB(1, 1), b3 + hstepB, voffB); PG8_STAGE(PG8_SA(1, 0), a3, voffA);
;             PG8_WAIT_V(8); PG8_WAIT_L(0); PG8_BAR; PG8_MMA(1, 0, At, B0); PG8_MMA(1, 1, At, B1); PG8_BAR; PG8_SCHED;
;         }
	s_add_i32 s16, s30, s24
	v_lshl_add_u64 v[138:139], v[138:139], 0, s[40:41]
	s_mov_b32 m0, s16
	ds_read_b128 v[176:179], v142 offset:49152
	ds_read_b128 v[180:183], v142 offset:50176
	ds_read_b128 v[184:187], v142 offset:51200
	ds_read_b128 v[188:191], v142 offset:52224
	ds_read_b128 v[192:195], v142 offset:53248
	ds_read_b128 v[202:205], v142 offset:54272
	ds_read_b128 v[206:209], v142 offset:55296
	ds_read_b128 v[210:213], v142 offset:56320
	global_load_lds_dwordx4 v[138:139], off
	s_add_i32 m0, s16, 0x2000
	s_add_u32 s16, s20, 0x160080
	v_lshl_add_u64 v[138:139], v[214:215], 0, s[40:41]
	s_addc_u32 s17, s21, 0
	s_add_i32 s20, s31, s24
	global_load_lds_dwordx4 v[138:139], off
	v_lshl_add_u64 v[138:139], s[16:17], 0, v[132:133]
	s_mov_b32 m0, s20
	s_nop 0
	global_load_lds_dwordx4 v[138:139], off
	v_lshl_add_u64 v[138:139], s[16:17], 0, v[130:131]
	s_add_i32 m0, s20, 0x2000
	s_nop 0
	global_load_lds_dwordx4 v[138:139], off
	v_lshl_add_u64 v[138:139], v[216:217], 0, s[40:41]
	s_mov_b32 m0, s56
	s_nop 0
	global_load_lds_dwordx4 v[138:139], off
	v_lshl_add_u64 v[138:139], v[218:219], 0, s[40:41]
	s_mov_b32 m0, s57
	s_nop 0
	global_load_lds_dwordx4 v[138:139], off
	s_waitcnt vmcnt(8)
	s_waitcnt lgkmcnt(0)
	s_barrier
	s_setprio 1
	v_mfma_f32_16x16x32_bf16 v[62:65], v[144:147], v[176:179], v[62:65]
	v_mfma_f32_16x16x32_bf16 v[58:61], v[152:155], v[176:179], v[58:61]
	v_mfma_f32_16x16x32_bf16 v[54:57], v[144:147], v[184:187], v[54:57]
	v_mfma_f32_16x16x32_bf16 v[42:45], v[152:155], v[184:187], v[42:45]
	v_mfma_f32_16x16x32_bf16 v[38:41], v[144:147], v[192:195], v[38:41]
	v_mfma_f32_16x16x32_bf16 v[26:29], v[152:155], v[192:195], v[26:29]
	v_mfma_f32_16x16x32_bf16 v[22:25], v[144:147], v[206:209], v[22:25]
	v_mfma_f32_16x16x32_bf16 v[10:13], v[152:155], v[206:209], v[10:13]
	v_mfma_f32_16x16x32_bf16 v[62:65], v[148:151], v[180:183], v[62:65]
	v_mfma_f32_16x16x32_bf16 v[58:61], v[156:159], v[180:183], v[58:61]
	v_mfma_f32_16x16x32_bf16 v[54:57], v[148:151], v[188:191], v[54:57]
	v_mfma_f32_16x16x32_bf16 v[42:45], v[156:159], v[188:191], v[42:45]
	v_mfma_f32_16x16x32_bf16 v[38:41], v[148:151], v[202:205], v[38:41]
	v_mfma_f32_16x16x32_bf16 v[26:29], v[156:159], v[202:205], v[26:29]
	v_mfma_f32_16x16x32_bf16 v[22:25], v[148:151], v[210:213], v[22:25]
	v_mfma_f32_16x16x32_bf16 v[10:13], v[156:159], v[210:213], v[10:13]
	v_mfma_f32_16x16x32_bf16 v[50:53], v[160:163], v[176:179], v[50:53]
	v_mfma_f32_16x16x32_bf16 v[46:49], v[168:171], v[176:179], v[46:49]
	v_mfma_f32_16x16x32_bf16 v[34:37], v[160:163], v[184:187], v[34:37]
	v_mfma_f32_16x16x32_bf16 v[30:33], v[168:171], v[184:187], v[30:33]
	v_mfma_f32_16x16x32_bf16 v[18:21], v[160:163], v[192:195], v[18:21]
	v_mfma_f32_16x16x32_bf16 v[14:17], v[168:171], v[192:195], v[14:17]
	v_mfma_f32_16x16x32_bf16 v[6:9], v[160:163], v[206:209], v[6:9]
	v_mfma_f32_16x16x32_bf16 v[2:5], v[168:171], v[206:209], v[2:5]
	v_mfma_f32_16x16x32_bf16 v[50:53], v[164:167], v[180:183], v[50:53]
	v_mfma_f32_16x16x32_bf16 v[46:49], v[172:175], v[180:183], v[46:49]
	v_mfma_f32_16x16x32_bf16 v[34:37], v[164:167], v[188:191], v[34:37]
	v_mfma_f32_16x16x32_bf16 v[30:33], v[172:175], v[188:191], v[30:33]
	v_mfma_f32_16x16x32_bf16 v[18:21], v[164:167], v[202:205], v[18:21]
	v_mfma_f32_16x16x32_bf16 v[14:17], v[172:175], v[202:205], v[14:17]
	v_mfma_f32_16x16x32_bf16 v[6:9], v[164:167], v[210:213], v[6:9]
	v_mfma_f32_16x16x32_bf16 v[2:5], v[172:175], v[210:213], v[2:5]
	s_setprio 0
	s_barrier
	s_add_i32 s96, s96, 2
	s_add_u32 s28, s28, 0x100
	s_addc_u32 s29, s29, 0
	s_cmp_gt_u32 s96, 19
	s_mov_b64 s[16:17], s[18:19]
	s_cbranch_scc0 .LBB0_1177
	s_and_b64 vcc, exec, s[8:9]
	s_cbranch_vccz .LBB0_1180
	s_barrier
